# k35: k33 (all micro-edits) + the 72 redundant post-barrier lgkmcnt waits removed
# baseline (speedup 1.0000x reference)
.LBB0_202:
	ds_read_b128 v[148:151], v167
	ds_read_b128 v[152:155], v167 offset:1024
	ds_read_b128 v[156:159], v167 offset:2048
	ds_read_b128 v[160:163], v167 offset:3072
	ds_read_b128 v[172:175], v168
	ds_read_b128 v[176:179], v168 offset:1024
	ds_read_b128 v[180:183], v168 offset:2048
	ds_read_b128 v[184:187], v168 offset:3072
	s_add_u32 s0, s28, 0xfffc0080
	s_addc_u32 s1, s29, -1
	s_cmp_eq_u32 s51, 12
	s_cselect_b32 s31, s21, s1
	s_cselect_b32 s30, s47, s0
	s_cselect_b32 s3, s19, s50
	s_cselect_b32 s2, s48, s49
	v_lshl_add_u64 v[220:221], s[28:29], 0, v[140:141]
	s_add_i32 m0, s27, 0xc000
	ds_read_b128 v[188:191], v169
	ds_read_b128 v[192:195], v169 offset:1024
	ds_read_b128 v[196:199], v169 offset:2048
	ds_read_b128 v[200:203], v169 offset:3072
	ds_read_b128 v[204:207], v169 offset:4096
	ds_read_b128 v[208:211], v169 offset:5120
	ds_read_b128 v[212:215], v169 offset:6144
	ds_read_b128 v[216:219], v169 offset:7168
	global_load_lds_dwordx4 v[220:221], off
	v_lshl_add_u64 v[220:221], s[28:29], 0, v[142:143]
	s_add_i32 m0, s27, 0xe000
	s_nop 0
	global_load_lds_dwordx4 v[220:221], off
	s_waitcnt vmcnt(8)
	s_waitcnt lgkmcnt(0)
	s_barrier
	s_setprio 1
	v_mfma_f32_16x16x32_bf16 v[126:129], v[148:151], v[188:191], v[126:129]
	v_mfma_f32_16x16x32_bf16 v[126:129], v[152:155], v[192:195], v[126:129]
	v_mfma_f32_16x16x32_bf16 v[118:121], v[156:159], v[188:191], v[118:121]
	v_mfma_f32_16x16x32_bf16 v[118:121], v[160:163], v[192:195], v[118:121]
	v_mfma_f32_16x16x32_bf16 v[110:113], v[148:151], v[196:199], v[110:113]
	v_mfma_f32_16x16x32_bf16 v[110:113], v[152:155], v[200:203], v[110:113]
	v_mfma_f32_16x16x32_bf16 v[106:109], v[156:159], v[196:199], v[106:109]
	v_mfma_f32_16x16x32_bf16 v[106:109], v[160:163], v[200:203], v[106:109]
	v_mfma_f32_16x16x32_bf16 v[94:97], v[148:151], v[204:207], v[94:97]
	v_mfma_f32_16x16x32_bf16 v[94:97], v[152:155], v[208:211], v[94:97]
	v_mfma_f32_16x16x32_bf16 v[90:93], v[156:159], v[204:207], v[90:93]
	v_mfma_f32_16x16x32_bf16 v[90:93], v[160:163], v[208:211], v[90:93]
	v_mfma_f32_16x16x32_bf16 v[78:81], v[148:151], v[212:215], v[78:81]
	v_mfma_f32_16x16x32_bf16 v[78:81], v[152:155], v[216:219], v[78:81]
	v_mfma_f32_16x16x32_bf16 v[74:77], v[156:159], v[212:215], v[74:77]
	v_mfma_f32_16x16x32_bf16 v[74:77], v[160:163], v[216:219], v[74:77]
	s_setprio 0
	s_setprio 1
	v_mfma_f32_16x16x32_bf16 v[122:125], v[172:175], v[188:191], v[122:125]
	v_mfma_f32_16x16x32_bf16 v[122:125], v[176:179], v[192:195], v[122:125]
	v_mfma_f32_16x16x32_bf16 v[114:117], v[180:183], v[188:191], v[114:117]
	v_mfma_f32_16x16x32_bf16 v[114:117], v[184:187], v[192:195], v[114:117]
	v_mfma_f32_16x16x32_bf16 v[102:105], v[172:175], v[196:199], v[102:105]
	v_mfma_f32_16x16x32_bf16 v[102:105], v[176:179], v[200:203], v[102:105]
	v_mfma_f32_16x16x32_bf16 v[98:101], v[180:183], v[196:199], v[98:101]
	v_mfma_f32_16x16x32_bf16 v[98:101], v[184:187], v[200:203], v[98:101]
	v_mfma_f32_16x16x32_bf16 v[86:89], v[172:175], v[204:207], v[86:89]
	v_mfma_f32_16x16x32_bf16 v[86:89], v[176:179], v[208:211], v[86:89]
	v_mfma_f32_16x16x32_bf16 v[82:85], v[180:183], v[204:207], v[82:85]
	v_mfma_f32_16x16x32_bf16 v[82:85], v[184:187], v[208:211], v[82:85]
	v_mfma_f32_16x16x32_bf16 v[70:73], v[172:175], v[212:215], v[70:73]
	v_mfma_f32_16x16x32_bf16 v[70:73], v[176:179], v[216:219], v[70:73]
	v_mfma_f32_16x16x32_bf16 v[66:69], v[180:183], v[212:215], v[66:69]
	v_mfma_f32_16x16x32_bf16 v[66:69], v[184:187], v[216:219], v[66:69]
	s_setprio 0
	s_barrier
	s_add_i32 s0, s43, s36
	v_lshl_add_u64 v[220:221], s[2:3], 0, v[132:133]
	s_mov_b32 m0, s0
	ds_read_b128 v[188:191], v169 offset:16384
	ds_read_b128 v[192:195], v169 offset:17408
	ds_read_b128 v[196:199], v169 offset:18432
	ds_read_b128 v[200:203], v169 offset:19456
	ds_read_b128 v[204:207], v169 offset:20480
	ds_read_b128 v[208:211], v169 offset:21504
	ds_read_b128 v[212:215], v169 offset:22528
	ds_read_b128 v[216:219], v169 offset:23552
	global_load_lds_dwordx4 v[220:221], off
	s_add_i32 m0, s0, 0x2000
	s_add_u32 s0, s2, 0x40000
	v_lshl_add_u64 v[222:223], s[2:3], 0, v[136:137]
	s_addc_u32 s1, s3, 0
	s_add_i32 s52, s44, s36
	global_load_lds_dwordx4 v[222:223], off
	v_lshl_add_u64 v[224:225], s[0:1], 0, v[132:133]
	s_mov_b32 m0, s52
	v_lshl_add_u64 v[226:227], s[30:31], 0, v[134:135]
	global_load_lds_dwordx4 v[224:225], off
	v_lshl_add_u64 v[224:225], s[0:1], 0, v[136:137]
	s_add_i32 m0, s52, 0x2000
	s_nop 0
	global_load_lds_dwordx4 v[224:225], off
	v_lshl_add_u64 v[224:225], s[30:31], 0, v[130:131]
	s_mov_b32 m0, s27
	s_nop 0
	global_load_lds_dwordx4 v[224:225], off
	s_mov_b32 m0, s37
	s_nop 0
	global_load_lds_dwordx4 v[226:227], off
	s_waitcnt vmcnt(8)
	s_waitcnt lgkmcnt(0)
	s_barrier
	s_setprio 1
	v_mfma_f32_16x16x32_bf16 v[62:65], v[148:151], v[188:191], v[62:65]
	v_mfma_f32_16x16x32_bf16 v[62:65], v[152:155], v[192:195], v[62:65]
	v_mfma_f32_16x16x32_bf16 v[58:61], v[156:159], v[188:191], v[58:61]
	v_mfma_f32_16x16x32_bf16 v[58:61], v[160:163], v[192:195], v[58:61]
	v_mfma_f32_16x16x32_bf16 v[46:49], v[148:151], v[196:199], v[46:49]
	v_mfma_f32_16x16x32_bf16 v[46:49], v[152:155], v[200:203], v[46:49]
	v_mfma_f32_16x16x32_bf16 v[42:45], v[156:159], v[196:199], v[42:45]
	v_mfma_f32_16x16x32_bf16 v[42:45], v[160:163], v[200:203], v[42:45]
	v_mfma_f32_16x16x32_bf16 v[30:33], v[148:151], v[204:207], v[30:33]
	v_mfma_f32_16x16x32_bf16 v[30:33], v[152:155], v[208:211], v[30:33]
	v_mfma_f32_16x16x32_bf16 v[26:29], v[156:159], v[204:207], v[26:29]
	v_mfma_f32_16x16x32_bf16 v[26:29], v[160:163], v[208:211], v[26:29]
	v_mfma_f32_16x16x32_bf16 v[14:17], v[148:151], v[212:215], v[14:17]
	v_mfma_f32_16x16x32_bf16 v[14:17], v[152:155], v[216:219], v[14:17]
	v_mfma_f32_16x16x32_bf16 v[10:13], v[156:159], v[212:215], v[10:13]
	v_mfma_f32_16x16x32_bf16 v[10:13], v[160:163], v[216:219], v[10:13]
	s_setprio 0
	s_setprio 1
	v_mfma_f32_16x16x32_bf16 v[54:57], v[172:175], v[188:191], v[54:57]
	v_mfma_f32_16x16x32_bf16 v[54:57], v[176:179], v[192:195], v[54:57]
	v_mfma_f32_16x16x32_bf16 v[50:53], v[180:183], v[188:191], v[50:53]
	v_mfma_f32_16x16x32_bf16 v[50:53], v[184:187], v[192:195], v[50:53]
	v_mfma_f32_16x16x32_bf16 v[38:41], v[172:175], v[196:199], v[38:41]
	v_mfma_f32_16x16x32_bf16 v[38:41], v[176:179], v[200:203], v[38:41]
	v_mfma_f32_16x16x32_bf16 v[34:37], v[180:183], v[196:199], v[34:37]
	v_mfma_f32_16x16x32_bf16 v[34:37], v[184:187], v[200:203], v[34:37]
	v_mfma_f32_16x16x32_bf16 v[22:25], v[172:175], v[204:207], v[22:25]
	v_mfma_f32_16x16x32_bf16 v[22:25], v[176:179], v[208:211], v[22:25]
	v_mfma_f32_16x16x32_bf16 v[18:21], v[180:183], v[204:207], v[18:21]
	v_mfma_f32_16x16x32_bf16 v[18:21], v[184:187], v[208:211], v[18:21]
	v_mfma_f32_16x16x32_bf16 v[6:9], v[172:175], v[212:215], v[6:9]
	v_mfma_f32_16x16x32_bf16 v[6:9], v[176:179], v[216:219], v[6:9]
	v_mfma_f32_16x16x32_bf16 v[2:5], v[180:183], v[212:215], v[2:5]
	v_mfma_f32_16x16x32_bf16 v[2:5], v[184:187], v[216:219], v[2:5]
	s_setprio 0
	s_barrier
	s_add_i32 s52, 0, 0x18000
	s_add_i32 s53, 0, 0x1c000
	v_add_u32_e32 v160, s52, v166
	v_add_u32_e32 v164, s53, v166
	ds_read_b128 v[148:151], v160
	ds_read_b128 v[152:155], v160 offset:1024
	ds_read_b128 v[156:159], v160 offset:2048
	ds_read_b128 v[160:163], v160 offset:3072
	ds_read_b128 v[172:175], v164
	ds_read_b128 v[176:179], v164 offset:1024
	ds_read_b128 v[180:183], v164 offset:2048
	ds_read_b128 v[184:187], v164 offset:3072
	s_add_u32 s0, s30, 0x40000
	s_addc_u32 s1, s31, 0
	s_mov_b32 m0, s38
	v_lshl_add_u64 v[228:229], s[0:1], 0, v[130:131]
	ds_read_b128 v[188:191], v169 offset:32768
	ds_read_b128 v[192:195], v169 offset:33792
	ds_read_b128 v[196:199], v169 offset:34816
	ds_read_b128 v[200:203], v169 offset:35840
	ds_read_b128 v[204:207], v169 offset:36864
	ds_read_b128 v[208:211], v169 offset:37888
	ds_read_b128 v[212:215], v169 offset:38912
	ds_read_b128 v[216:219], v169 offset:39936
	global_load_lds_dwordx4 v[228:229], off
	v_lshl_add_u64 v[228:229], s[0:1], 0, v[134:135]
	s_mov_b32 m0, s39
	s_nop 0
	global_load_lds_dwordx4 v[228:229], off
	s_waitcnt vmcnt(8)
	s_waitcnt lgkmcnt(0)
	s_barrier
	s_setprio 1
	v_mfma_f32_16x16x32_bf16 v[126:129], v[148:151], v[188:191], v[126:129]
	v_mfma_f32_16x16x32_bf16 v[126:129], v[152:155], v[192:195], v[126:129]
	v_mfma_f32_16x16x32_bf16 v[118:121], v[156:159], v[188:191], v[118:121]
	v_mfma_f32_16x16x32_bf16 v[118:121], v[160:163], v[192:195], v[118:121]
	v_mfma_f32_16x16x32_bf16 v[110:113], v[148:151], v[196:199], v[110:113]
	v_mfma_f32_16x16x32_bf16 v[110:113], v[152:155], v[200:203], v[110:113]
	v_mfma_f32_16x16x32_bf16 v[106:109], v[156:159], v[196:199], v[106:109]
	v_mfma_f32_16x16x32_bf16 v[106:109], v[160:163], v[200:203], v[106:109]
	v_mfma_f32_16x16x32_bf16 v[94:97], v[148:151], v[204:207], v[94:97]
	v_mfma_f32_16x16x32_bf16 v[94:97], v[152:155], v[208:211], v[94:97]
	v_mfma_f32_16x16x32_bf16 v[90:93], v[156:159], v[204:207], v[90:93]
	v_mfma_f32_16x16x32_bf16 v[90:93], v[160:163], v[208:211], v[90:93]
	v_mfma_f32_16x16x32_bf16 v[78:81], v[148:151], v[212:215], v[78:81]
	v_mfma_f32_16x16x32_bf16 v[78:81], v[152:155], v[216:219], v[78:81]
	v_mfma_f32_16x16x32_bf16 v[74:77], v[156:159], v[212:215], v[74:77]
	v_mfma_f32_16x16x32_bf16 v[74:77], v[160:163], v[216:219], v[74:77]
	s_setprio 0
	s_setprio 1
	v_mfma_f32_16x16x32_bf16 v[122:125], v[172:175], v[188:191], v[122:125]
	v_mfma_f32_16x16x32_bf16 v[122:125], v[176:179], v[192:195], v[122:125]
	v_mfma_f32_16x16x32_bf16 v[114:117], v[180:183], v[188:191], v[114:117]
	v_mfma_f32_16x16x32_bf16 v[114:117], v[184:187], v[192:195], v[114:117]
	v_mfma_f32_16x16x32_bf16 v[102:105], v[172:175], v[196:199], v[102:105]
	v_mfma_f32_16x16x32_bf16 v[102:105], v[176:179], v[200:203], v[102:105]
	v_mfma_f32_16x16x32_bf16 v[98:101], v[180:183], v[196:199], v[98:101]
	v_mfma_f32_16x16x32_bf16 v[98:101], v[184:187], v[200:203], v[98:101]
	v_mfma_f32_16x16x32_bf16 v[86:89], v[172:175], v[204:207], v[86:89]
	v_mfma_f32_16x16x32_bf16 v[86:89], v[176:179], v[208:211], v[86:89]
	v_mfma_f32_16x16x32_bf16 v[82:85], v[180:183], v[204:207], v[82:85]
	v_mfma_f32_16x16x32_bf16 v[82:85], v[184:187], v[208:211], v[82:85]
	v_mfma_f32_16x16x32_bf16 v[70:73], v[172:175], v[212:215], v[70:73]
	v_mfma_f32_16x16x32_bf16 v[70:73], v[176:179], v[216:219], v[70:73]
	v_mfma_f32_16x16x32_bf16 v[66:69], v[180:183], v[212:215], v[66:69]
	v_mfma_f32_16x16x32_bf16 v[66:69], v[184:187], v[216:219], v[66:69]
	s_setprio 0
	s_barrier
	s_add_i32 s0, s52, s36
	v_lshl_add_u64 v[220:221], v[220:221], 0, s[14:15]
	s_mov_b32 m0, s0
	ds_read_b128 v[188:191], v169 offset:49152
	ds_read_b128 v[192:195], v169 offset:50176
	ds_read_b128 v[196:199], v169 offset:51200
	ds_read_b128 v[200:203], v169 offset:52224
	ds_read_b128 v[204:207], v169 offset:53248
	ds_read_b128 v[208:211], v169 offset:54272
	ds_read_b128 v[212:215], v169 offset:55296
	ds_read_b128 v[216:219], v169 offset:56320
	global_load_lds_dwordx4 v[220:221], off
	s_add_i32 m0, s0, 0x2000
	s_add_u32 s0, s2, 0x40080
	v_lshl_add_u64 v[220:221], v[222:223], 0, s[14:15]
	s_addc_u32 s1, s3, 0
	s_add_i32 s2, s53, s36
	global_load_lds_dwordx4 v[220:221], off
	v_lshl_add_u64 v[220:221], s[0:1], 0, v[132:133]
	s_mov_b32 m0, s2
	s_nop 0
	global_load_lds_dwordx4 v[220:221], off
	v_lshl_add_u64 v[220:221], s[0:1], 0, v[136:137]
	s_add_i32 m0, s2, 0x2000
	s_nop 0
	global_load_lds_dwordx4 v[220:221], off
	v_lshl_add_u64 v[220:221], v[224:225], 0, s[14:15]
	s_mov_b32 m0, s40
	s_nop 0
	global_load_lds_dwordx4 v[220:221], off
	v_lshl_add_u64 v[220:221], v[226:227], 0, s[14:15]
	s_mov_b32 m0, s41
	s_nop 0
	global_load_lds_dwordx4 v[220:221], off
	s_waitcnt vmcnt(8)
	s_waitcnt lgkmcnt(0)
	s_barrier
	s_setprio 1
	v_mfma_f32_16x16x32_bf16 v[62:65], v[148:151], v[188:191], v[62:65]
	v_mfma_f32_16x16x32_bf16 v[62:65], v[152:155], v[192:195], v[62:65]
	v_mfma_f32_16x16x32_bf16 v[58:61], v[156:159], v[188:191], v[58:61]
	v_mfma_f32_16x16x32_bf16 v[58:61], v[160:163], v[192:195], v[58:61]
	v_mfma_f32_16x16x32_bf16 v[46:49], v[148:151], v[196:199], v[46:49]
	v_mfma_f32_16x16x32_bf16 v[46:49], v[152:155], v[200:203], v[46:49]
	v_mfma_f32_16x16x32_bf16 v[42:45], v[156:159], v[196:199], v[42:45]
	v_mfma_f32_16x16x32_bf16 v[42:45], v[160:163], v[200:203], v[42:45]
	v_mfma_f32_16x16x32_bf16 v[30:33], v[148:151], v[204:207], v[30:33]
	v_mfma_f32_16x16x32_bf16 v[30:33], v[152:155], v[208:211], v[30:33]
	v_mfma_f32_16x16x32_bf16 v[26:29], v[156:159], v[204:207], v[26:29]
	v_mfma_f32_16x16x32_bf16 v[26:29], v[160:163], v[208:211], v[26:29]
	v_mfma_f32_16x16x32_bf16 v[14:17], v[148:151], v[212:215], v[14:17]
	v_mfma_f32_16x16x32_bf16 v[14:17], v[152:155], v[216:219], v[14:17]
	v_mfma_f32_16x16x32_bf16 v[10:13], v[156:159], v[212:215], v[10:13]
	v_mfma_f32_16x16x32_bf16 v[10:13], v[160:163], v[216:219], v[10:13]
	s_setprio 0
	s_setprio 1
	v_mfma_f32_16x16x32_bf16 v[54:57], v[172:175], v[188:191], v[54:57]
	s_add_i32 s51, s51, 2
	s_add_u32 s28, s28, 0x100
	s_addc_u32 s29, s29, 0
	s_add_u32 s49, s49, 0x100
	s_addc_u32 s50, s50, 0
	s_cmp_gt_u32 s51, 13
	v_mfma_f32_16x16x32_bf16 v[54:57], v[176:179], v[192:195], v[54:57]
	v_mfma_f32_16x16x32_bf16 v[50:53], v[180:183], v[188:191], v[50:53]
	v_mfma_f32_16x16x32_bf16 v[50:53], v[184:187], v[192:195], v[50:53]
	v_mfma_f32_16x16x32_bf16 v[38:41], v[172:175], v[196:199], v[38:41]
	v_mfma_f32_16x16x32_bf16 v[38:41], v[176:179], v[200:203], v[38:41]
	v_mfma_f32_16x16x32_bf16 v[34:37], v[180:183], v[196:199], v[34:37]
	v_mfma_f32_16x16x32_bf16 v[34:37], v[184:187], v[200:203], v[34:37]
	v_mfma_f32_16x16x32_bf16 v[22:25], v[172:175], v[204:207], v[22:25]
	v_mfma_f32_16x16x32_bf16 v[22:25], v[176:179], v[208:211], v[22:25]
	v_mfma_f32_16x16x32_bf16 v[18:21], v[180:183], v[204:207], v[18:21]
	v_mfma_f32_16x16x32_bf16 v[18:21], v[184:187], v[208:211], v[18:21]
	v_mfma_f32_16x16x32_bf16 v[6:9], v[172:175], v[212:215], v[6:9]
	v_mfma_f32_16x16x32_bf16 v[6:9], v[176:179], v[216:219], v[6:9]
	v_mfma_f32_16x16x32_bf16 v[2:5], v[180:183], v[212:215], v[2:5]
	v_mfma_f32_16x16x32_bf16 v[2:5], v[184:187], v[216:219], v[2:5]
	s_setprio 0
	s_barrier
	s_cbranch_scc0 .LBB0_202
	s_and_b64 vcc, exec, s[16:17]
	s_cbranch_vccz .LBB0_205
	s_barrier

.LBB0_283:
	ds_read_b128 v[114:117], v228
	ds_read_b128 v[118:121], v228 offset:1024
	ds_read_b128 v[122:125], v228 offset:2048
	ds_read_b128 v[126:129], v228 offset:3072
	ds_read_b128 v[146:149], v229
	ds_read_b128 v[150:153], v229 offset:1024
	ds_read_b128 v[154:157], v229 offset:2048
	ds_read_b128 v[158:161], v229 offset:3072
	s_add_u32 s0, s10, 0xfffc0080
	s_addc_u32 s1, s11, -1
	s_cmp_eq_u32 s51, 12
	s_cselect_b32 s13, s7, s1
	s_cselect_b32 s12, s9, s0
	s_cselect_b32 s3, s27, s37
	s_cselect_b32 s2, s29, s36
	v_lshl_add_u64 v[212:213], s[10:11], 0, v[180:181]
	s_add_i32 m0, s40, 0xc000
	ds_read_b128 v[162:165], v230
	ds_read_b128 v[166:169], v230 offset:1024
	ds_read_b128 v[188:191], v230 offset:2048
	ds_read_b128 v[192:195], v230 offset:3072
	ds_read_b128 v[196:199], v230 offset:4096
	ds_read_b128 v[200:203], v230 offset:5120
	ds_read_b128 v[204:207], v230 offset:6144
	ds_read_b128 v[208:211], v230 offset:7168
	global_load_lds_dwordx4 v[212:213], off
	v_lshl_add_u64 v[212:213], s[10:11], 0, v[182:183]
	s_add_i32 m0, s40, 0xe000
	s_nop 0
	global_load_lds_dwordx4 v[212:213], off
	s_waitcnt vmcnt(8)
	s_waitcnt lgkmcnt(0)
	s_barrier
	s_setprio 1
	v_mfma_f32_16x16x32_bf16 v[142:145], v[114:117], v[162:165], v[142:145]
	v_mfma_f32_16x16x32_bf16 v[142:145], v[118:121], v[166:169], v[142:145]
	v_mfma_f32_16x16x32_bf16 v[138:141], v[122:125], v[162:165], v[138:141]
	v_mfma_f32_16x16x32_bf16 v[138:141], v[126:129], v[166:169], v[138:141]
	v_mfma_f32_16x16x32_bf16 v[134:137], v[114:117], v[188:191], v[134:137]
	v_mfma_f32_16x16x32_bf16 v[134:137], v[118:121], v[192:195], v[134:137]
	v_mfma_f32_16x16x32_bf16 v[130:133], v[122:125], v[188:191], v[130:133]
	v_mfma_f32_16x16x32_bf16 v[130:133], v[126:129], v[192:195], v[130:133]
	v_mfma_f32_16x16x32_bf16 v[110:113], v[114:117], v[196:199], v[110:113]
	v_mfma_f32_16x16x32_bf16 v[110:113], v[118:121], v[200:203], v[110:113]
	v_mfma_f32_16x16x32_bf16 v[106:109], v[122:125], v[196:199], v[106:109]
	v_mfma_f32_16x16x32_bf16 v[106:109], v[126:129], v[200:203], v[106:109]
	v_mfma_f32_16x16x32_bf16 v[102:105], v[114:117], v[204:207], v[102:105]
	v_mfma_f32_16x16x32_bf16 v[102:105], v[118:121], v[208:211], v[102:105]
	v_mfma_f32_16x16x32_bf16 v[98:101], v[122:125], v[204:207], v[98:101]
	v_mfma_f32_16x16x32_bf16 v[98:101], v[126:129], v[208:211], v[98:101]
	s_setprio 0
	s_setprio 1
	v_mfma_f32_16x16x32_bf16 v[62:65], v[146:149], v[162:165], v[62:65]
	v_mfma_f32_16x16x32_bf16 v[62:65], v[150:153], v[166:169], v[62:65]
	v_mfma_f32_16x16x32_bf16 v[58:61], v[154:157], v[162:165], v[58:61]
	v_mfma_f32_16x16x32_bf16 v[58:61], v[158:161], v[166:169], v[58:61]
	v_mfma_f32_16x16x32_bf16 v[54:57], v[146:149], v[188:191], v[54:57]
	v_mfma_f32_16x16x32_bf16 v[54:57], v[150:153], v[192:195], v[54:57]
	v_mfma_f32_16x16x32_bf16 v[50:53], v[154:157], v[188:191], v[50:53]
	v_mfma_f32_16x16x32_bf16 v[50:53], v[158:161], v[192:195], v[50:53]
	v_mfma_f32_16x16x32_bf16 v[46:49], v[146:149], v[196:199], v[46:49]
	v_mfma_f32_16x16x32_bf16 v[46:49], v[150:153], v[200:203], v[46:49]
	v_mfma_f32_16x16x32_bf16 v[42:45], v[154:157], v[196:199], v[42:45]
	v_mfma_f32_16x16x32_bf16 v[42:45], v[158:161], v[200:203], v[42:45]
	v_mfma_f32_16x16x32_bf16 v[38:41], v[146:149], v[204:207], v[38:41]
	v_mfma_f32_16x16x32_bf16 v[38:41], v[150:153], v[208:211], v[38:41]
	v_mfma_f32_16x16x32_bf16 v[34:37], v[154:157], v[204:207], v[34:37]
	v_mfma_f32_16x16x32_bf16 v[34:37], v[158:161], v[208:211], v[34:37]
	s_setprio 0
	s_barrier
	s_add_i32 s0, s49, s39
	v_lshl_add_u64 v[212:213], s[2:3], 0, v[172:173]
	s_mov_b32 m0, s0
	ds_read_b128 v[162:165], v230 offset:16384
	ds_read_b128 v[166:169], v230 offset:17408
	ds_read_b128 v[188:191], v230 offset:18432
	ds_read_b128 v[192:195], v230 offset:19456
	ds_read_b128 v[196:199], v230 offset:20480
	ds_read_b128 v[200:203], v230 offset:21504
	ds_read_b128 v[204:207], v230 offset:22528
	ds_read_b128 v[208:211], v230 offset:23552
	global_load_lds_dwordx4 v[212:213], off
	s_add_i32 m0, s0, 0x2000
	s_add_u32 s0, s2, 0x40000
	v_lshl_add_u64 v[214:215], s[2:3], 0, v[176:177]
	s_addc_u32 s1, s3, 0
	s_add_i32 s52, s50, s39
	global_load_lds_dwordx4 v[214:215], off
	v_lshl_add_u64 v[216:217], s[0:1], 0, v[172:173]
	s_mov_b32 m0, s52
	v_lshl_add_u64 v[218:219], s[12:13], 0, v[174:175]
	global_load_lds_dwordx4 v[216:217], off
	v_lshl_add_u64 v[216:217], s[0:1], 0, v[176:177]
	s_add_i32 m0, s52, 0x2000
	s_nop 0
	global_load_lds_dwordx4 v[216:217], off
	v_lshl_add_u64 v[216:217], s[12:13], 0, v[170:171]
	s_mov_b32 m0, s40
	s_nop 0
	global_load_lds_dwordx4 v[216:217], off
	s_mov_b32 m0, s41
	s_nop 0
	global_load_lds_dwordx4 v[218:219], off
	s_waitcnt vmcnt(8)
	s_waitcnt lgkmcnt(0)
	s_barrier
	s_setprio 1
	v_mfma_f32_16x16x32_bf16 v[94:97], v[114:117], v[162:165], v[94:97]
	v_mfma_f32_16x16x32_bf16 v[94:97], v[118:121], v[166:169], v[94:97]
	v_mfma_f32_16x16x32_bf16 v[90:93], v[122:125], v[162:165], v[90:93]
	v_mfma_f32_16x16x32_bf16 v[90:93], v[126:129], v[166:169], v[90:93]
	v_mfma_f32_16x16x32_bf16 v[86:89], v[114:117], v[188:191], v[86:89]
	v_mfma_f32_16x16x32_bf16 v[86:89], v[118:121], v[192:195], v[86:89]
	v_mfma_f32_16x16x32_bf16 v[82:85], v[122:125], v[188:191], v[82:85]
	v_mfma_f32_16x16x32_bf16 v[82:85], v[126:129], v[192:195], v[82:85]
	v_mfma_f32_16x16x32_bf16 v[78:81], v[114:117], v[196:199], v[78:81]
	v_mfma_f32_16x16x32_bf16 v[78:81], v[118:121], v[200:203], v[78:81]
	v_mfma_f32_16x16x32_bf16 v[74:77], v[122:125], v[196:199], v[74:77]
	v_mfma_f32_16x16x32_bf16 v[74:77], v[126:129], v[200:203], v[74:77]
	v_mfma_f32_16x16x32_bf16 v[70:73], v[114:117], v[204:207], v[70:73]
	v_mfma_f32_16x16x32_bf16 v[70:73], v[118:121], v[208:211], v[70:73]
	v_mfma_f32_16x16x32_bf16 v[66:69], v[122:125], v[204:207], v[66:69]
	v_mfma_f32_16x16x32_bf16 v[66:69], v[126:129], v[208:211], v[66:69]
	s_setprio 0
	s_setprio 1
	v_mfma_f32_16x16x32_bf16 v[30:33], v[146:149], v[162:165], v[30:33]
	v_mfma_f32_16x16x32_bf16 v[30:33], v[150:153], v[166:169], v[30:33]
	v_mfma_f32_16x16x32_bf16 v[26:29], v[154:157], v[162:165], v[26:29]
	v_mfma_f32_16x16x32_bf16 v[26:29], v[158:161], v[166:169], v[26:29]
	v_mfma_f32_16x16x32_bf16 v[22:25], v[146:149], v[188:191], v[22:25]
	v_mfma_f32_16x16x32_bf16 v[22:25], v[150:153], v[192:195], v[22:25]
	v_mfma_f32_16x16x32_bf16 v[18:21], v[154:157], v[188:191], v[18:21]
	v_mfma_f32_16x16x32_bf16 v[18:21], v[158:161], v[192:195], v[18:21]
	v_mfma_f32_16x16x32_bf16 v[14:17], v[146:149], v[196:199], v[14:17]
	v_mfma_f32_16x16x32_bf16 v[14:17], v[150:153], v[200:203], v[14:17]
	v_mfma_f32_16x16x32_bf16 v[10:13], v[154:157], v[196:199], v[10:13]
	v_mfma_f32_16x16x32_bf16 v[10:13], v[158:161], v[200:203], v[10:13]
	v_mfma_f32_16x16x32_bf16 v[6:9], v[146:149], v[204:207], v[6:9]
	v_mfma_f32_16x16x32_bf16 v[6:9], v[150:153], v[208:211], v[6:9]
	v_mfma_f32_16x16x32_bf16 v[2:5], v[154:157], v[204:207], v[2:5]
	v_mfma_f32_16x16x32_bf16 v[2:5], v[158:161], v[208:211], v[2:5]
	s_setprio 0
	s_barrier
	s_add_i32 s52, 0, 0x18000
	s_add_i32 s53, 0, 0x1c000
	v_add_u32_e32 v126, s52, v223
	v_add_u32_e32 v158, s53, v223
	ds_read_b128 v[114:117], v126
	ds_read_b128 v[118:121], v126 offset:1024
	ds_read_b128 v[122:125], v126 offset:2048
	ds_read_b128 v[126:129], v126 offset:3072
	ds_read_b128 v[146:149], v158
	ds_read_b128 v[150:153], v158 offset:1024
	ds_read_b128 v[154:157], v158 offset:2048
	ds_read_b128 v[158:161], v158 offset:3072
	s_add_u32 s0, s12, 0x40000
	s_addc_u32 s1, s13, 0
	s_mov_b32 m0, s42
	v_lshl_add_u64 v[220:221], s[0:1], 0, v[170:171]
	ds_read_b128 v[162:165], v230 offset:32768
	ds_read_b128 v[166:169], v230 offset:33792
	ds_read_b128 v[188:191], v230 offset:34816
	ds_read_b128 v[192:195], v230 offset:35840
	ds_read_b128 v[196:199], v230 offset:36864
	ds_read_b128 v[200:203], v230 offset:37888
	ds_read_b128 v[204:207], v230 offset:38912
	ds_read_b128 v[208:211], v230 offset:39936
	global_load_lds_dwordx4 v[220:221], off
	v_lshl_add_u64 v[220:221], s[0:1], 0, v[174:175]
	s_mov_b32 m0, s43
	s_nop 0
	global_load_lds_dwordx4 v[220:221], off
	s_waitcnt vmcnt(8)
	s_waitcnt lgkmcnt(0)
	s_barrier
	s_setprio 1
	v_mfma_f32_16x16x32_bf16 v[142:145], v[114:117], v[162:165], v[142:145]
	v_mfma_f32_16x16x32_bf16 v[142:145], v[118:121], v[166:169], v[142:145]
	v_mfma_f32_16x16x32_bf16 v[138:141], v[122:125], v[162:165], v[138:141]
	v_mfma_f32_16x16x32_bf16 v[138:141], v[126:129], v[166:169], v[138:141]
	v_mfma_f32_16x16x32_bf16 v[134:137], v[114:117], v[188:191], v[134:137]
	v_mfma_f32_16x16x32_bf16 v[134:137], v[118:121], v[192:195], v[134:137]
	v_mfma_f32_16x16x32_bf16 v[130:133], v[122:125], v[188:191], v[130:133]
	v_mfma_f32_16x16x32_bf16 v[130:133], v[126:129], v[192:195], v[130:133]
	v_mfma_f32_16x16x32_bf16 v[110:113], v[114:117], v[196:199], v[110:113]
	v_mfma_f32_16x16x32_bf16 v[110:113], v[118:121], v[200:203], v[110:113]
	v_mfma_f32_16x16x32_bf16 v[106:109], v[122:125], v[196:199], v[106:109]
	v_mfma_f32_16x16x32_bf16 v[106:109], v[126:129], v[200:203], v[106:109]
	v_mfma_f32_16x16x32_bf16 v[102:105], v[114:117], v[204:207], v[102:105]
	v_mfma_f32_16x16x32_bf16 v[102:105], v[118:121], v[208:211], v[102:105]
	v_mfma_f32_16x16x32_bf16 v[98:101], v[122:125], v[204:207], v[98:101]
	v_mfma_f32_16x16x32_bf16 v[98:101], v[126:129], v[208:211], v[98:101]
	s_setprio 0
	s_setprio 1
	v_mfma_f32_16x16x32_bf16 v[62:65], v[146:149], v[162:165], v[62:65]
	v_mfma_f32_16x16x32_bf16 v[62:65], v[150:153], v[166:169], v[62:65]
	v_mfma_f32_16x16x32_bf16 v[58:61], v[154:157], v[162:165], v[58:61]
	v_mfma_f32_16x16x32_bf16 v[58:61], v[158:161], v[166:169], v[58:61]
	v_mfma_f32_16x16x32_bf16 v[54:57], v[146:149], v[188:191], v[54:57]
	v_mfma_f32_16x16x32_bf16 v[54:57], v[150:153], v[192:195], v[54:57]
	v_mfma_f32_16x16x32_bf16 v[50:53], v[154:157], v[188:191], v[50:53]
	v_mfma_f32_16x16x32_bf16 v[50:53], v[158:161], v[192:195], v[50:53]
	v_mfma_f32_16x16x32_bf16 v[46:49], v[146:149], v[196:199], v[46:49]
	v_mfma_f32_16x16x32_bf16 v[46:49], v[150:153], v[200:203], v[46:49]
	v_mfma_f32_16x16x32_bf16 v[42:45], v[154:157], v[196:199], v[42:45]
	v_mfma_f32_16x16x32_bf16 v[42:45], v[158:161], v[200:203], v[42:45]
	v_mfma_f32_16x16x32_bf16 v[38:41], v[146:149], v[204:207], v[38:41]
	v_mfma_f32_16x16x32_bf16 v[38:41], v[150:153], v[208:211], v[38:41]
	v_mfma_f32_16x16x32_bf16 v[34:37], v[154:157], v[204:207], v[34:37]
	v_mfma_f32_16x16x32_bf16 v[34:37], v[158:161], v[208:211], v[34:37]
	s_setprio 0
	s_barrier
	s_add_i32 s0, s52, s39
	v_lshl_add_u64 v[212:213], v[212:213], 0, s[22:23]
	s_mov_b32 m0, s0
	ds_read_b128 v[162:165], v230 offset:49152
	ds_read_b128 v[166:169], v230 offset:50176
	ds_read_b128 v[188:191], v230 offset:51200
	ds_read_b128 v[192:195], v230 offset:52224
	ds_read_b128 v[196:199], v230 offset:53248
	ds_read_b128 v[200:203], v230 offset:54272
	ds_read_b128 v[204:207], v230 offset:55296
	ds_read_b128 v[208:211], v230 offset:56320
	global_load_lds_dwordx4 v[212:213], off
	s_add_i32 m0, s0, 0x2000
	s_add_u32 s0, s2, 0x40080
	v_lshl_add_u64 v[212:213], v[214:215], 0, s[22:23]
	s_addc_u32 s1, s3, 0
	s_add_i32 s2, s53, s39
	global_load_lds_dwordx4 v[212:213], off
	v_lshl_add_u64 v[212:213], s[0:1], 0, v[172:173]
	s_mov_b32 m0, s2
	s_nop 0
	global_load_lds_dwordx4 v[212:213], off
	v_lshl_add_u64 v[212:213], s[0:1], 0, v[176:177]
	s_add_i32 m0, s2, 0x2000
	s_nop 0
	global_load_lds_dwordx4 v[212:213], off
	v_lshl_add_u64 v[212:213], v[216:217], 0, s[22:23]
	s_mov_b32 m0, s45
	s_nop 0
	global_load_lds_dwordx4 v[212:213], off
	v_lshl_add_u64 v[212:213], v[218:219], 0, s[22:23]
	s_mov_b32 m0, s46
	s_nop 0
	global_load_lds_dwordx4 v[212:213], off
	s_waitcnt vmcnt(8)
	s_waitcnt lgkmcnt(0)
	s_barrier
	s_setprio 1
	v_mfma_f32_16x16x32_bf16 v[94:97], v[114:117], v[162:165], v[94:97]
	v_mfma_f32_16x16x32_bf16 v[94:97], v[118:121], v[166:169], v[94:97]
	v_mfma_f32_16x16x32_bf16 v[90:93], v[122:125], v[162:165], v[90:93]
	v_mfma_f32_16x16x32_bf16 v[90:93], v[126:129], v[166:169], v[90:93]
	v_mfma_f32_16x16x32_bf16 v[86:89], v[114:117], v[188:191], v[86:89]
	v_mfma_f32_16x16x32_bf16 v[86:89], v[118:121], v[192:195], v[86:89]
	v_mfma_f32_16x16x32_bf16 v[82:85], v[122:125], v[188:191], v[82:85]
	v_mfma_f32_16x16x32_bf16 v[82:85], v[126:129], v[192:195], v[82:85]
	v_mfma_f32_16x16x32_bf16 v[78:81], v[114:117], v[196:199], v[78:81]
	v_mfma_f32_16x16x32_bf16 v[78:81], v[118:121], v[200:203], v[78:81]
	v_mfma_f32_16x16x32_bf16 v[74:77], v[122:125], v[196:199], v[74:77]
	v_mfma_f32_16x16x32_bf16 v[74:77], v[126:129], v[200:203], v[74:77]
	v_mfma_f32_16x16x32_bf16 v[70:73], v[114:117], v[204:207], v[70:73]
	v_mfma_f32_16x16x32_bf16 v[70:73], v[118:121], v[208:211], v[70:73]
	v_mfma_f32_16x16x32_bf16 v[66:69], v[122:125], v[204:207], v[66:69]
	v_mfma_f32_16x16x32_bf16 v[66:69], v[126:129], v[208:211], v[66:69]
	s_setprio 0
	s_setprio 1
	v_mfma_f32_16x16x32_bf16 v[30:33], v[146:149], v[162:165], v[30:33]
	s_add_i32 s51, s51, 2
	s_add_u32 s10, s10, 0x100
	s_addc_u32 s11, s11, 0
	s_add_u32 s36, s36, 0x100
	s_addc_u32 s37, s37, 0
	s_cmp_gt_u32 s51, 13
	v_mfma_f32_16x16x32_bf16 v[30:33], v[150:153], v[166:169], v[30:33]
	v_mfma_f32_16x16x32_bf16 v[26:29], v[154:157], v[162:165], v[26:29]
	v_mfma_f32_16x16x32_bf16 v[26:29], v[158:161], v[166:169], v[26:29]
	v_mfma_f32_16x16x32_bf16 v[22:25], v[146:149], v[188:191], v[22:25]
	v_mfma_f32_16x16x32_bf16 v[22:25], v[150:153], v[192:195], v[22:25]
	v_mfma_f32_16x16x32_bf16 v[18:21], v[154:157], v[188:191], v[18:21]
	v_mfma_f32_16x16x32_bf16 v[18:21], v[158:161], v[192:195], v[18:21]
	v_mfma_f32_16x16x32_bf16 v[14:17], v[146:149], v[196:199], v[14:17]
	v_mfma_f32_16x16x32_bf16 v[14:17], v[150:153], v[200:203], v[14:17]
	v_mfma_f32_16x16x32_bf16 v[10:13], v[154:157], v[196:199], v[10:13]
	v_mfma_f32_16x16x32_bf16 v[10:13], v[158:161], v[200:203], v[10:13]
	v_mfma_f32_16x16x32_bf16 v[6:9], v[146:149], v[204:207], v[6:9]
	v_mfma_f32_16x16x32_bf16 v[6:9], v[150:153], v[208:211], v[6:9]
	v_mfma_f32_16x16x32_bf16 v[2:5], v[154:157], v[204:207], v[2:5]
	v_mfma_f32_16x16x32_bf16 v[2:5], v[158:161], v[208:211], v[2:5]
	s_setprio 0
	s_barrier
	s_cbranch_scc0 .LBB0_283
	s_and_b64 vcc, exec, s[24:25]
	s_cbranch_vccz .LBB0_286
	s_barrier

.LBB0_382:
	ds_read_b128 v[130:133], v211
	ds_read_b128 v[134:137], v211 offset:1024
	ds_read_b128 v[138:141], v211 offset:2048
	ds_read_b128 v[142:145], v211 offset:3072
	ds_read_b128 v[146:149], v212
	ds_read_b128 v[150:153], v212 offset:1024
	ds_read_b128 v[154:157], v212 offset:2048
	ds_read_b128 v[158:161], v212 offset:3072
	s_add_u32 s0, s28, 0xfffc0080
	s_addc_u32 s1, s29, -1
	s_cmp_eq_u32 s51, 12
	s_cselect_b32 s31, s11, s1
	s_cselect_b32 s30, s21, s0
	s_cselect_b32 s3, s19, s50
	s_cselect_b32 s2, s48, s49
	v_lshl_add_u64 v[220:221], s[28:29], 0, v[186:187]
	s_add_i32 m0, s27, 0xc000
	ds_read_b128 v[162:165], v213
	ds_read_b128 v[166:169], v213 offset:1024
	ds_read_b128 v[170:173], v213 offset:2048
	ds_read_b128 v[174:177], v213 offset:3072
	ds_read_b128 v[194:197], v213 offset:4096
	ds_read_b128 v[198:201], v213 offset:5120
	ds_read_b128 v[202:205], v213 offset:6144
	ds_read_b128 v[216:219], v213 offset:7168
	global_load_lds_dwordx4 v[220:221], off
	v_lshl_add_u64 v[220:221], s[28:29], 0, v[188:189]
	s_add_i32 m0, s27, 0xe000
	s_nop 0
	global_load_lds_dwordx4 v[220:221], off
	s_waitcnt vmcnt(8)
	s_waitcnt lgkmcnt(0)
	s_barrier
	s_setprio 1
	v_mfma_f32_16x16x32_bf16 v[126:129], v[130:133], v[162:165], v[126:129]
	v_mfma_f32_16x16x32_bf16 v[126:129], v[134:137], v[166:169], v[126:129]
	v_mfma_f32_16x16x32_bf16 v[122:125], v[138:141], v[162:165], v[122:125]
	v_mfma_f32_16x16x32_bf16 v[122:125], v[142:145], v[166:169], v[122:125]
	v_mfma_f32_16x16x32_bf16 v[110:113], v[130:133], v[170:173], v[110:113]
	v_mfma_f32_16x16x32_bf16 v[110:113], v[134:137], v[174:177], v[110:113]
	v_mfma_f32_16x16x32_bf16 v[106:109], v[138:141], v[170:173], v[106:109]
	v_mfma_f32_16x16x32_bf16 v[106:109], v[142:145], v[174:177], v[106:109]
	v_mfma_f32_16x16x32_bf16 v[94:97], v[130:133], v[194:197], v[94:97]
	v_mfma_f32_16x16x32_bf16 v[94:97], v[134:137], v[198:201], v[94:97]
	v_mfma_f32_16x16x32_bf16 v[90:93], v[138:141], v[194:197], v[90:93]
	v_mfma_f32_16x16x32_bf16 v[90:93], v[142:145], v[198:201], v[90:93]
	v_mfma_f32_16x16x32_bf16 v[78:81], v[130:133], v[202:205], v[78:81]
	v_mfma_f32_16x16x32_bf16 v[78:81], v[134:137], v[216:219], v[78:81]
	v_mfma_f32_16x16x32_bf16 v[74:77], v[138:141], v[202:205], v[74:77]
	v_mfma_f32_16x16x32_bf16 v[74:77], v[142:145], v[216:219], v[74:77]
	s_setprio 0
	s_setprio 1
	v_mfma_f32_16x16x32_bf16 v[118:121], v[146:149], v[162:165], v[118:121]
	v_mfma_f32_16x16x32_bf16 v[118:121], v[150:153], v[166:169], v[118:121]
	v_mfma_f32_16x16x32_bf16 v[114:117], v[154:157], v[162:165], v[114:117]
	v_mfma_f32_16x16x32_bf16 v[114:117], v[158:161], v[166:169], v[114:117]
	v_mfma_f32_16x16x32_bf16 v[102:105], v[146:149], v[170:173], v[102:105]
	v_mfma_f32_16x16x32_bf16 v[102:105], v[150:153], v[174:177], v[102:105]
	v_mfma_f32_16x16x32_bf16 v[98:101], v[154:157], v[170:173], v[98:101]
	v_mfma_f32_16x16x32_bf16 v[98:101], v[158:161], v[174:177], v[98:101]
	v_mfma_f32_16x16x32_bf16 v[86:89], v[146:149], v[194:197], v[86:89]
	v_mfma_f32_16x16x32_bf16 v[86:89], v[150:153], v[198:201], v[86:89]
	v_mfma_f32_16x16x32_bf16 v[82:85], v[154:157], v[194:197], v[82:85]
	v_mfma_f32_16x16x32_bf16 v[82:85], v[158:161], v[198:201], v[82:85]
	v_mfma_f32_16x16x32_bf16 v[70:73], v[146:149], v[202:205], v[70:73]
	v_mfma_f32_16x16x32_bf16 v[70:73], v[150:153], v[216:219], v[70:73]
	v_mfma_f32_16x16x32_bf16 v[66:69], v[154:157], v[202:205], v[66:69]
	v_mfma_f32_16x16x32_bf16 v[66:69], v[158:161], v[216:219], v[66:69]
	s_setprio 0
	s_barrier
	s_add_i32 s0, s46, s37
	v_lshl_add_u64 v[220:221], s[2:3], 0, v[180:181]
	s_mov_b32 m0, s0
	ds_read_b128 v[162:165], v213 offset:16384
	ds_read_b128 v[166:169], v213 offset:17408
	ds_read_b128 v[170:173], v213 offset:18432
	ds_read_b128 v[174:177], v213 offset:19456
	ds_read_b128 v[194:197], v213 offset:20480
	ds_read_b128 v[198:201], v213 offset:21504
	ds_read_b128 v[202:205], v213 offset:22528
	ds_read_b128 v[216:219], v213 offset:23552
	global_load_lds_dwordx4 v[220:221], off
	s_add_i32 m0, s0, 0x2000
	s_add_u32 s0, s2, 0x40000
	v_lshl_add_u64 v[222:223], s[2:3], 0, v[184:185]
	s_addc_u32 s1, s3, 0
	s_add_i32 s52, s47, s37
	global_load_lds_dwordx4 v[222:223], off
	v_lshl_add_u64 v[224:225], s[0:1], 0, v[180:181]
	s_mov_b32 m0, s52
	v_lshl_add_u64 v[226:227], s[30:31], 0, v[182:183]
	global_load_lds_dwordx4 v[224:225], off
	v_lshl_add_u64 v[224:225], s[0:1], 0, v[184:185]
	s_add_i32 m0, s52, 0x2000
	s_nop 0
	global_load_lds_dwordx4 v[224:225], off
	v_lshl_add_u64 v[224:225], s[30:31], 0, v[178:179]
	s_mov_b32 m0, s27
	s_nop 0
	global_load_lds_dwordx4 v[224:225], off
	s_mov_b32 m0, s38
	s_nop 0
	global_load_lds_dwordx4 v[226:227], off
	s_waitcnt vmcnt(8)
	s_waitcnt lgkmcnt(0)
	s_barrier
	s_setprio 1
	v_mfma_f32_16x16x32_bf16 v[62:65], v[130:133], v[162:165], v[62:65]
	v_mfma_f32_16x16x32_bf16 v[62:65], v[134:137], v[166:169], v[62:65]
	v_mfma_f32_16x16x32_bf16 v[58:61], v[138:141], v[162:165], v[58:61]
	v_mfma_f32_16x16x32_bf16 v[58:61], v[142:145], v[166:169], v[58:61]
	v_mfma_f32_16x16x32_bf16 v[46:49], v[130:133], v[170:173], v[46:49]
	v_mfma_f32_16x16x32_bf16 v[46:49], v[134:137], v[174:177], v[46:49]
	v_mfma_f32_16x16x32_bf16 v[42:45], v[138:141], v[170:173], v[42:45]
	v_mfma_f32_16x16x32_bf16 v[42:45], v[142:145], v[174:177], v[42:45]
	v_mfma_f32_16x16x32_bf16 v[30:33], v[130:133], v[194:197], v[30:33]
	v_mfma_f32_16x16x32_bf16 v[30:33], v[134:137], v[198:201], v[30:33]
	v_mfma_f32_16x16x32_bf16 v[26:29], v[138:141], v[194:197], v[26:29]
	v_mfma_f32_16x16x32_bf16 v[26:29], v[142:145], v[198:201], v[26:29]
	v_mfma_f32_16x16x32_bf16 v[14:17], v[130:133], v[202:205], v[14:17]
	v_mfma_f32_16x16x32_bf16 v[14:17], v[134:137], v[216:219], v[14:17]
	v_mfma_f32_16x16x32_bf16 v[10:13], v[138:141], v[202:205], v[10:13]
	v_mfma_f32_16x16x32_bf16 v[10:13], v[142:145], v[216:219], v[10:13]
	s_setprio 0
	s_setprio 1
	v_mfma_f32_16x16x32_bf16 v[54:57], v[146:149], v[162:165], v[54:57]
	v_mfma_f32_16x16x32_bf16 v[54:57], v[150:153], v[166:169], v[54:57]
	v_mfma_f32_16x16x32_bf16 v[50:53], v[154:157], v[162:165], v[50:53]
	v_mfma_f32_16x16x32_bf16 v[50:53], v[158:161], v[166:169], v[50:53]
	v_mfma_f32_16x16x32_bf16 v[38:41], v[146:149], v[170:173], v[38:41]
	v_mfma_f32_16x16x32_bf16 v[38:41], v[150:153], v[174:177], v[38:41]
	v_mfma_f32_16x16x32_bf16 v[34:37], v[154:157], v[170:173], v[34:37]
	v_mfma_f32_16x16x32_bf16 v[34:37], v[158:161], v[174:177], v[34:37]
	v_mfma_f32_16x16x32_bf16 v[22:25], v[146:149], v[194:197], v[22:25]
	v_mfma_f32_16x16x32_bf16 v[22:25], v[150:153], v[198:201], v[22:25]
	v_mfma_f32_16x16x32_bf16 v[18:21], v[154:157], v[194:197], v[18:21]
	v_mfma_f32_16x16x32_bf16 v[18:21], v[158:161], v[198:201], v[18:21]
	v_mfma_f32_16x16x32_bf16 v[6:9], v[146:149], v[202:205], v[6:9]
	v_mfma_f32_16x16x32_bf16 v[6:9], v[150:153], v[216:219], v[6:9]
	v_mfma_f32_16x16x32_bf16 v[2:5], v[154:157], v[202:205], v[2:5]
	v_mfma_f32_16x16x32_bf16 v[2:5], v[158:161], v[216:219], v[2:5]
	s_setprio 0
	s_barrier
	s_add_i32 s52, 0, 0x18000
	s_add_i32 s53, 0, 0x1c000
	v_add_u32_e32 v142, s52, v207
	v_add_u32_e32 v158, s53, v207
	ds_read_b128 v[130:133], v142
	ds_read_b128 v[134:137], v142 offset:1024
	ds_read_b128 v[138:141], v142 offset:2048
	ds_read_b128 v[142:145], v142 offset:3072
	ds_read_b128 v[146:149], v158
	ds_read_b128 v[150:153], v158 offset:1024
	ds_read_b128 v[154:157], v158 offset:2048
	ds_read_b128 v[158:161], v158 offset:3072
	s_add_u32 s0, s30, 0x40000
	s_addc_u32 s1, s31, 0
	s_mov_b32 m0, s39
	v_lshl_add_u64 v[228:229], s[0:1], 0, v[178:179]
	ds_read_b128 v[162:165], v213 offset:32768
	ds_read_b128 v[166:169], v213 offset:33792
	ds_read_b128 v[170:173], v213 offset:34816
	ds_read_b128 v[174:177], v213 offset:35840
	ds_read_b128 v[194:197], v213 offset:36864
	ds_read_b128 v[198:201], v213 offset:37888
	ds_read_b128 v[202:205], v213 offset:38912
	ds_read_b128 v[216:219], v213 offset:39936
	global_load_lds_dwordx4 v[228:229], off
	v_lshl_add_u64 v[228:229], s[0:1], 0, v[182:183]
	s_mov_b32 m0, s40
	s_nop 0
	global_load_lds_dwordx4 v[228:229], off
	s_waitcnt vmcnt(8)
	s_waitcnt lgkmcnt(0)
	s_barrier
	s_setprio 1
	v_mfma_f32_16x16x32_bf16 v[126:129], v[130:133], v[162:165], v[126:129]
	v_mfma_f32_16x16x32_bf16 v[126:129], v[134:137], v[166:169], v[126:129]
	v_mfma_f32_16x16x32_bf16 v[122:125], v[138:141], v[162:165], v[122:125]
	v_mfma_f32_16x16x32_bf16 v[122:125], v[142:145], v[166:169], v[122:125]
	v_mfma_f32_16x16x32_bf16 v[110:113], v[130:133], v[170:173], v[110:113]
	v_mfma_f32_16x16x32_bf16 v[110:113], v[134:137], v[174:177], v[110:113]
	v_mfma_f32_16x16x32_bf16 v[106:109], v[138:141], v[170:173], v[106:109]
	v_mfma_f32_16x16x32_bf16 v[106:109], v[142:145], v[174:177], v[106:109]
	v_mfma_f32_16x16x32_bf16 v[94:97], v[130:133], v[194:197], v[94:97]
	v_mfma_f32_16x16x32_bf16 v[94:97], v[134:137], v[198:201], v[94:97]
	v_mfma_f32_16x16x32_bf16 v[90:93], v[138:141], v[194:197], v[90:93]
	v_mfma_f32_16x16x32_bf16 v[90:93], v[142:145], v[198:201], v[90:93]
	v_mfma_f32_16x16x32_bf16 v[78:81], v[130:133], v[202:205], v[78:81]
	v_mfma_f32_16x16x32_bf16 v[78:81], v[134:137], v[216:219], v[78:81]
	v_mfma_f32_16x16x32_bf16 v[74:77], v[138:141], v[202:205], v[74:77]
	v_mfma_f32_16x16x32_bf16 v[74:77], v[142:145], v[216:219], v[74:77]
	s_setprio 0
	s_setprio 1
	v_mfma_f32_16x16x32_bf16 v[118:121], v[146:149], v[162:165], v[118:121]
	v_mfma_f32_16x16x32_bf16 v[118:121], v[150:153], v[166:169], v[118:121]
	v_mfma_f32_16x16x32_bf16 v[114:117], v[154:157], v[162:165], v[114:117]
	v_mfma_f32_16x16x32_bf16 v[114:117], v[158:161], v[166:169], v[114:117]
	v_mfma_f32_16x16x32_bf16 v[102:105], v[146:149], v[170:173], v[102:105]
	v_mfma_f32_16x16x32_bf16 v[102:105], v[150:153], v[174:177], v[102:105]
	v_mfma_f32_16x16x32_bf16 v[98:101], v[154:157], v[170:173], v[98:101]
	v_mfma_f32_16x16x32_bf16 v[98:101], v[158:161], v[174:177], v[98:101]
	v_mfma_f32_16x16x32_bf16 v[86:89], v[146:149], v[194:197], v[86:89]
	v_mfma_f32_16x16x32_bf16 v[86:89], v[150:153], v[198:201], v[86:89]
	v_mfma_f32_16x16x32_bf16 v[82:85], v[154:157], v[194:197], v[82:85]
	v_mfma_f32_16x16x32_bf16 v[82:85], v[158:161], v[198:201], v[82:85]
	v_mfma_f32_16x16x32_bf16 v[70:73], v[146:149], v[202:205], v[70:73]
	v_mfma_f32_16x16x32_bf16 v[70:73], v[150:153], v[216:219], v[70:73]
	v_mfma_f32_16x16x32_bf16 v[66:69], v[154:157], v[202:205], v[66:69]
	v_mfma_f32_16x16x32_bf16 v[66:69], v[158:161], v[216:219], v[66:69]
	s_setprio 0
	s_barrier
	s_add_i32 s0, s52, s37
	v_lshl_add_u64 v[220:221], v[220:221], 0, s[14:15]
	s_mov_b32 m0, s0
	ds_read_b128 v[162:165], v213 offset:49152
	ds_read_b128 v[166:169], v213 offset:50176
	ds_read_b128 v[170:173], v213 offset:51200
	ds_read_b128 v[174:177], v213 offset:52224
	ds_read_b128 v[194:197], v213 offset:53248
	ds_read_b128 v[198:201], v213 offset:54272
	ds_read_b128 v[202:205], v213 offset:55296
	ds_read_b128 v[216:219], v213 offset:56320
	global_load_lds_dwordx4 v[220:221], off
	s_add_i32 m0, s0, 0x2000
	s_add_u32 s0, s2, 0x40080
	v_lshl_add_u64 v[220:221], v[222:223], 0, s[14:15]
	s_addc_u32 s1, s3, 0
	s_add_i32 s2, s53, s37
	global_load_lds_dwordx4 v[220:221], off
	v_lshl_add_u64 v[220:221], s[0:1], 0, v[180:181]
	s_mov_b32 m0, s2
	s_nop 0
	global_load_lds_dwordx4 v[220:221], off
	v_lshl_add_u64 v[220:221], s[0:1], 0, v[184:185]
	s_add_i32 m0, s2, 0x2000
	s_nop 0
	global_load_lds_dwordx4 v[220:221], off
	v_lshl_add_u64 v[220:221], v[224:225], 0, s[14:15]
	s_mov_b32 m0, s42
	s_nop 0
	global_load_lds_dwordx4 v[220:221], off
	v_lshl_add_u64 v[220:221], v[226:227], 0, s[14:15]
	s_mov_b32 m0, s43
	s_nop 0
	global_load_lds_dwordx4 v[220:221], off
	s_waitcnt vmcnt(8)
	s_waitcnt lgkmcnt(0)
	s_barrier
	s_setprio 1
	v_mfma_f32_16x16x32_bf16 v[62:65], v[130:133], v[162:165], v[62:65]
	v_mfma_f32_16x16x32_bf16 v[62:65], v[134:137], v[166:169], v[62:65]
	v_mfma_f32_16x16x32_bf16 v[58:61], v[138:141], v[162:165], v[58:61]
	v_mfma_f32_16x16x32_bf16 v[58:61], v[142:145], v[166:169], v[58:61]
	v_mfma_f32_16x16x32_bf16 v[46:49], v[130:133], v[170:173], v[46:49]
	v_mfma_f32_16x16x32_bf16 v[46:49], v[134:137], v[174:177], v[46:49]
	v_mfma_f32_16x16x32_bf16 v[42:45], v[138:141], v[170:173], v[42:45]
	v_mfma_f32_16x16x32_bf16 v[42:45], v[142:145], v[174:177], v[42:45]
	v_mfma_f32_16x16x32_bf16 v[30:33], v[130:133], v[194:197], v[30:33]
	v_mfma_f32_16x16x32_bf16 v[30:33], v[134:137], v[198:201], v[30:33]
	v_mfma_f32_16x16x32_bf16 v[26:29], v[138:141], v[194:197], v[26:29]
	v_mfma_f32_16x16x32_bf16 v[26:29], v[142:145], v[198:201], v[26:29]
	v_mfma_f32_16x16x32_bf16 v[14:17], v[130:133], v[202:205], v[14:17]
	v_mfma_f32_16x16x32_bf16 v[14:17], v[134:137], v[216:219], v[14:17]
	v_mfma_f32_16x16x32_bf16 v[10:13], v[138:141], v[202:205], v[10:13]
	v_mfma_f32_16x16x32_bf16 v[10:13], v[142:145], v[216:219], v[10:13]
	s_setprio 0
	s_setprio 1
	v_mfma_f32_16x16x32_bf16 v[54:57], v[146:149], v[162:165], v[54:57]
	s_add_i32 s51, s51, 2
	s_add_u32 s28, s28, 0x100
	s_addc_u32 s29, s29, 0
	s_add_u32 s49, s49, 0x100
	s_addc_u32 s50, s50, 0
	s_cmp_gt_u32 s51, 13
	v_mfma_f32_16x16x32_bf16 v[54:57], v[150:153], v[166:169], v[54:57]
	v_mfma_f32_16x16x32_bf16 v[50:53], v[154:157], v[162:165], v[50:53]
	v_mfma_f32_16x16x32_bf16 v[50:53], v[158:161], v[166:169], v[50:53]
	v_mfma_f32_16x16x32_bf16 v[38:41], v[146:149], v[170:173], v[38:41]
	v_mfma_f32_16x16x32_bf16 v[38:41], v[150:153], v[174:177], v[38:41]
	v_mfma_f32_16x16x32_bf16 v[34:37], v[154:157], v[170:173], v[34:37]
	v_mfma_f32_16x16x32_bf16 v[34:37], v[158:161], v[174:177], v[34:37]
	v_mfma_f32_16x16x32_bf16 v[22:25], v[146:149], v[194:197], v[22:25]
	v_mfma_f32_16x16x32_bf16 v[22:25], v[150:153], v[198:201], v[22:25]
	v_mfma_f32_16x16x32_bf16 v[18:21], v[154:157], v[194:197], v[18:21]
	v_mfma_f32_16x16x32_bf16 v[18:21], v[158:161], v[198:201], v[18:21]
	v_mfma_f32_16x16x32_bf16 v[6:9], v[146:149], v[202:205], v[6:9]
	v_mfma_f32_16x16x32_bf16 v[6:9], v[150:153], v[216:219], v[6:9]
	v_mfma_f32_16x16x32_bf16 v[2:5], v[154:157], v[202:205], v[2:5]
	v_mfma_f32_16x16x32_bf16 v[2:5], v[158:161], v[216:219], v[2:5]
	s_setprio 0
	s_barrier
	s_cbranch_scc0 .LBB0_382
	s_and_b64 vcc, exec, s[16:17]
	s_cbranch_vccz .LBB0_385
	s_barrier

.LBB0_471:
	ds_read_b128 v[148:151], v167
	ds_read_b128 v[152:155], v167 offset:1024
	ds_read_b128 v[156:159], v167 offset:2048
	ds_read_b128 v[160:163], v167 offset:3072
	ds_read_b128 v[172:175], v168
	ds_read_b128 v[176:179], v168 offset:1024
	ds_read_b128 v[180:183], v168 offset:2048
	ds_read_b128 v[184:187], v168 offset:3072
	s_add_u32 s0, s28, 0xfffc0080
	s_addc_u32 s1, s29, -1
	s_cmp_eq_u32 s53, 12
	s_cselect_b32 s31, s21, s1
	s_cselect_b32 s30, s49, s0
	s_cselect_b32 s3, s19, s52
	s_cselect_b32 s2, s50, s51
	v_lshl_add_u64 v[220:221], s[28:29], 0, v[140:141]
	s_add_i32 m0, s38, 0xc000
	ds_read_b128 v[188:191], v169
	ds_read_b128 v[192:195], v169 offset:1024
	ds_read_b128 v[196:199], v169 offset:2048
	ds_read_b128 v[200:203], v169 offset:3072
	ds_read_b128 v[204:207], v169 offset:4096
	ds_read_b128 v[208:211], v169 offset:5120
	ds_read_b128 v[212:215], v169 offset:6144
	ds_read_b128 v[216:219], v169 offset:7168
	global_load_lds_dwordx4 v[220:221], off
	v_lshl_add_u64 v[220:221], s[28:29], 0, v[142:143]
	s_add_i32 m0, s38, 0xe000
	s_nop 0
	global_load_lds_dwordx4 v[220:221], off
	s_waitcnt vmcnt(8)
	s_waitcnt lgkmcnt(0)
	s_barrier
	s_setprio 1
	v_mfma_f32_16x16x32_bf16 v[126:129], v[148:151], v[188:191], v[126:129]
	v_mfma_f32_16x16x32_bf16 v[126:129], v[152:155], v[192:195], v[126:129]
	v_mfma_f32_16x16x32_bf16 v[118:121], v[156:159], v[188:191], v[118:121]
	v_mfma_f32_16x16x32_bf16 v[118:121], v[160:163], v[192:195], v[118:121]
	v_mfma_f32_16x16x32_bf16 v[110:113], v[148:151], v[196:199], v[110:113]
	v_mfma_f32_16x16x32_bf16 v[110:113], v[152:155], v[200:203], v[110:113]
	v_mfma_f32_16x16x32_bf16 v[102:105], v[156:159], v[196:199], v[102:105]
	v_mfma_f32_16x16x32_bf16 v[102:105], v[160:163], v[200:203], v[102:105]
	v_mfma_f32_16x16x32_bf16 v[94:97], v[148:151], v[204:207], v[94:97]
	v_mfma_f32_16x16x32_bf16 v[94:97], v[152:155], v[208:211], v[94:97]
	v_mfma_f32_16x16x32_bf16 v[86:89], v[156:159], v[204:207], v[86:89]
	v_mfma_f32_16x16x32_bf16 v[86:89], v[160:163], v[208:211], v[86:89]
	v_mfma_f32_16x16x32_bf16 v[78:81], v[148:151], v[212:215], v[78:81]
	v_mfma_f32_16x16x32_bf16 v[78:81], v[152:155], v[216:219], v[78:81]
	v_mfma_f32_16x16x32_bf16 v[70:73], v[156:159], v[212:215], v[70:73]
	v_mfma_f32_16x16x32_bf16 v[70:73], v[160:163], v[216:219], v[70:73]
	s_setprio 0
	s_setprio 1
	v_mfma_f32_16x16x32_bf16 v[122:125], v[172:175], v[188:191], v[122:125]
	v_mfma_f32_16x16x32_bf16 v[122:125], v[176:179], v[192:195], v[122:125]
	v_mfma_f32_16x16x32_bf16 v[114:117], v[180:183], v[188:191], v[114:117]
	v_mfma_f32_16x16x32_bf16 v[114:117], v[184:187], v[192:195], v[114:117]
	v_mfma_f32_16x16x32_bf16 v[106:109], v[172:175], v[196:199], v[106:109]
	v_mfma_f32_16x16x32_bf16 v[106:109], v[176:179], v[200:203], v[106:109]
	v_mfma_f32_16x16x32_bf16 v[98:101], v[180:183], v[196:199], v[98:101]
	v_mfma_f32_16x16x32_bf16 v[98:101], v[184:187], v[200:203], v[98:101]
	v_mfma_f32_16x16x32_bf16 v[90:93], v[172:175], v[204:207], v[90:93]
	v_mfma_f32_16x16x32_bf16 v[90:93], v[176:179], v[208:211], v[90:93]
	v_mfma_f32_16x16x32_bf16 v[82:85], v[180:183], v[204:207], v[82:85]
	v_mfma_f32_16x16x32_bf16 v[82:85], v[184:187], v[208:211], v[82:85]
	v_mfma_f32_16x16x32_bf16 v[74:77], v[172:175], v[212:215], v[74:77]
	v_mfma_f32_16x16x32_bf16 v[74:77], v[176:179], v[216:219], v[74:77]
	v_mfma_f32_16x16x32_bf16 v[66:69], v[180:183], v[212:215], v[66:69]
	v_mfma_f32_16x16x32_bf16 v[66:69], v[184:187], v[216:219], v[66:69]
	s_setprio 0
	s_barrier
	s_add_i32 s0, s45, s35
	v_lshl_add_u64 v[220:221], s[2:3], 0, v[134:135]
	s_mov_b32 m0, s0
	ds_read_b128 v[188:191], v169 offset:16384
	ds_read_b128 v[192:195], v169 offset:17408
	ds_read_b128 v[196:199], v169 offset:18432
	ds_read_b128 v[200:203], v169 offset:19456
	ds_read_b128 v[204:207], v169 offset:20480
	ds_read_b128 v[208:211], v169 offset:21504
	ds_read_b128 v[212:215], v169 offset:22528
	ds_read_b128 v[216:219], v169 offset:23552
	global_load_lds_dwordx4 v[220:221], off
	s_add_i32 m0, s0, 0x2000
	s_add_u32 s0, s2, 0x40000
	v_lshl_add_u64 v[222:223], s[2:3], 0, v[130:131]
	s_addc_u32 s1, s3, 0
	s_add_i32 s54, s46, s35
	global_load_lds_dwordx4 v[222:223], off
	v_lshl_add_u64 v[224:225], s[0:1], 0, v[134:135]
	s_mov_b32 m0, s54
	v_lshl_add_u64 v[226:227], s[30:31], 0, v[132:133]
	global_load_lds_dwordx4 v[224:225], off
	v_lshl_add_u64 v[224:225], s[0:1], 0, v[130:131]
	s_add_i32 m0, s54, 0x2000
	s_nop 0
	global_load_lds_dwordx4 v[224:225], off
	v_lshl_add_u64 v[224:225], s[30:31], 0, v[136:137]
	s_mov_b32 m0, s38
	s_nop 0
	global_load_lds_dwordx4 v[224:225], off
	s_mov_b32 m0, s39
	s_nop 0
	global_load_lds_dwordx4 v[226:227], off
	s_waitcnt vmcnt(8)
	s_waitcnt lgkmcnt(0)
	s_barrier
	s_setprio 1
	v_mfma_f32_16x16x32_bf16 v[62:65], v[148:151], v[188:191], v[62:65]
	v_mfma_f32_16x16x32_bf16 v[62:65], v[152:155], v[192:195], v[62:65]
	v_mfma_f32_16x16x32_bf16 v[54:57], v[156:159], v[188:191], v[54:57]
	v_mfma_f32_16x16x32_bf16 v[54:57], v[160:163], v[192:195], v[54:57]
	v_mfma_f32_16x16x32_bf16 v[46:49], v[148:151], v[196:199], v[46:49]
	v_mfma_f32_16x16x32_bf16 v[46:49], v[152:155], v[200:203], v[46:49]
	v_mfma_f32_16x16x32_bf16 v[38:41], v[156:159], v[196:199], v[38:41]
	v_mfma_f32_16x16x32_bf16 v[38:41], v[160:163], v[200:203], v[38:41]
	v_mfma_f32_16x16x32_bf16 v[30:33], v[148:151], v[204:207], v[30:33]
	v_mfma_f32_16x16x32_bf16 v[30:33], v[152:155], v[208:211], v[30:33]
	v_mfma_f32_16x16x32_bf16 v[22:25], v[156:159], v[204:207], v[22:25]
	v_mfma_f32_16x16x32_bf16 v[22:25], v[160:163], v[208:211], v[22:25]
	v_mfma_f32_16x16x32_bf16 v[14:17], v[148:151], v[212:215], v[14:17]
	v_mfma_f32_16x16x32_bf16 v[14:17], v[152:155], v[216:219], v[14:17]
	v_mfma_f32_16x16x32_bf16 v[6:9], v[156:159], v[212:215], v[6:9]
	v_mfma_f32_16x16x32_bf16 v[6:9], v[160:163], v[216:219], v[6:9]
	s_setprio 0
	s_setprio 1
	v_mfma_f32_16x16x32_bf16 v[58:61], v[172:175], v[188:191], v[58:61]
	v_mfma_f32_16x16x32_bf16 v[58:61], v[176:179], v[192:195], v[58:61]
	v_mfma_f32_16x16x32_bf16 v[50:53], v[180:183], v[188:191], v[50:53]
	v_mfma_f32_16x16x32_bf16 v[50:53], v[184:187], v[192:195], v[50:53]
	v_mfma_f32_16x16x32_bf16 v[42:45], v[172:175], v[196:199], v[42:45]
	v_mfma_f32_16x16x32_bf16 v[42:45], v[176:179], v[200:203], v[42:45]
	v_mfma_f32_16x16x32_bf16 v[34:37], v[180:183], v[196:199], v[34:37]
	v_mfma_f32_16x16x32_bf16 v[34:37], v[184:187], v[200:203], v[34:37]
	v_mfma_f32_16x16x32_bf16 v[26:29], v[172:175], v[204:207], v[26:29]
	v_mfma_f32_16x16x32_bf16 v[26:29], v[176:179], v[208:211], v[26:29]
	v_mfma_f32_16x16x32_bf16 v[18:21], v[180:183], v[204:207], v[18:21]
	v_mfma_f32_16x16x32_bf16 v[18:21], v[184:187], v[208:211], v[18:21]
	v_mfma_f32_16x16x32_bf16 v[10:13], v[172:175], v[212:215], v[10:13]
	v_mfma_f32_16x16x32_bf16 v[10:13], v[176:179], v[216:219], v[10:13]
	v_mfma_f32_16x16x32_bf16 v[2:5], v[180:183], v[212:215], v[2:5]
	v_mfma_f32_16x16x32_bf16 v[2:5], v[184:187], v[216:219], v[2:5]
	s_setprio 0
	s_barrier
	s_add_i32 s54, 0, 0x18000
	s_add_i32 s55, 0, 0x1c000
	v_add_u32_e32 v160, s54, v166
	v_add_u32_e32 v171, s55, v166
	ds_read_b128 v[148:151], v160
	ds_read_b128 v[152:155], v160 offset:1024
	ds_read_b128 v[156:159], v160 offset:2048
	ds_read_b128 v[160:163], v160 offset:3072
	ds_read_b128 v[172:175], v171
	ds_read_b128 v[176:179], v171 offset:1024
	ds_read_b128 v[180:183], v171 offset:2048
	ds_read_b128 v[184:187], v171 offset:3072
	s_add_u32 s0, s30, 0x40000
	s_addc_u32 s1, s31, 0
	s_mov_b32 m0, s40
	v_lshl_add_u64 v[228:229], s[0:1], 0, v[136:137]
	ds_read_b128 v[188:191], v169 offset:32768
	ds_read_b128 v[192:195], v169 offset:33792
	ds_read_b128 v[196:199], v169 offset:34816
	ds_read_b128 v[200:203], v169 offset:35840
	ds_read_b128 v[204:207], v169 offset:36864
	ds_read_b128 v[208:211], v169 offset:37888
	ds_read_b128 v[212:215], v169 offset:38912
	ds_read_b128 v[216:219], v169 offset:39936
	global_load_lds_dwordx4 v[228:229], off
	v_lshl_add_u64 v[228:229], s[0:1], 0, v[132:133]
	s_mov_b32 m0, s41
	s_nop 0
	global_load_lds_dwordx4 v[228:229], off
	s_waitcnt vmcnt(8)
	s_waitcnt lgkmcnt(0)
	s_barrier
	s_setprio 1
	v_mfma_f32_16x16x32_bf16 v[126:129], v[148:151], v[188:191], v[126:129]
	v_mfma_f32_16x16x32_bf16 v[126:129], v[152:155], v[192:195], v[126:129]
	v_mfma_f32_16x16x32_bf16 v[118:121], v[156:159], v[188:191], v[118:121]
	v_mfma_f32_16x16x32_bf16 v[118:121], v[160:163], v[192:195], v[118:121]
	v_mfma_f32_16x16x32_bf16 v[110:113], v[148:151], v[196:199], v[110:113]
	v_mfma_f32_16x16x32_bf16 v[110:113], v[152:155], v[200:203], v[110:113]
	v_mfma_f32_16x16x32_bf16 v[102:105], v[156:159], v[196:199], v[102:105]
	v_mfma_f32_16x16x32_bf16 v[102:105], v[160:163], v[200:203], v[102:105]
	v_mfma_f32_16x16x32_bf16 v[94:97], v[148:151], v[204:207], v[94:97]
	v_mfma_f32_16x16x32_bf16 v[94:97], v[152:155], v[208:211], v[94:97]
	v_mfma_f32_16x16x32_bf16 v[86:89], v[156:159], v[204:207], v[86:89]
	v_mfma_f32_16x16x32_bf16 v[86:89], v[160:163], v[208:211], v[86:89]
	v_mfma_f32_16x16x32_bf16 v[78:81], v[148:151], v[212:215], v[78:81]
	v_mfma_f32_16x16x32_bf16 v[78:81], v[152:155], v[216:219], v[78:81]
	v_mfma_f32_16x16x32_bf16 v[70:73], v[156:159], v[212:215], v[70:73]
	v_mfma_f32_16x16x32_bf16 v[70:73], v[160:163], v[216:219], v[70:73]
	s_setprio 0
	s_setprio 1
	v_mfma_f32_16x16x32_bf16 v[122:125], v[172:175], v[188:191], v[122:125]
	v_mfma_f32_16x16x32_bf16 v[122:125], v[176:179], v[192:195], v[122:125]
	v_mfma_f32_16x16x32_bf16 v[114:117], v[180:183], v[188:191], v[114:117]
	v_mfma_f32_16x16x32_bf16 v[114:117], v[184:187], v[192:195], v[114:117]
	v_mfma_f32_16x16x32_bf16 v[106:109], v[172:175], v[196:199], v[106:109]
	v_mfma_f32_16x16x32_bf16 v[106:109], v[176:179], v[200:203], v[106:109]
	v_mfma_f32_16x16x32_bf16 v[98:101], v[180:183], v[196:199], v[98:101]
	v_mfma_f32_16x16x32_bf16 v[98:101], v[184:187], v[200:203], v[98:101]
	v_mfma_f32_16x16x32_bf16 v[90:93], v[172:175], v[204:207], v[90:93]
	v_mfma_f32_16x16x32_bf16 v[90:93], v[176:179], v[208:211], v[90:93]
	v_mfma_f32_16x16x32_bf16 v[82:85], v[180:183], v[204:207], v[82:85]
	v_mfma_f32_16x16x32_bf16 v[82:85], v[184:187], v[208:211], v[82:85]
	v_mfma_f32_16x16x32_bf16 v[74:77], v[172:175], v[212:215], v[74:77]
	v_mfma_f32_16x16x32_bf16 v[74:77], v[176:179], v[216:219], v[74:77]
	v_mfma_f32_16x16x32_bf16 v[66:69], v[180:183], v[212:215], v[66:69]
	v_mfma_f32_16x16x32_bf16 v[66:69], v[184:187], v[216:219], v[66:69]
	s_setprio 0
	s_barrier
	s_add_i32 s0, s54, s35
	v_lshl_add_u64 v[220:221], v[220:221], 0, s[14:15]
	s_mov_b32 m0, s0
	ds_read_b128 v[188:191], v169 offset:49152
	ds_read_b128 v[192:195], v169 offset:50176
	ds_read_b128 v[196:199], v169 offset:51200
	ds_read_b128 v[200:203], v169 offset:52224
	ds_read_b128 v[204:207], v169 offset:53248
	ds_read_b128 v[208:211], v169 offset:54272
	ds_read_b128 v[212:215], v169 offset:55296
	ds_read_b128 v[216:219], v169 offset:56320
	global_load_lds_dwordx4 v[220:221], off
	s_add_i32 m0, s0, 0x2000
	s_add_u32 s0, s2, 0x40080
	v_lshl_add_u64 v[220:221], v[222:223], 0, s[14:15]
	s_addc_u32 s1, s3, 0
	s_add_i32 s2, s55, s35
	global_load_lds_dwordx4 v[220:221], off
	v_lshl_add_u64 v[220:221], s[0:1], 0, v[134:135]
	s_mov_b32 m0, s2
	s_nop 0
	global_load_lds_dwordx4 v[220:221], off
	v_lshl_add_u64 v[220:221], s[0:1], 0, v[130:131]
	s_add_i32 m0, s2, 0x2000
	s_nop 0
	global_load_lds_dwordx4 v[220:221], off
	v_lshl_add_u64 v[220:221], v[224:225], 0, s[14:15]
	s_mov_b32 m0, s42
	s_nop 0
	global_load_lds_dwordx4 v[220:221], off
	v_lshl_add_u64 v[220:221], v[226:227], 0, s[14:15]
	s_mov_b32 m0, s43
	s_nop 0
	global_load_lds_dwordx4 v[220:221], off
	s_waitcnt vmcnt(8)
	s_waitcnt lgkmcnt(0)
	s_barrier
	s_setprio 1
	v_mfma_f32_16x16x32_bf16 v[62:65], v[148:151], v[188:191], v[62:65]
	v_mfma_f32_16x16x32_bf16 v[62:65], v[152:155], v[192:195], v[62:65]
	v_mfma_f32_16x16x32_bf16 v[54:57], v[156:159], v[188:191], v[54:57]
	v_mfma_f32_16x16x32_bf16 v[54:57], v[160:163], v[192:195], v[54:57]
	v_mfma_f32_16x16x32_bf16 v[46:49], v[148:151], v[196:199], v[46:49]
	v_mfma_f32_16x16x32_bf16 v[46:49], v[152:155], v[200:203], v[46:49]
	v_mfma_f32_16x16x32_bf16 v[38:41], v[156:159], v[196:199], v[38:41]
	v_mfma_f32_16x16x32_bf16 v[38:41], v[160:163], v[200:203], v[38:41]
	v_mfma_f32_16x16x32_bf16 v[30:33], v[148:151], v[204:207], v[30:33]
	v_mfma_f32_16x16x32_bf16 v[30:33], v[152:155], v[208:211], v[30:33]
	v_mfma_f32_16x16x32_bf16 v[22:25], v[156:159], v[204:207], v[22:25]
	v_mfma_f32_16x16x32_bf16 v[22:25], v[160:163], v[208:211], v[22:25]
	v_mfma_f32_16x16x32_bf16 v[14:17], v[148:151], v[212:215], v[14:17]
	v_mfma_f32_16x16x32_bf16 v[14:17], v[152:155], v[216:219], v[14:17]
	v_mfma_f32_16x16x32_bf16 v[6:9], v[156:159], v[212:215], v[6:9]
	v_mfma_f32_16x16x32_bf16 v[6:9], v[160:163], v[216:219], v[6:9]
	s_setprio 0
	s_setprio 1
	v_mfma_f32_16x16x32_bf16 v[58:61], v[172:175], v[188:191], v[58:61]
	s_add_i32 s53, s53, 2
	s_add_u32 s28, s28, 0x100
	s_addc_u32 s29, s29, 0
	s_add_u32 s51, s51, 0x100
	s_addc_u32 s52, s52, 0
	s_cmp_gt_u32 s53, 13
	v_mfma_f32_16x16x32_bf16 v[58:61], v[176:179], v[192:195], v[58:61]
	v_mfma_f32_16x16x32_bf16 v[50:53], v[180:183], v[188:191], v[50:53]
	v_mfma_f32_16x16x32_bf16 v[50:53], v[184:187], v[192:195], v[50:53]
	v_mfma_f32_16x16x32_bf16 v[42:45], v[172:175], v[196:199], v[42:45]
	v_mfma_f32_16x16x32_bf16 v[42:45], v[176:179], v[200:203], v[42:45]
	v_mfma_f32_16x16x32_bf16 v[34:37], v[180:183], v[196:199], v[34:37]
	v_mfma_f32_16x16x32_bf16 v[34:37], v[184:187], v[200:203], v[34:37]
	v_mfma_f32_16x16x32_bf16 v[26:29], v[172:175], v[204:207], v[26:29]
	v_mfma_f32_16x16x32_bf16 v[26:29], v[176:179], v[208:211], v[26:29]
	v_mfma_f32_16x16x32_bf16 v[18:21], v[180:183], v[204:207], v[18:21]
	v_mfma_f32_16x16x32_bf16 v[18:21], v[184:187], v[208:211], v[18:21]
	v_mfma_f32_16x16x32_bf16 v[10:13], v[172:175], v[212:215], v[10:13]
	v_mfma_f32_16x16x32_bf16 v[10:13], v[176:179], v[216:219], v[10:13]
	v_mfma_f32_16x16x32_bf16 v[2:5], v[180:183], v[212:215], v[2:5]
	v_mfma_f32_16x16x32_bf16 v[2:5], v[184:187], v[216:219], v[2:5]
	s_setprio 0
	s_barrier
	s_cbranch_scc0 .LBB0_471
	s_and_b64 vcc, exec, s[16:17]
	s_cbranch_vccz .LBB0_474
	s_barrier

.LBB0_584:
	ds_read_b128 v[130:133], v187
	ds_read_b128 v[134:137], v187 offset:1024
	ds_read_b128 v[138:141], v187 offset:2048
	ds_read_b128 v[142:145], v187 offset:3072
	ds_read_b128 v[146:149], v188
	ds_read_b128 v[150:153], v188 offset:1024
	ds_read_b128 v[170:173], v188 offset:2048
	ds_read_b128 v[174:177], v188 offset:3072
	s_add_u32 s0, s22, 0xfff50080
	s_addc_u32 s1, s23, -1
	s_cmp_eq_u32 s47, 40
	s_cselect_b32 s25, s9, s1
	s_cselect_b32 s24, s8, s0
	s_cselect_b32 s3, s21, s46
	s_cselect_b32 s2, s20, s45
	v_lshl_add_u64 v[220:221], s[22:23], 0, v[162:163]
	s_add_i32 m0, s31, 0xc000
	ds_read_b128 v[178:181], v189
	ds_read_b128 v[192:195], v189 offset:1024
	ds_read_b128 v[196:199], v189 offset:2048
	ds_read_b128 v[200:203], v189 offset:3072
	ds_read_b128 v[204:207], v189 offset:4096
	ds_read_b128 v[208:211], v189 offset:5120
	ds_read_b128 v[212:215], v189 offset:6144
	ds_read_b128 v[216:219], v189 offset:7168
	global_load_lds_dwordx4 v[220:221], off
	v_lshl_add_u64 v[220:221], s[22:23], 0, v[164:165]
	s_add_i32 m0, s31, 0xe000
	s_nop 0
	global_load_lds_dwordx4 v[220:221], off
	s_waitcnt vmcnt(8)
	s_waitcnt lgkmcnt(0)
	s_barrier
	s_setprio 1
	v_mfma_f32_16x16x32_bf16 v[126:129], v[130:133], v[178:181], v[126:129]
	v_mfma_f32_16x16x32_bf16 v[126:129], v[134:137], v[192:195], v[126:129]
	v_mfma_f32_16x16x32_bf16 v[122:125], v[138:141], v[178:181], v[122:125]
	v_mfma_f32_16x16x32_bf16 v[122:125], v[142:145], v[192:195], v[122:125]
	v_mfma_f32_16x16x32_bf16 v[110:113], v[130:133], v[196:199], v[110:113]
	v_mfma_f32_16x16x32_bf16 v[110:113], v[134:137], v[200:203], v[110:113]
	v_mfma_f32_16x16x32_bf16 v[106:109], v[138:141], v[196:199], v[106:109]
	v_mfma_f32_16x16x32_bf16 v[106:109], v[142:145], v[200:203], v[106:109]
	v_mfma_f32_16x16x32_bf16 v[94:97], v[130:133], v[204:207], v[94:97]
	v_mfma_f32_16x16x32_bf16 v[94:97], v[134:137], v[208:211], v[94:97]
	v_mfma_f32_16x16x32_bf16 v[90:93], v[138:141], v[204:207], v[90:93]
	v_mfma_f32_16x16x32_bf16 v[90:93], v[142:145], v[208:211], v[90:93]
	v_mfma_f32_16x16x32_bf16 v[78:81], v[130:133], v[212:215], v[78:81]
	v_mfma_f32_16x16x32_bf16 v[78:81], v[134:137], v[216:219], v[78:81]
	v_mfma_f32_16x16x32_bf16 v[74:77], v[138:141], v[212:215], v[74:77]
	v_mfma_f32_16x16x32_bf16 v[74:77], v[142:145], v[216:219], v[74:77]
	s_setprio 0
	s_setprio 1
	v_mfma_f32_16x16x32_bf16 v[118:121], v[146:149], v[178:181], v[118:121]
	v_mfma_f32_16x16x32_bf16 v[118:121], v[150:153], v[192:195], v[118:121]
	v_mfma_f32_16x16x32_bf16 v[114:117], v[170:173], v[178:181], v[114:117]
	v_mfma_f32_16x16x32_bf16 v[114:117], v[174:177], v[192:195], v[114:117]
	v_mfma_f32_16x16x32_bf16 v[102:105], v[146:149], v[196:199], v[102:105]
	v_mfma_f32_16x16x32_bf16 v[102:105], v[150:153], v[200:203], v[102:105]
	v_mfma_f32_16x16x32_bf16 v[98:101], v[170:173], v[196:199], v[98:101]
	v_mfma_f32_16x16x32_bf16 v[98:101], v[174:177], v[200:203], v[98:101]
	v_mfma_f32_16x16x32_bf16 v[86:89], v[146:149], v[204:207], v[86:89]
	v_mfma_f32_16x16x32_bf16 v[86:89], v[150:153], v[208:211], v[86:89]
	v_mfma_f32_16x16x32_bf16 v[82:85], v[170:173], v[204:207], v[82:85]
	v_mfma_f32_16x16x32_bf16 v[82:85], v[174:177], v[208:211], v[82:85]
	v_mfma_f32_16x16x32_bf16 v[70:73], v[146:149], v[212:215], v[70:73]
	v_mfma_f32_16x16x32_bf16 v[70:73], v[150:153], v[216:219], v[70:73]
	v_mfma_f32_16x16x32_bf16 v[66:69], v[170:173], v[212:215], v[66:69]
	v_mfma_f32_16x16x32_bf16 v[66:69], v[174:177], v[216:219], v[66:69]
	s_setprio 0
	s_barrier
	s_add_i32 s0, s41, s30
	v_lshl_add_u64 v[220:221], s[2:3], 0, v[156:157]
	s_mov_b32 m0, s0
	ds_read_b128 v[178:181], v189 offset:16384
	ds_read_b128 v[192:195], v189 offset:17408
	ds_read_b128 v[196:199], v189 offset:18432
	ds_read_b128 v[200:203], v189 offset:19456
	ds_read_b128 v[204:207], v189 offset:20480
	ds_read_b128 v[208:211], v189 offset:21504
	ds_read_b128 v[212:215], v189 offset:22528
	ds_read_b128 v[216:219], v189 offset:23552
	global_load_lds_dwordx4 v[220:221], off
	s_add_i32 m0, s0, 0x2000
	s_add_u32 s0, s2, 0xb0000
	v_lshl_add_u64 v[222:223], s[2:3], 0, v[160:161]
	s_addc_u32 s1, s3, 0
	s_add_i32 s48, s42, s30
	global_load_lds_dwordx4 v[222:223], off
	v_lshl_add_u64 v[224:225], s[0:1], 0, v[156:157]
	s_mov_b32 m0, s48
	v_lshl_add_u64 v[226:227], s[24:25], 0, v[158:159]
	global_load_lds_dwordx4 v[224:225], off
	v_lshl_add_u64 v[224:225], s[0:1], 0, v[160:161]
	s_add_i32 m0, s48, 0x2000
	s_nop 0
	global_load_lds_dwordx4 v[224:225], off
	v_lshl_add_u64 v[224:225], s[24:25], 0, v[154:155]
	s_mov_b32 m0, s31
	s_nop 0
	global_load_lds_dwordx4 v[224:225], off
	s_mov_b32 m0, s33
	s_nop 0
	global_load_lds_dwordx4 v[226:227], off
	s_waitcnt vmcnt(8)
	s_waitcnt lgkmcnt(0)
	s_barrier
	s_setprio 1
	v_mfma_f32_16x16x32_bf16 v[62:65], v[130:133], v[178:181], v[62:65]
	v_mfma_f32_16x16x32_bf16 v[62:65], v[134:137], v[192:195], v[62:65]
	v_mfma_f32_16x16x32_bf16 v[58:61], v[138:141], v[178:181], v[58:61]
	v_mfma_f32_16x16x32_bf16 v[58:61], v[142:145], v[192:195], v[58:61]
	v_mfma_f32_16x16x32_bf16 v[46:49], v[130:133], v[196:199], v[46:49]
	v_mfma_f32_16x16x32_bf16 v[46:49], v[134:137], v[200:203], v[46:49]
	v_mfma_f32_16x16x32_bf16 v[42:45], v[138:141], v[196:199], v[42:45]
	v_mfma_f32_16x16x32_bf16 v[42:45], v[142:145], v[200:203], v[42:45]
	v_mfma_f32_16x16x32_bf16 v[30:33], v[130:133], v[204:207], v[30:33]
	v_mfma_f32_16x16x32_bf16 v[30:33], v[134:137], v[208:211], v[30:33]
	v_mfma_f32_16x16x32_bf16 v[26:29], v[138:141], v[204:207], v[26:29]
	v_mfma_f32_16x16x32_bf16 v[26:29], v[142:145], v[208:211], v[26:29]
	v_mfma_f32_16x16x32_bf16 v[14:17], v[130:133], v[212:215], v[14:17]
	v_mfma_f32_16x16x32_bf16 v[14:17], v[134:137], v[216:219], v[14:17]
	v_mfma_f32_16x16x32_bf16 v[10:13], v[138:141], v[212:215], v[10:13]
	v_mfma_f32_16x16x32_bf16 v[10:13], v[142:145], v[216:219], v[10:13]
	s_setprio 0
	s_setprio 1
	v_mfma_f32_16x16x32_bf16 v[54:57], v[146:149], v[178:181], v[54:57]
	v_mfma_f32_16x16x32_bf16 v[54:57], v[150:153], v[192:195], v[54:57]
	v_mfma_f32_16x16x32_bf16 v[50:53], v[170:173], v[178:181], v[50:53]
	v_mfma_f32_16x16x32_bf16 v[50:53], v[174:177], v[192:195], v[50:53]
	v_mfma_f32_16x16x32_bf16 v[38:41], v[146:149], v[196:199], v[38:41]
	v_mfma_f32_16x16x32_bf16 v[38:41], v[150:153], v[200:203], v[38:41]
	v_mfma_f32_16x16x32_bf16 v[34:37], v[170:173], v[196:199], v[34:37]
	v_mfma_f32_16x16x32_bf16 v[34:37], v[174:177], v[200:203], v[34:37]
	v_mfma_f32_16x16x32_bf16 v[22:25], v[146:149], v[204:207], v[22:25]
	v_mfma_f32_16x16x32_bf16 v[22:25], v[150:153], v[208:211], v[22:25]
	v_mfma_f32_16x16x32_bf16 v[18:21], v[170:173], v[204:207], v[18:21]
	v_mfma_f32_16x16x32_bf16 v[18:21], v[174:177], v[208:211], v[18:21]
	v_mfma_f32_16x16x32_bf16 v[6:9], v[146:149], v[212:215], v[6:9]
	v_mfma_f32_16x16x32_bf16 v[6:9], v[150:153], v[216:219], v[6:9]
	v_mfma_f32_16x16x32_bf16 v[2:5], v[170:173], v[212:215], v[2:5]
	v_mfma_f32_16x16x32_bf16 v[2:5], v[174:177], v[216:219], v[2:5]
	s_setprio 0
	s_barrier
	s_add_i32 s48, 0, 0x18000
	s_add_i32 s49, 0, 0x1c000
	v_add_u32_e32 v142, s48, v183
	v_add_u32_e32 v174, s49, v183
	ds_read_b128 v[130:133], v142
	ds_read_b128 v[134:137], v142 offset:1024
	ds_read_b128 v[138:141], v142 offset:2048
	ds_read_b128 v[142:145], v142 offset:3072
	ds_read_b128 v[146:149], v174
	ds_read_b128 v[150:153], v174 offset:1024
	ds_read_b128 v[170:173], v174 offset:2048
	ds_read_b128 v[174:177], v174 offset:3072
	s_add_u32 s0, s24, 0xb0000
	s_addc_u32 s1, s25, 0
	s_mov_b32 m0, s34
	v_lshl_add_u64 v[228:229], s[0:1], 0, v[154:155]
	ds_read_b128 v[178:181], v189 offset:32768
	ds_read_b128 v[192:195], v189 offset:33792
	ds_read_b128 v[196:199], v189 offset:34816
	ds_read_b128 v[200:203], v189 offset:35840
	ds_read_b128 v[204:207], v189 offset:36864
	ds_read_b128 v[208:211], v189 offset:37888
	ds_read_b128 v[212:215], v189 offset:38912
	ds_read_b128 v[216:219], v189 offset:39936
	global_load_lds_dwordx4 v[228:229], off
	v_lshl_add_u64 v[228:229], s[0:1], 0, v[158:159]
	s_mov_b32 m0, s35
	s_nop 0
	global_load_lds_dwordx4 v[228:229], off
	s_waitcnt vmcnt(8)
	s_waitcnt lgkmcnt(0)
	s_barrier
	s_setprio 1
	v_mfma_f32_16x16x32_bf16 v[126:129], v[130:133], v[178:181], v[126:129]
	v_mfma_f32_16x16x32_bf16 v[126:129], v[134:137], v[192:195], v[126:129]
	v_mfma_f32_16x16x32_bf16 v[122:125], v[138:141], v[178:181], v[122:125]
	v_mfma_f32_16x16x32_bf16 v[122:125], v[142:145], v[192:195], v[122:125]
	v_mfma_f32_16x16x32_bf16 v[110:113], v[130:133], v[196:199], v[110:113]
	v_mfma_f32_16x16x32_bf16 v[110:113], v[134:137], v[200:203], v[110:113]
	v_mfma_f32_16x16x32_bf16 v[106:109], v[138:141], v[196:199], v[106:109]
	v_mfma_f32_16x16x32_bf16 v[106:109], v[142:145], v[200:203], v[106:109]
	v_mfma_f32_16x16x32_bf16 v[94:97], v[130:133], v[204:207], v[94:97]
	v_mfma_f32_16x16x32_bf16 v[94:97], v[134:137], v[208:211], v[94:97]
	v_mfma_f32_16x16x32_bf16 v[90:93], v[138:141], v[204:207], v[90:93]
	v_mfma_f32_16x16x32_bf16 v[90:93], v[142:145], v[208:211], v[90:93]
	v_mfma_f32_16x16x32_bf16 v[78:81], v[130:133], v[212:215], v[78:81]
	v_mfma_f32_16x16x32_bf16 v[78:81], v[134:137], v[216:219], v[78:81]
	v_mfma_f32_16x16x32_bf16 v[74:77], v[138:141], v[212:215], v[74:77]
	v_mfma_f32_16x16x32_bf16 v[74:77], v[142:145], v[216:219], v[74:77]
	s_setprio 0
	s_setprio 1
	v_mfma_f32_16x16x32_bf16 v[118:121], v[146:149], v[178:181], v[118:121]
	v_mfma_f32_16x16x32_bf16 v[118:121], v[150:153], v[192:195], v[118:121]
	v_mfma_f32_16x16x32_bf16 v[114:117], v[170:173], v[178:181], v[114:117]
	v_mfma_f32_16x16x32_bf16 v[114:117], v[174:177], v[192:195], v[114:117]
	v_mfma_f32_16x16x32_bf16 v[102:105], v[146:149], v[196:199], v[102:105]
	v_mfma_f32_16x16x32_bf16 v[102:105], v[150:153], v[200:203], v[102:105]
	v_mfma_f32_16x16x32_bf16 v[98:101], v[170:173], v[196:199], v[98:101]
	v_mfma_f32_16x16x32_bf16 v[98:101], v[174:177], v[200:203], v[98:101]
	v_mfma_f32_16x16x32_bf16 v[86:89], v[146:149], v[204:207], v[86:89]
	v_mfma_f32_16x16x32_bf16 v[86:89], v[150:153], v[208:211], v[86:89]
	v_mfma_f32_16x16x32_bf16 v[82:85], v[170:173], v[204:207], v[82:85]
	v_mfma_f32_16x16x32_bf16 v[82:85], v[174:177], v[208:211], v[82:85]
	v_mfma_f32_16x16x32_bf16 v[70:73], v[146:149], v[212:215], v[70:73]
	v_mfma_f32_16x16x32_bf16 v[70:73], v[150:153], v[216:219], v[70:73]
	v_mfma_f32_16x16x32_bf16 v[66:69], v[170:173], v[212:215], v[66:69]
	v_mfma_f32_16x16x32_bf16 v[66:69], v[174:177], v[216:219], v[66:69]
	s_setprio 0
	s_barrier
	s_add_i32 s0, s48, s30
	v_lshl_add_u64 v[220:221], v[220:221], 0, s[16:17]
	s_mov_b32 m0, s0
	ds_read_b128 v[178:181], v189 offset:49152
	ds_read_b128 v[192:195], v189 offset:50176
	ds_read_b128 v[196:199], v189 offset:51200
	ds_read_b128 v[200:203], v189 offset:52224
	ds_read_b128 v[204:207], v189 offset:53248
	ds_read_b128 v[208:211], v189 offset:54272
	ds_read_b128 v[212:215], v189 offset:55296
	ds_read_b128 v[216:219], v189 offset:56320
	global_load_lds_dwordx4 v[220:221], off
	s_add_i32 m0, s0, 0x2000
	s_add_u32 s0, s2, 0xb0080
	v_lshl_add_u64 v[220:221], v[222:223], 0, s[16:17]
	s_addc_u32 s1, s3, 0
	s_add_i32 s2, s49, s30
	global_load_lds_dwordx4 v[220:221], off
	v_lshl_add_u64 v[220:221], s[0:1], 0, v[156:157]
	s_mov_b32 m0, s2
	s_nop 0
	global_load_lds_dwordx4 v[220:221], off
	v_lshl_add_u64 v[220:221], s[0:1], 0, v[160:161]
	s_add_i32 m0, s2, 0x2000
	s_nop 0
	global_load_lds_dwordx4 v[220:221], off
	v_lshl_add_u64 v[220:221], v[224:225], 0, s[16:17]
	s_mov_b32 m0, s37
	s_nop 0
	global_load_lds_dwordx4 v[220:221], off
	v_lshl_add_u64 v[220:221], v[226:227], 0, s[16:17]
	s_mov_b32 m0, s38
	s_nop 0
	global_load_lds_dwordx4 v[220:221], off
	s_waitcnt vmcnt(8)
	s_waitcnt lgkmcnt(0)
	s_barrier
	s_setprio 1
	v_mfma_f32_16x16x32_bf16 v[62:65], v[130:133], v[178:181], v[62:65]
	v_mfma_f32_16x16x32_bf16 v[62:65], v[134:137], v[192:195], v[62:65]
	v_mfma_f32_16x16x32_bf16 v[58:61], v[138:141], v[178:181], v[58:61]
	v_mfma_f32_16x16x32_bf16 v[58:61], v[142:145], v[192:195], v[58:61]
	v_mfma_f32_16x16x32_bf16 v[46:49], v[130:133], v[196:199], v[46:49]
	v_mfma_f32_16x16x32_bf16 v[46:49], v[134:137], v[200:203], v[46:49]
	v_mfma_f32_16x16x32_bf16 v[42:45], v[138:141], v[196:199], v[42:45]
	v_mfma_f32_16x16x32_bf16 v[42:45], v[142:145], v[200:203], v[42:45]
	v_mfma_f32_16x16x32_bf16 v[30:33], v[130:133], v[204:207], v[30:33]
	v_mfma_f32_16x16x32_bf16 v[30:33], v[134:137], v[208:211], v[30:33]
	v_mfma_f32_16x16x32_bf16 v[26:29], v[138:141], v[204:207], v[26:29]
	v_mfma_f32_16x16x32_bf16 v[26:29], v[142:145], v[208:211], v[26:29]
	v_mfma_f32_16x16x32_bf16 v[14:17], v[130:133], v[212:215], v[14:17]
	v_mfma_f32_16x16x32_bf16 v[14:17], v[134:137], v[216:219], v[14:17]
	v_mfma_f32_16x16x32_bf16 v[10:13], v[138:141], v[212:215], v[10:13]
	v_mfma_f32_16x16x32_bf16 v[10:13], v[142:145], v[216:219], v[10:13]
	s_setprio 0
	s_setprio 1
	v_mfma_f32_16x16x32_bf16 v[54:57], v[146:149], v[178:181], v[54:57]
	s_add_i32 s47, s47, 2
	s_add_u32 s22, s22, 0x100
	s_addc_u32 s23, s23, 0
	s_add_u32 s45, s45, 0x100
	s_addc_u32 s46, s46, 0
	s_cmp_gt_u32 s47, 41
	v_mfma_f32_16x16x32_bf16 v[54:57], v[150:153], v[192:195], v[54:57]
	v_mfma_f32_16x16x32_bf16 v[50:53], v[170:173], v[178:181], v[50:53]
	v_mfma_f32_16x16x32_bf16 v[50:53], v[174:177], v[192:195], v[50:53]
	v_mfma_f32_16x16x32_bf16 v[38:41], v[146:149], v[196:199], v[38:41]
	v_mfma_f32_16x16x32_bf16 v[38:41], v[150:153], v[200:203], v[38:41]
	v_mfma_f32_16x16x32_bf16 v[34:37], v[170:173], v[196:199], v[34:37]
	v_mfma_f32_16x16x32_bf16 v[34:37], v[174:177], v[200:203], v[34:37]
	v_mfma_f32_16x16x32_bf16 v[22:25], v[146:149], v[204:207], v[22:25]
	v_mfma_f32_16x16x32_bf16 v[22:25], v[150:153], v[208:211], v[22:25]
	v_mfma_f32_16x16x32_bf16 v[18:21], v[170:173], v[204:207], v[18:21]
	v_mfma_f32_16x16x32_bf16 v[18:21], v[174:177], v[208:211], v[18:21]
	v_mfma_f32_16x16x32_bf16 v[6:9], v[146:149], v[212:215], v[6:9]
	v_mfma_f32_16x16x32_bf16 v[6:9], v[150:153], v[216:219], v[6:9]
	v_mfma_f32_16x16x32_bf16 v[2:5], v[170:173], v[212:215], v[2:5]
	v_mfma_f32_16x16x32_bf16 v[2:5], v[174:177], v[216:219], v[2:5]
	s_setprio 0
	s_barrier
	s_cbranch_scc0 .LBB0_584
	s_and_b64 vcc, exec, s[18:19]
	s_cbranch_vccz .LBB0_587
	s_barrier

.LBB0_675:
	ds_read_b128 v[82:85], v219
	ds_read_b128 v[86:89], v219 offset:1024
	ds_read_b128 v[94:97], v219 offset:2048
	ds_read_b128 v[102:105], v219 offset:3072
	ds_read_b128 v[110:113], v220
	ds_read_b128 v[118:121], v220 offset:1024
	ds_read_b128 v[138:141], v220 offset:2048
	ds_read_b128 v[158:161], v220 offset:3072
	s_add_u32 s0, s8, 0xfffc0080
	s_addc_u32 s1, s9, -1
	s_cmp_eq_u32 s51, 12
	s_cselect_b32 s31, s7, s1
	s_cselect_b32 s30, s23, s0
	s_cselect_b32 s3, s21, s50
	s_cselect_b32 s2, s34, s35
	v_lshl_add_u64 v[224:225], s[8:9], 0, v[190:191]
	s_add_i32 m0, s29, 0xc000
	ds_read_b128 v[162:165], v221
	ds_read_b128 v[166:169], v221 offset:1024
	ds_read_b128 v[170:173], v221 offset:2048
	ds_read_b128 v[174:177], v221 offset:3072
	ds_read_b128 v[198:201], v221 offset:4096
	ds_read_b128 v[202:205], v221 offset:5120
	ds_read_b128 v[206:209], v221 offset:6144
	ds_read_b128 v[210:213], v221 offset:7168
	global_load_lds_dwordx4 v[224:225], off
	v_lshl_add_u64 v[224:225], s[8:9], 0, v[192:193]
	s_add_i32 m0, s29, 0xe000
	s_nop 0
	global_load_lds_dwordx4 v[224:225], off
	s_waitcnt vmcnt(8)
	s_waitcnt lgkmcnt(0)
	s_barrier
	s_setprio 1
	v_mfma_f32_16x16x32_bf16 v[154:157], v[82:85], v[162:165], v[154:157]
	v_mfma_f32_16x16x32_bf16 v[154:157], v[86:89], v[166:169], v[154:157]
	v_mfma_f32_16x16x32_bf16 v[150:153], v[94:97], v[162:165], v[150:153]
	v_mfma_f32_16x16x32_bf16 v[150:153], v[102:105], v[166:169], v[150:153]
	v_mfma_f32_16x16x32_bf16 v[134:137], v[82:85], v[170:173], v[134:137]
	v_mfma_f32_16x16x32_bf16 v[134:137], v[86:89], v[174:177], v[134:137]
	v_mfma_f32_16x16x32_bf16 v[130:133], v[94:97], v[170:173], v[130:133]
	v_mfma_f32_16x16x32_bf16 v[130:133], v[102:105], v[174:177], v[130:133]
	v_mfma_f32_16x16x32_bf16 v[114:117], v[82:85], v[198:201], v[114:117]
	v_mfma_f32_16x16x32_bf16 v[114:117], v[86:89], v[202:205], v[114:117]
	v_mfma_f32_16x16x32_bf16 v[106:109], v[94:97], v[198:201], v[106:109]
	v_mfma_f32_16x16x32_bf16 v[106:109], v[102:105], v[202:205], v[106:109]
	v_mfma_f32_16x16x32_bf16 v[78:81], v[82:85], v[206:209], v[78:81]
	v_mfma_f32_16x16x32_bf16 v[78:81], v[86:89], v[210:213], v[78:81]
	v_mfma_f32_16x16x32_bf16 v[74:77], v[94:97], v[206:209], v[74:77]
	v_mfma_f32_16x16x32_bf16 v[74:77], v[102:105], v[210:213], v[74:77]
	s_setprio 0
	s_setprio 1
	v_mfma_f32_16x16x32_bf16 v[146:149], v[110:113], v[162:165], v[146:149]
	v_mfma_f32_16x16x32_bf16 v[146:149], v[118:121], v[166:169], v[146:149]
	v_mfma_f32_16x16x32_bf16 v[142:145], v[138:141], v[162:165], v[142:145]
	v_mfma_f32_16x16x32_bf16 v[142:145], v[158:161], v[166:169], v[142:145]
	v_mfma_f32_16x16x32_bf16 v[126:129], v[110:113], v[170:173], v[126:129]
	v_mfma_f32_16x16x32_bf16 v[126:129], v[118:121], v[174:177], v[126:129]
	v_mfma_f32_16x16x32_bf16 v[122:125], v[138:141], v[170:173], v[122:125]
	v_mfma_f32_16x16x32_bf16 v[122:125], v[158:161], v[174:177], v[122:125]
	v_mfma_f32_16x16x32_bf16 v[98:101], v[110:113], v[198:201], v[98:101]
	v_mfma_f32_16x16x32_bf16 v[98:101], v[118:121], v[202:205], v[98:101]
	v_mfma_f32_16x16x32_bf16 v[90:93], v[138:141], v[198:201], v[90:93]
	v_mfma_f32_16x16x32_bf16 v[90:93], v[158:161], v[202:205], v[90:93]
	v_mfma_f32_16x16x32_bf16 v[70:73], v[110:113], v[206:209], v[70:73]
	v_mfma_f32_16x16x32_bf16 v[70:73], v[118:121], v[210:213], v[70:73]
	v_mfma_f32_16x16x32_bf16 v[66:69], v[138:141], v[206:209], v[66:69]
	v_mfma_f32_16x16x32_bf16 v[66:69], v[158:161], v[210:213], v[66:69]
	s_setprio 0
	s_barrier
	s_add_i32 s0, s48, s36
	v_lshl_add_u64 v[224:225], s[2:3], 0, v[182:183]
	s_mov_b32 m0, s0
	ds_read_b128 v[162:165], v221 offset:16384
	ds_read_b128 v[166:169], v221 offset:17408
	ds_read_b128 v[170:173], v221 offset:18432
	ds_read_b128 v[174:177], v221 offset:19456
	ds_read_b128 v[198:201], v221 offset:20480
	ds_read_b128 v[202:205], v221 offset:21504
	ds_read_b128 v[206:209], v221 offset:22528
	ds_read_b128 v[210:213], v221 offset:23552
	global_load_lds_dwordx4 v[224:225], off
	s_add_i32 m0, s0, 0x2000
	s_add_u32 s0, s2, 0x40000
	v_lshl_add_u64 v[226:227], s[2:3], 0, v[186:187]
	s_addc_u32 s1, s3, 0
	s_add_i32 s52, s49, s36
	global_load_lds_dwordx4 v[226:227], off
	v_lshl_add_u64 v[228:229], s[0:1], 0, v[182:183]
	s_mov_b32 m0, s52
	v_lshl_add_u64 v[230:231], s[30:31], 0, v[184:185]
	global_load_lds_dwordx4 v[228:229], off
	v_lshl_add_u64 v[228:229], s[0:1], 0, v[186:187]
	s_add_i32 m0, s52, 0x2000
	s_nop 0
	global_load_lds_dwordx4 v[228:229], off
	v_lshl_add_u64 v[228:229], s[30:31], 0, v[180:181]
	s_mov_b32 m0, s29
	s_nop 0
	global_load_lds_dwordx4 v[228:229], off
	s_mov_b32 m0, s37
	s_nop 0
	global_load_lds_dwordx4 v[230:231], off
	s_waitcnt vmcnt(8)
	s_waitcnt lgkmcnt(0)
	s_barrier
	s_setprio 1
	v_mfma_f32_16x16x32_bf16 v[62:65], v[82:85], v[162:165], v[62:65]
	v_mfma_f32_16x16x32_bf16 v[62:65], v[86:89], v[166:169], v[62:65]
	v_mfma_f32_16x16x32_bf16 v[58:61], v[94:97], v[162:165], v[58:61]
	v_mfma_f32_16x16x32_bf16 v[58:61], v[102:105], v[166:169], v[58:61]
	v_mfma_f32_16x16x32_bf16 v[46:49], v[82:85], v[170:173], v[46:49]
	v_mfma_f32_16x16x32_bf16 v[46:49], v[86:89], v[174:177], v[46:49]
	v_mfma_f32_16x16x32_bf16 v[42:45], v[94:97], v[170:173], v[42:45]
	v_mfma_f32_16x16x32_bf16 v[42:45], v[102:105], v[174:177], v[42:45]
	v_mfma_f32_16x16x32_bf16 v[30:33], v[82:85], v[198:201], v[30:33]
	v_mfma_f32_16x16x32_bf16 v[30:33], v[86:89], v[202:205], v[30:33]
	v_mfma_f32_16x16x32_bf16 v[26:29], v[94:97], v[198:201], v[26:29]
	v_mfma_f32_16x16x32_bf16 v[26:29], v[102:105], v[202:205], v[26:29]
	v_mfma_f32_16x16x32_bf16 v[14:17], v[82:85], v[206:209], v[14:17]
	v_mfma_f32_16x16x32_bf16 v[14:17], v[86:89], v[210:213], v[14:17]
	v_mfma_f32_16x16x32_bf16 v[10:13], v[94:97], v[206:209], v[10:13]
	v_mfma_f32_16x16x32_bf16 v[10:13], v[102:105], v[210:213], v[10:13]
	s_setprio 0
	s_setprio 1
	v_mfma_f32_16x16x32_bf16 v[54:57], v[110:113], v[162:165], v[54:57]
	v_mfma_f32_16x16x32_bf16 v[54:57], v[118:121], v[166:169], v[54:57]
	v_mfma_f32_16x16x32_bf16 v[50:53], v[138:141], v[162:165], v[50:53]
	v_mfma_f32_16x16x32_bf16 v[50:53], v[158:161], v[166:169], v[50:53]
	v_mfma_f32_16x16x32_bf16 v[38:41], v[110:113], v[170:173], v[38:41]
	v_mfma_f32_16x16x32_bf16 v[38:41], v[118:121], v[174:177], v[38:41]
	v_mfma_f32_16x16x32_bf16 v[34:37], v[138:141], v[170:173], v[34:37]
	v_mfma_f32_16x16x32_bf16 v[34:37], v[158:161], v[174:177], v[34:37]
	v_mfma_f32_16x16x32_bf16 v[22:25], v[110:113], v[198:201], v[22:25]
	v_mfma_f32_16x16x32_bf16 v[22:25], v[118:121], v[202:205], v[22:25]
	v_mfma_f32_16x16x32_bf16 v[18:21], v[138:141], v[198:201], v[18:21]
	v_mfma_f32_16x16x32_bf16 v[18:21], v[158:161], v[202:205], v[18:21]
	v_mfma_f32_16x16x32_bf16 v[6:9], v[110:113], v[206:209], v[6:9]
	v_mfma_f32_16x16x32_bf16 v[6:9], v[118:121], v[210:213], v[6:9]
	v_mfma_f32_16x16x32_bf16 v[2:5], v[138:141], v[206:209], v[2:5]
	v_mfma_f32_16x16x32_bf16 v[2:5], v[158:161], v[210:213], v[2:5]
	s_setprio 0
	s_barrier
	s_add_i32 s52, 0, 0x18000
	s_add_i32 s53, 0, 0x1c000
	v_add_u32_e32 v102, s52, v218
	v_add_u32_e32 v158, s53, v218
	ds_read_b128 v[82:85], v102
	ds_read_b128 v[86:89], v102 offset:1024
	ds_read_b128 v[94:97], v102 offset:2048
	ds_read_b128 v[102:105], v102 offset:3072
	ds_read_b128 v[110:113], v158
	ds_read_b128 v[118:121], v158 offset:1024
	ds_read_b128 v[138:141], v158 offset:2048
	ds_read_b128 v[158:161], v158 offset:3072
	s_add_u32 s0, s30, 0x40000
	s_addc_u32 s1, s31, 0
	s_mov_b32 m0, s38
	v_lshl_add_u64 v[232:233], s[0:1], 0, v[180:181]
	ds_read_b128 v[162:165], v221 offset:32768
	ds_read_b128 v[166:169], v221 offset:33792
	ds_read_b128 v[170:173], v221 offset:34816
	ds_read_b128 v[174:177], v221 offset:35840
	ds_read_b128 v[198:201], v221 offset:36864
	ds_read_b128 v[202:205], v221 offset:37888
	ds_read_b128 v[206:209], v221 offset:38912
	ds_read_b128 v[210:213], v221 offset:39936
	global_load_lds_dwordx4 v[232:233], off
	v_lshl_add_u64 v[232:233], s[0:1], 0, v[184:185]
	s_mov_b32 m0, s39
	s_nop 0
	global_load_lds_dwordx4 v[232:233], off
	s_waitcnt vmcnt(8)
	s_waitcnt lgkmcnt(0)
	s_barrier
	s_setprio 1
	v_mfma_f32_16x16x32_bf16 v[154:157], v[82:85], v[162:165], v[154:157]
	v_mfma_f32_16x16x32_bf16 v[154:157], v[86:89], v[166:169], v[154:157]
	v_mfma_f32_16x16x32_bf16 v[150:153], v[94:97], v[162:165], v[150:153]
	v_mfma_f32_16x16x32_bf16 v[150:153], v[102:105], v[166:169], v[150:153]
	v_mfma_f32_16x16x32_bf16 v[134:137], v[82:85], v[170:173], v[134:137]
	v_mfma_f32_16x16x32_bf16 v[134:137], v[86:89], v[174:177], v[134:137]
	v_mfma_f32_16x16x32_bf16 v[130:133], v[94:97], v[170:173], v[130:133]
	v_mfma_f32_16x16x32_bf16 v[130:133], v[102:105], v[174:177], v[130:133]
	v_mfma_f32_16x16x32_bf16 v[114:117], v[82:85], v[198:201], v[114:117]
	v_mfma_f32_16x16x32_bf16 v[114:117], v[86:89], v[202:205], v[114:117]
	v_mfma_f32_16x16x32_bf16 v[106:109], v[94:97], v[198:201], v[106:109]
	v_mfma_f32_16x16x32_bf16 v[106:109], v[102:105], v[202:205], v[106:109]
	v_mfma_f32_16x16x32_bf16 v[78:81], v[82:85], v[206:209], v[78:81]
	v_mfma_f32_16x16x32_bf16 v[78:81], v[86:89], v[210:213], v[78:81]
	v_mfma_f32_16x16x32_bf16 v[74:77], v[94:97], v[206:209], v[74:77]
	v_mfma_f32_16x16x32_bf16 v[74:77], v[102:105], v[210:213], v[74:77]
	s_setprio 0
	s_setprio 1
	v_mfma_f32_16x16x32_bf16 v[146:149], v[110:113], v[162:165], v[146:149]
	v_mfma_f32_16x16x32_bf16 v[146:149], v[118:121], v[166:169], v[146:149]
	v_mfma_f32_16x16x32_bf16 v[142:145], v[138:141], v[162:165], v[142:145]
	v_mfma_f32_16x16x32_bf16 v[142:145], v[158:161], v[166:169], v[142:145]
	v_mfma_f32_16x16x32_bf16 v[126:129], v[110:113], v[170:173], v[126:129]
	v_mfma_f32_16x16x32_bf16 v[126:129], v[118:121], v[174:177], v[126:129]
	v_mfma_f32_16x16x32_bf16 v[122:125], v[138:141], v[170:173], v[122:125]
	v_mfma_f32_16x16x32_bf16 v[122:125], v[158:161], v[174:177], v[122:125]
	v_mfma_f32_16x16x32_bf16 v[98:101], v[110:113], v[198:201], v[98:101]
	v_mfma_f32_16x16x32_bf16 v[98:101], v[118:121], v[202:205], v[98:101]
	v_mfma_f32_16x16x32_bf16 v[90:93], v[138:141], v[198:201], v[90:93]
	v_mfma_f32_16x16x32_bf16 v[90:93], v[158:161], v[202:205], v[90:93]
	v_mfma_f32_16x16x32_bf16 v[70:73], v[110:113], v[206:209], v[70:73]
	v_mfma_f32_16x16x32_bf16 v[70:73], v[118:121], v[210:213], v[70:73]
	v_mfma_f32_16x16x32_bf16 v[66:69], v[138:141], v[206:209], v[66:69]
	v_mfma_f32_16x16x32_bf16 v[66:69], v[158:161], v[210:213], v[66:69]
	s_setprio 0
	s_barrier
	s_add_i32 s0, s52, s36
	v_lshl_add_u64 v[224:225], v[224:225], 0, s[12:13]
	s_mov_b32 m0, s0
	ds_read_b128 v[162:165], v221 offset:49152
	ds_read_b128 v[166:169], v221 offset:50176
	ds_read_b128 v[170:173], v221 offset:51200
	ds_read_b128 v[174:177], v221 offset:52224
	ds_read_b128 v[198:201], v221 offset:53248
	ds_read_b128 v[202:205], v221 offset:54272
	ds_read_b128 v[206:209], v221 offset:55296
	ds_read_b128 v[210:213], v221 offset:56320
	global_load_lds_dwordx4 v[224:225], off
	s_add_i32 m0, s0, 0x2000
	s_add_u32 s0, s2, 0x40080
	v_lshl_add_u64 v[224:225], v[226:227], 0, s[12:13]
	s_addc_u32 s1, s3, 0
	s_add_i32 s2, s53, s36
	global_load_lds_dwordx4 v[224:225], off
	v_lshl_add_u64 v[224:225], s[0:1], 0, v[182:183]
	s_mov_b32 m0, s2
	s_nop 0
	global_load_lds_dwordx4 v[224:225], off
	v_lshl_add_u64 v[224:225], s[0:1], 0, v[186:187]
	s_add_i32 m0, s2, 0x2000
	s_nop 0
	global_load_lds_dwordx4 v[224:225], off
	v_lshl_add_u64 v[224:225], v[228:229], 0, s[12:13]
	s_mov_b32 m0, s44
	s_nop 0
	global_load_lds_dwordx4 v[224:225], off
	v_lshl_add_u64 v[224:225], v[230:231], 0, s[12:13]
	s_mov_b32 m0, s45
	s_nop 0
	global_load_lds_dwordx4 v[224:225], off
	s_waitcnt vmcnt(8)
	s_waitcnt lgkmcnt(0)
	s_barrier
	s_setprio 1
	v_mfma_f32_16x16x32_bf16 v[62:65], v[82:85], v[162:165], v[62:65]
	v_mfma_f32_16x16x32_bf16 v[62:65], v[86:89], v[166:169], v[62:65]
	v_mfma_f32_16x16x32_bf16 v[58:61], v[94:97], v[162:165], v[58:61]
	v_mfma_f32_16x16x32_bf16 v[58:61], v[102:105], v[166:169], v[58:61]
	v_mfma_f32_16x16x32_bf16 v[46:49], v[82:85], v[170:173], v[46:49]
	v_mfma_f32_16x16x32_bf16 v[46:49], v[86:89], v[174:177], v[46:49]
	v_mfma_f32_16x16x32_bf16 v[42:45], v[94:97], v[170:173], v[42:45]
	v_mfma_f32_16x16x32_bf16 v[42:45], v[102:105], v[174:177], v[42:45]
	v_mfma_f32_16x16x32_bf16 v[30:33], v[82:85], v[198:201], v[30:33]
	v_mfma_f32_16x16x32_bf16 v[30:33], v[86:89], v[202:205], v[30:33]
	v_mfma_f32_16x16x32_bf16 v[26:29], v[94:97], v[198:201], v[26:29]
	v_mfma_f32_16x16x32_bf16 v[26:29], v[102:105], v[202:205], v[26:29]
	v_mfma_f32_16x16x32_bf16 v[14:17], v[82:85], v[206:209], v[14:17]
	v_mfma_f32_16x16x32_bf16 v[14:17], v[86:89], v[210:213], v[14:17]
	v_mfma_f32_16x16x32_bf16 v[10:13], v[94:97], v[206:209], v[10:13]
	v_mfma_f32_16x16x32_bf16 v[10:13], v[102:105], v[210:213], v[10:13]
	s_setprio 0
	s_setprio 1
	v_mfma_f32_16x16x32_bf16 v[54:57], v[110:113], v[162:165], v[54:57]
	s_add_i32 s51, s51, 2
	s_add_u32 s8, s8, 0x100
	s_addc_u32 s9, s9, 0
	s_add_u32 s35, s35, 0x100
	s_addc_u32 s50, s50, 0
	s_cmp_gt_u32 s51, 13
	v_mfma_f32_16x16x32_bf16 v[54:57], v[118:121], v[166:169], v[54:57]
	v_mfma_f32_16x16x32_bf16 v[50:53], v[138:141], v[162:165], v[50:53]
	v_mfma_f32_16x16x32_bf16 v[50:53], v[158:161], v[166:169], v[50:53]
	v_mfma_f32_16x16x32_bf16 v[38:41], v[110:113], v[170:173], v[38:41]
	v_mfma_f32_16x16x32_bf16 v[38:41], v[118:121], v[174:177], v[38:41]
	v_mfma_f32_16x16x32_bf16 v[34:37], v[138:141], v[170:173], v[34:37]
	v_mfma_f32_16x16x32_bf16 v[34:37], v[158:161], v[174:177], v[34:37]
	v_mfma_f32_16x16x32_bf16 v[22:25], v[110:113], v[198:201], v[22:25]
	v_mfma_f32_16x16x32_bf16 v[22:25], v[118:121], v[202:205], v[22:25]
	v_mfma_f32_16x16x32_bf16 v[18:21], v[138:141], v[198:201], v[18:21]
	v_mfma_f32_16x16x32_bf16 v[18:21], v[158:161], v[202:205], v[18:21]
	v_mfma_f32_16x16x32_bf16 v[6:9], v[110:113], v[206:209], v[6:9]
	v_mfma_f32_16x16x32_bf16 v[6:9], v[118:121], v[210:213], v[6:9]
	v_mfma_f32_16x16x32_bf16 v[2:5], v[138:141], v[206:209], v[2:5]
	v_mfma_f32_16x16x32_bf16 v[2:5], v[158:161], v[210:213], v[2:5]
	s_setprio 0
	s_barrier
	s_cbranch_scc0 .LBB0_675
	s_and_b64 vcc, exec, s[14:15]
	s_cbranch_vccz .LBB0_678
	s_barrier

.LBB0_920:
	ds_read_b128 v[130:133], v187
	ds_read_b128 v[134:137], v187 offset:1024
	ds_read_b128 v[138:141], v187 offset:2048
	ds_read_b128 v[142:145], v187 offset:3072
	ds_read_b128 v[146:149], v188
	ds_read_b128 v[150:153], v188 offset:1024
	ds_read_b128 v[170:173], v188 offset:2048
	ds_read_b128 v[174:177], v188 offset:3072
	s_add_u32 s0, s28, 0xfffc0080
	s_addc_u32 s1, s29, -1
	s_cmp_eq_u32 s51, 12
	s_cselect_b32 s31, s11, s1
	s_cselect_b32 s30, s21, s0
	s_cselect_b32 s3, s19, s50
	s_cselect_b32 s2, s48, s49
	v_lshl_add_u64 v[220:221], s[28:29], 0, v[162:163]
	s_add_i32 m0, s27, 0xc000
	ds_read_b128 v[178:181], v189
	ds_read_b128 v[192:195], v189 offset:1024
	ds_read_b128 v[196:199], v189 offset:2048
	ds_read_b128 v[200:203], v189 offset:3072
	ds_read_b128 v[204:207], v189 offset:4096
	ds_read_b128 v[208:211], v189 offset:5120
	ds_read_b128 v[212:215], v189 offset:6144
	ds_read_b128 v[216:219], v189 offset:7168
	global_load_lds_dwordx4 v[220:221], off
	v_lshl_add_u64 v[220:221], s[28:29], 0, v[164:165]
	s_add_i32 m0, s27, 0xe000
	s_nop 0
	global_load_lds_dwordx4 v[220:221], off
	s_waitcnt vmcnt(8)
	s_waitcnt lgkmcnt(0)
	s_barrier
	s_setprio 1
	v_mfma_f32_16x16x32_bf16 v[126:129], v[130:133], v[178:181], v[126:129]
	v_mfma_f32_16x16x32_bf16 v[126:129], v[134:137], v[192:195], v[126:129]
	v_mfma_f32_16x16x32_bf16 v[122:125], v[138:141], v[178:181], v[122:125]
	v_mfma_f32_16x16x32_bf16 v[122:125], v[142:145], v[192:195], v[122:125]
	v_mfma_f32_16x16x32_bf16 v[110:113], v[130:133], v[196:199], v[110:113]
	v_mfma_f32_16x16x32_bf16 v[110:113], v[134:137], v[200:203], v[110:113]
	v_mfma_f32_16x16x32_bf16 v[106:109], v[138:141], v[196:199], v[106:109]
	v_mfma_f32_16x16x32_bf16 v[106:109], v[142:145], v[200:203], v[106:109]
	v_mfma_f32_16x16x32_bf16 v[94:97], v[130:133], v[204:207], v[94:97]
	v_mfma_f32_16x16x32_bf16 v[94:97], v[134:137], v[208:211], v[94:97]
	v_mfma_f32_16x16x32_bf16 v[90:93], v[138:141], v[204:207], v[90:93]
	v_mfma_f32_16x16x32_bf16 v[90:93], v[142:145], v[208:211], v[90:93]
	v_mfma_f32_16x16x32_bf16 v[78:81], v[130:133], v[212:215], v[78:81]
	v_mfma_f32_16x16x32_bf16 v[78:81], v[134:137], v[216:219], v[78:81]
	v_mfma_f32_16x16x32_bf16 v[74:77], v[138:141], v[212:215], v[74:77]
	v_mfma_f32_16x16x32_bf16 v[74:77], v[142:145], v[216:219], v[74:77]
	s_setprio 0
	s_setprio 1
	v_mfma_f32_16x16x32_bf16 v[118:121], v[146:149], v[178:181], v[118:121]
	v_mfma_f32_16x16x32_bf16 v[118:121], v[150:153], v[192:195], v[118:121]
	v_mfma_f32_16x16x32_bf16 v[114:117], v[170:173], v[178:181], v[114:117]
	v_mfma_f32_16x16x32_bf16 v[114:117], v[174:177], v[192:195], v[114:117]
	v_mfma_f32_16x16x32_bf16 v[102:105], v[146:149], v[196:199], v[102:105]
	v_mfma_f32_16x16x32_bf16 v[102:105], v[150:153], v[200:203], v[102:105]
	v_mfma_f32_16x16x32_bf16 v[98:101], v[170:173], v[196:199], v[98:101]
	v_mfma_f32_16x16x32_bf16 v[98:101], v[174:177], v[200:203], v[98:101]
	v_mfma_f32_16x16x32_bf16 v[86:89], v[146:149], v[204:207], v[86:89]
	v_mfma_f32_16x16x32_bf16 v[86:89], v[150:153], v[208:211], v[86:89]
	v_mfma_f32_16x16x32_bf16 v[82:85], v[170:173], v[204:207], v[82:85]
	v_mfma_f32_16x16x32_bf16 v[82:85], v[174:177], v[208:211], v[82:85]
	v_mfma_f32_16x16x32_bf16 v[70:73], v[146:149], v[212:215], v[70:73]
	v_mfma_f32_16x16x32_bf16 v[70:73], v[150:153], v[216:219], v[70:73]
	v_mfma_f32_16x16x32_bf16 v[66:69], v[170:173], v[212:215], v[66:69]
	v_mfma_f32_16x16x32_bf16 v[66:69], v[174:177], v[216:219], v[66:69]
	s_setprio 0
	s_barrier
	s_add_i32 s0, s46, s37
	v_lshl_add_u64 v[220:221], s[2:3], 0, v[156:157]
	s_mov_b32 m0, s0
	ds_read_b128 v[178:181], v189 offset:16384
	ds_read_b128 v[192:195], v189 offset:17408
	ds_read_b128 v[196:199], v189 offset:18432
	ds_read_b128 v[200:203], v189 offset:19456
	ds_read_b128 v[204:207], v189 offset:20480
	ds_read_b128 v[208:211], v189 offset:21504
	ds_read_b128 v[212:215], v189 offset:22528
	ds_read_b128 v[216:219], v189 offset:23552
	global_load_lds_dwordx4 v[220:221], off
	s_add_i32 m0, s0, 0x2000
	s_add_u32 s0, s2, 0x40000
	v_lshl_add_u64 v[222:223], s[2:3], 0, v[160:161]
	s_addc_u32 s1, s3, 0
	s_add_i32 s52, s47, s37
	global_load_lds_dwordx4 v[222:223], off
	v_lshl_add_u64 v[224:225], s[0:1], 0, v[156:157]
	s_mov_b32 m0, s52
	v_lshl_add_u64 v[226:227], s[30:31], 0, v[158:159]
	global_load_lds_dwordx4 v[224:225], off
	v_lshl_add_u64 v[224:225], s[0:1], 0, v[160:161]
	s_add_i32 m0, s52, 0x2000
	s_nop 0
	global_load_lds_dwordx4 v[224:225], off
	v_lshl_add_u64 v[224:225], s[30:31], 0, v[154:155]
	s_mov_b32 m0, s27
	s_nop 0
	global_load_lds_dwordx4 v[224:225], off
	s_mov_b32 m0, s38
	s_nop 0
	global_load_lds_dwordx4 v[226:227], off
	s_waitcnt vmcnt(8)
	s_waitcnt lgkmcnt(0)
	s_barrier
	s_setprio 1
	v_mfma_f32_16x16x32_bf16 v[62:65], v[130:133], v[178:181], v[62:65]
	v_mfma_f32_16x16x32_bf16 v[62:65], v[134:137], v[192:195], v[62:65]
	v_mfma_f32_16x16x32_bf16 v[58:61], v[138:141], v[178:181], v[58:61]
	v_mfma_f32_16x16x32_bf16 v[58:61], v[142:145], v[192:195], v[58:61]
	v_mfma_f32_16x16x32_bf16 v[46:49], v[130:133], v[196:199], v[46:49]
	v_mfma_f32_16x16x32_bf16 v[46:49], v[134:137], v[200:203], v[46:49]
	v_mfma_f32_16x16x32_bf16 v[42:45], v[138:141], v[196:199], v[42:45]
	v_mfma_f32_16x16x32_bf16 v[42:45], v[142:145], v[200:203], v[42:45]
	v_mfma_f32_16x16x32_bf16 v[30:33], v[130:133], v[204:207], v[30:33]
	v_mfma_f32_16x16x32_bf16 v[30:33], v[134:137], v[208:211], v[30:33]
	v_mfma_f32_16x16x32_bf16 v[26:29], v[138:141], v[204:207], v[26:29]
	v_mfma_f32_16x16x32_bf16 v[26:29], v[142:145], v[208:211], v[26:29]
	v_mfma_f32_16x16x32_bf16 v[14:17], v[130:133], v[212:215], v[14:17]
	v_mfma_f32_16x16x32_bf16 v[14:17], v[134:137], v[216:219], v[14:17]
	v_mfma_f32_16x16x32_bf16 v[10:13], v[138:141], v[212:215], v[10:13]
	v_mfma_f32_16x16x32_bf16 v[10:13], v[142:145], v[216:219], v[10:13]
	s_setprio 0
	s_setprio 1
	v_mfma_f32_16x16x32_bf16 v[54:57], v[146:149], v[178:181], v[54:57]
	v_mfma_f32_16x16x32_bf16 v[54:57], v[150:153], v[192:195], v[54:57]
	v_mfma_f32_16x16x32_bf16 v[50:53], v[170:173], v[178:181], v[50:53]
	v_mfma_f32_16x16x32_bf16 v[50:53], v[174:177], v[192:195], v[50:53]
	v_mfma_f32_16x16x32_bf16 v[38:41], v[146:149], v[196:199], v[38:41]
	v_mfma_f32_16x16x32_bf16 v[38:41], v[150:153], v[200:203], v[38:41]
	v_mfma_f32_16x16x32_bf16 v[34:37], v[170:173], v[196:199], v[34:37]
	v_mfma_f32_16x16x32_bf16 v[34:37], v[174:177], v[200:203], v[34:37]
	v_mfma_f32_16x16x32_bf16 v[22:25], v[146:149], v[204:207], v[22:25]
	v_mfma_f32_16x16x32_bf16 v[22:25], v[150:153], v[208:211], v[22:25]
	v_mfma_f32_16x16x32_bf16 v[18:21], v[170:173], v[204:207], v[18:21]
	v_mfma_f32_16x16x32_bf16 v[18:21], v[174:177], v[208:211], v[18:21]
	v_mfma_f32_16x16x32_bf16 v[6:9], v[146:149], v[212:215], v[6:9]
	v_mfma_f32_16x16x32_bf16 v[6:9], v[150:153], v[216:219], v[6:9]
	v_mfma_f32_16x16x32_bf16 v[2:5], v[170:173], v[212:215], v[2:5]
	v_mfma_f32_16x16x32_bf16 v[2:5], v[174:177], v[216:219], v[2:5]
	s_setprio 0
	s_barrier
	s_add_i32 s52, 0, 0x18000
	s_add_i32 s53, 0, 0x1c000
	v_add_u32_e32 v142, s52, v183
	v_add_u32_e32 v174, s53, v183
	ds_read_b128 v[130:133], v142
	ds_read_b128 v[134:137], v142 offset:1024
	ds_read_b128 v[138:141], v142 offset:2048
	ds_read_b128 v[142:145], v142 offset:3072
	ds_read_b128 v[146:149], v174
	ds_read_b128 v[150:153], v174 offset:1024
	ds_read_b128 v[170:173], v174 offset:2048
	ds_read_b128 v[174:177], v174 offset:3072
	s_add_u32 s0, s30, 0x40000
	s_addc_u32 s1, s31, 0
	s_mov_b32 m0, s39
	v_lshl_add_u64 v[228:229], s[0:1], 0, v[154:155]
	ds_read_b128 v[178:181], v189 offset:32768
	ds_read_b128 v[192:195], v189 offset:33792
	ds_read_b128 v[196:199], v189 offset:34816
	ds_read_b128 v[200:203], v189 offset:35840
	ds_read_b128 v[204:207], v189 offset:36864
	ds_read_b128 v[208:211], v189 offset:37888
	ds_read_b128 v[212:215], v189 offset:38912
	ds_read_b128 v[216:219], v189 offset:39936
	global_load_lds_dwordx4 v[228:229], off
	v_lshl_add_u64 v[228:229], s[0:1], 0, v[158:159]
	s_mov_b32 m0, s40
	s_nop 0
	global_load_lds_dwordx4 v[228:229], off
	s_waitcnt vmcnt(8)
	s_waitcnt lgkmcnt(0)
	s_barrier
	s_setprio 1
	v_mfma_f32_16x16x32_bf16 v[126:129], v[130:133], v[178:181], v[126:129]
	v_mfma_f32_16x16x32_bf16 v[126:129], v[134:137], v[192:195], v[126:129]
	v_mfma_f32_16x16x32_bf16 v[122:125], v[138:141], v[178:181], v[122:125]
	v_mfma_f32_16x16x32_bf16 v[122:125], v[142:145], v[192:195], v[122:125]
	v_mfma_f32_16x16x32_bf16 v[110:113], v[130:133], v[196:199], v[110:113]
	v_mfma_f32_16x16x32_bf16 v[110:113], v[134:137], v[200:203], v[110:113]
	v_mfma_f32_16x16x32_bf16 v[106:109], v[138:141], v[196:199], v[106:109]
	v_mfma_f32_16x16x32_bf16 v[106:109], v[142:145], v[200:203], v[106:109]
	v_mfma_f32_16x16x32_bf16 v[94:97], v[130:133], v[204:207], v[94:97]
	v_mfma_f32_16x16x32_bf16 v[94:97], v[134:137], v[208:211], v[94:97]
	v_mfma_f32_16x16x32_bf16 v[90:93], v[138:141], v[204:207], v[90:93]
	v_mfma_f32_16x16x32_bf16 v[90:93], v[142:145], v[208:211], v[90:93]
	v_mfma_f32_16x16x32_bf16 v[78:81], v[130:133], v[212:215], v[78:81]
	v_mfma_f32_16x16x32_bf16 v[78:81], v[134:137], v[216:219], v[78:81]
	v_mfma_f32_16x16x32_bf16 v[74:77], v[138:141], v[212:215], v[74:77]
	v_mfma_f32_16x16x32_bf16 v[74:77], v[142:145], v[216:219], v[74:77]
	s_setprio 0
	s_setprio 1
	v_mfma_f32_16x16x32_bf16 v[118:121], v[146:149], v[178:181], v[118:121]
	v_mfma_f32_16x16x32_bf16 v[118:121], v[150:153], v[192:195], v[118:121]
	v_mfma_f32_16x16x32_bf16 v[114:117], v[170:173], v[178:181], v[114:117]
	v_mfma_f32_16x16x32_bf16 v[114:117], v[174:177], v[192:195], v[114:117]
	v_mfma_f32_16x16x32_bf16 v[102:105], v[146:149], v[196:199], v[102:105]
	v_mfma_f32_16x16x32_bf16 v[102:105], v[150:153], v[200:203], v[102:105]
	v_mfma_f32_16x16x32_bf16 v[98:101], v[170:173], v[196:199], v[98:101]
	v_mfma_f32_16x16x32_bf16 v[98:101], v[174:177], v[200:203], v[98:101]
	v_mfma_f32_16x16x32_bf16 v[86:89], v[146:149], v[204:207], v[86:89]
	v_mfma_f32_16x16x32_bf16 v[86:89], v[150:153], v[208:211], v[86:89]
	v_mfma_f32_16x16x32_bf16 v[82:85], v[170:173], v[204:207], v[82:85]
	v_mfma_f32_16x16x32_bf16 v[82:85], v[174:177], v[208:211], v[82:85]
	v_mfma_f32_16x16x32_bf16 v[70:73], v[146:149], v[212:215], v[70:73]
	v_mfma_f32_16x16x32_bf16 v[70:73], v[150:153], v[216:219], v[70:73]
	v_mfma_f32_16x16x32_bf16 v[66:69], v[170:173], v[212:215], v[66:69]
	v_mfma_f32_16x16x32_bf16 v[66:69], v[174:177], v[216:219], v[66:69]
	s_setprio 0
	s_barrier
	s_add_i32 s0, s52, s37
	v_lshl_add_u64 v[220:221], v[220:221], 0, s[14:15]
	s_mov_b32 m0, s0
	ds_read_b128 v[178:181], v189 offset:49152
	ds_read_b128 v[192:195], v189 offset:50176
	ds_read_b128 v[196:199], v189 offset:51200
	ds_read_b128 v[200:203], v189 offset:52224
	ds_read_b128 v[204:207], v189 offset:53248
	ds_read_b128 v[208:211], v189 offset:54272
	ds_read_b128 v[212:215], v189 offset:55296
	ds_read_b128 v[216:219], v189 offset:56320
	global_load_lds_dwordx4 v[220:221], off
	s_add_i32 m0, s0, 0x2000
	s_add_u32 s0, s2, 0x40080
	v_lshl_add_u64 v[220:221], v[222:223], 0, s[14:15]
	s_addc_u32 s1, s3, 0
	s_add_i32 s2, s53, s37
	global_load_lds_dwordx4 v[220:221], off
	v_lshl_add_u64 v[220:221], s[0:1], 0, v[156:157]
	s_mov_b32 m0, s2
	s_nop 0
	global_load_lds_dwordx4 v[220:221], off
	v_lshl_add_u64 v[220:221], s[0:1], 0, v[160:161]
	s_add_i32 m0, s2, 0x2000
	s_nop 0
	global_load_lds_dwordx4 v[220:221], off
	v_lshl_add_u64 v[220:221], v[224:225], 0, s[14:15]
	s_mov_b32 m0, s42
	s_nop 0
	global_load_lds_dwordx4 v[220:221], off
	v_lshl_add_u64 v[220:221], v[226:227], 0, s[14:15]
	s_mov_b32 m0, s43
	s_nop 0
	global_load_lds_dwordx4 v[220:221], off
	s_waitcnt vmcnt(8)
	s_waitcnt lgkmcnt(0)
	s_barrier
	s_setprio 1
	v_mfma_f32_16x16x32_bf16 v[62:65], v[130:133], v[178:181], v[62:65]
	v_mfma_f32_16x16x32_bf16 v[62:65], v[134:137], v[192:195], v[62:65]
	v_mfma_f32_16x16x32_bf16 v[58:61], v[138:141], v[178:181], v[58:61]
	v_mfma_f32_16x16x32_bf16 v[58:61], v[142:145], v[192:195], v[58:61]
	v_mfma_f32_16x16x32_bf16 v[46:49], v[130:133], v[196:199], v[46:49]
	v_mfma_f32_16x16x32_bf16 v[46:49], v[134:137], v[200:203], v[46:49]
	v_mfma_f32_16x16x32_bf16 v[42:45], v[138:141], v[196:199], v[42:45]
	v_mfma_f32_16x16x32_bf16 v[42:45], v[142:145], v[200:203], v[42:45]
	v_mfma_f32_16x16x32_bf16 v[30:33], v[130:133], v[204:207], v[30:33]
	v_mfma_f32_16x16x32_bf16 v[30:33], v[134:137], v[208:211], v[30:33]
	v_mfma_f32_16x16x32_bf16 v[26:29], v[138:141], v[204:207], v[26:29]
	v_mfma_f32_16x16x32_bf16 v[26:29], v[142:145], v[208:211], v[26:29]
	v_mfma_f32_16x16x32_bf16 v[14:17], v[130:133], v[212:215], v[14:17]
	v_mfma_f32_16x16x32_bf16 v[14:17], v[134:137], v[216:219], v[14:17]
	v_mfma_f32_16x16x32_bf16 v[10:13], v[138:141], v[212:215], v[10:13]
	v_mfma_f32_16x16x32_bf16 v[10:13], v[142:145], v[216:219], v[10:13]
	s_setprio 0
	s_setprio 1
	v_mfma_f32_16x16x32_bf16 v[54:57], v[146:149], v[178:181], v[54:57]
	s_add_i32 s51, s51, 2
	s_add_u32 s28, s28, 0x100
	s_addc_u32 s29, s29, 0
	s_add_u32 s49, s49, 0x100
	s_addc_u32 s50, s50, 0
	s_cmp_gt_u32 s51, 13
	v_mfma_f32_16x16x32_bf16 v[54:57], v[150:153], v[192:195], v[54:57]
	v_mfma_f32_16x16x32_bf16 v[50:53], v[170:173], v[178:181], v[50:53]
	v_mfma_f32_16x16x32_bf16 v[50:53], v[174:177], v[192:195], v[50:53]
	v_mfma_f32_16x16x32_bf16 v[38:41], v[146:149], v[196:199], v[38:41]
	v_mfma_f32_16x16x32_bf16 v[38:41], v[150:153], v[200:203], v[38:41]
	v_mfma_f32_16x16x32_bf16 v[34:37], v[170:173], v[196:199], v[34:37]
	v_mfma_f32_16x16x32_bf16 v[34:37], v[174:177], v[200:203], v[34:37]
	v_mfma_f32_16x16x32_bf16 v[22:25], v[146:149], v[204:207], v[22:25]
	v_mfma_f32_16x16x32_bf16 v[22:25], v[150:153], v[208:211], v[22:25]
	v_mfma_f32_16x16x32_bf16 v[18:21], v[170:173], v[204:207], v[18:21]
	v_mfma_f32_16x16x32_bf16 v[18:21], v[174:177], v[208:211], v[18:21]
	v_mfma_f32_16x16x32_bf16 v[6:9], v[146:149], v[212:215], v[6:9]
	v_mfma_f32_16x16x32_bf16 v[6:9], v[150:153], v[216:219], v[6:9]
	v_mfma_f32_16x16x32_bf16 v[2:5], v[170:173], v[212:215], v[2:5]
	v_mfma_f32_16x16x32_bf16 v[2:5], v[174:177], v[216:219], v[2:5]
	s_setprio 0
	s_barrier
	s_cbranch_scc0 .LBB0_920
	s_and_b64 vcc, exec, s[16:17]
	s_cbranch_vccz .LBB0_923
	s_barrier

.LBB0_1009:
	ds_read_b128 v[148:151], v167
	ds_read_b128 v[152:155], v167 offset:1024
	ds_read_b128 v[156:159], v167 offset:2048
	ds_read_b128 v[160:163], v167 offset:3072
	ds_read_b128 v[172:175], v168
	ds_read_b128 v[176:179], v168 offset:1024
	ds_read_b128 v[180:183], v168 offset:2048
	ds_read_b128 v[184:187], v168 offset:3072
	s_add_u32 s0, s28, 0xfffc0080
	s_addc_u32 s1, s29, -1
	s_cmp_eq_u32 s53, 12
	s_cselect_b32 s31, s21, s1
	s_cselect_b32 s30, s49, s0
	s_cselect_b32 s3, s19, s52
	s_cselect_b32 s2, s50, s51
	v_lshl_add_u64 v[220:221], s[28:29], 0, v[140:141]
	s_add_i32 m0, s27, 0xc000
	ds_read_b128 v[188:191], v169
	ds_read_b128 v[192:195], v169 offset:1024
	ds_read_b128 v[196:199], v169 offset:2048
	ds_read_b128 v[200:203], v169 offset:3072
	ds_read_b128 v[204:207], v169 offset:4096
	ds_read_b128 v[208:211], v169 offset:5120
	ds_read_b128 v[212:215], v169 offset:6144
	ds_read_b128 v[216:219], v169 offset:7168
	global_load_lds_dwordx4 v[220:221], off
	v_lshl_add_u64 v[220:221], s[28:29], 0, v[142:143]
	s_add_i32 m0, s27, 0xe000
	s_nop 0
	global_load_lds_dwordx4 v[220:221], off
	s_waitcnt vmcnt(8)
	s_waitcnt lgkmcnt(0)
	s_barrier
	s_setprio 1
	v_mfma_f32_16x16x32_bf16 v[126:129], v[148:151], v[188:191], v[126:129]
	v_mfma_f32_16x16x32_bf16 v[126:129], v[152:155], v[192:195], v[126:129]
	v_mfma_f32_16x16x32_bf16 v[118:121], v[156:159], v[188:191], v[118:121]
	v_mfma_f32_16x16x32_bf16 v[118:121], v[160:163], v[192:195], v[118:121]
	v_mfma_f32_16x16x32_bf16 v[110:113], v[148:151], v[196:199], v[110:113]
	v_mfma_f32_16x16x32_bf16 v[110:113], v[152:155], v[200:203], v[110:113]
	v_mfma_f32_16x16x32_bf16 v[102:105], v[156:159], v[196:199], v[102:105]
	v_mfma_f32_16x16x32_bf16 v[102:105], v[160:163], v[200:203], v[102:105]
	v_mfma_f32_16x16x32_bf16 v[94:97], v[148:151], v[204:207], v[94:97]
	v_mfma_f32_16x16x32_bf16 v[94:97], v[152:155], v[208:211], v[94:97]
	v_mfma_f32_16x16x32_bf16 v[86:89], v[156:159], v[204:207], v[86:89]
	v_mfma_f32_16x16x32_bf16 v[86:89], v[160:163], v[208:211], v[86:89]
	v_mfma_f32_16x16x32_bf16 v[78:81], v[148:151], v[212:215], v[78:81]
	v_mfma_f32_16x16x32_bf16 v[78:81], v[152:155], v[216:219], v[78:81]
	v_mfma_f32_16x16x32_bf16 v[70:73], v[156:159], v[212:215], v[70:73]
	v_mfma_f32_16x16x32_bf16 v[70:73], v[160:163], v[216:219], v[70:73]
	s_setprio 0
	s_setprio 1
	v_mfma_f32_16x16x32_bf16 v[122:125], v[172:175], v[188:191], v[122:125]
	v_mfma_f32_16x16x32_bf16 v[122:125], v[176:179], v[192:195], v[122:125]
	v_mfma_f32_16x16x32_bf16 v[114:117], v[180:183], v[188:191], v[114:117]
	v_mfma_f32_16x16x32_bf16 v[114:117], v[184:187], v[192:195], v[114:117]
	v_mfma_f32_16x16x32_bf16 v[106:109], v[172:175], v[196:199], v[106:109]
	v_mfma_f32_16x16x32_bf16 v[106:109], v[176:179], v[200:203], v[106:109]
	v_mfma_f32_16x16x32_bf16 v[98:101], v[180:183], v[196:199], v[98:101]
	v_mfma_f32_16x16x32_bf16 v[98:101], v[184:187], v[200:203], v[98:101]
	v_mfma_f32_16x16x32_bf16 v[90:93], v[172:175], v[204:207], v[90:93]
	v_mfma_f32_16x16x32_bf16 v[90:93], v[176:179], v[208:211], v[90:93]
	v_mfma_f32_16x16x32_bf16 v[82:85], v[180:183], v[204:207], v[82:85]
	v_mfma_f32_16x16x32_bf16 v[82:85], v[184:187], v[208:211], v[82:85]
	v_mfma_f32_16x16x32_bf16 v[74:77], v[172:175], v[212:215], v[74:77]
	v_mfma_f32_16x16x32_bf16 v[74:77], v[176:179], v[216:219], v[74:77]
	v_mfma_f32_16x16x32_bf16 v[66:69], v[180:183], v[212:215], v[66:69]
	v_mfma_f32_16x16x32_bf16 v[66:69], v[184:187], v[216:219], v[66:69]
	s_setprio 0
	s_barrier
	s_add_i32 s0, s44, s35
	v_lshl_add_u64 v[220:221], s[2:3], 0, v[134:135]
	s_mov_b32 m0, s0
	ds_read_b128 v[188:191], v169 offset:16384
	ds_read_b128 v[192:195], v169 offset:17408
	ds_read_b128 v[196:199], v169 offset:18432
	ds_read_b128 v[200:203], v169 offset:19456
	ds_read_b128 v[204:207], v169 offset:20480
	ds_read_b128 v[208:211], v169 offset:21504
	ds_read_b128 v[212:215], v169 offset:22528
	ds_read_b128 v[216:219], v169 offset:23552
	global_load_lds_dwordx4 v[220:221], off
	s_add_i32 m0, s0, 0x2000
	s_add_u32 s0, s2, 0x40000
	v_lshl_add_u64 v[222:223], s[2:3], 0, v[130:131]
	s_addc_u32 s1, s3, 0
	s_add_i32 s54, s45, s35
	global_load_lds_dwordx4 v[222:223], off
	v_lshl_add_u64 v[224:225], s[0:1], 0, v[134:135]
	s_mov_b32 m0, s54
	v_lshl_add_u64 v[226:227], s[30:31], 0, v[132:133]
	global_load_lds_dwordx4 v[224:225], off
	v_lshl_add_u64 v[224:225], s[0:1], 0, v[130:131]
	s_add_i32 m0, s54, 0x2000
	s_nop 0
	global_load_lds_dwordx4 v[224:225], off
	v_lshl_add_u64 v[224:225], s[30:31], 0, v[136:137]
	s_mov_b32 m0, s27
	s_nop 0
	global_load_lds_dwordx4 v[224:225], off
	s_mov_b32 m0, s38
	s_nop 0
	global_load_lds_dwordx4 v[226:227], off
	s_waitcnt vmcnt(8)
	s_waitcnt lgkmcnt(0)
	s_barrier
	s_setprio 1
	v_mfma_f32_16x16x32_bf16 v[62:65], v[148:151], v[188:191], v[62:65]
	v_mfma_f32_16x16x32_bf16 v[62:65], v[152:155], v[192:195], v[62:65]
	v_mfma_f32_16x16x32_bf16 v[54:57], v[156:159], v[188:191], v[54:57]
	v_mfma_f32_16x16x32_bf16 v[54:57], v[160:163], v[192:195], v[54:57]
	v_mfma_f32_16x16x32_bf16 v[46:49], v[148:151], v[196:199], v[46:49]
	v_mfma_f32_16x16x32_bf16 v[46:49], v[152:155], v[200:203], v[46:49]
	v_mfma_f32_16x16x32_bf16 v[38:41], v[156:159], v[196:199], v[38:41]
	v_mfma_f32_16x16x32_bf16 v[38:41], v[160:163], v[200:203], v[38:41]
	v_mfma_f32_16x16x32_bf16 v[30:33], v[148:151], v[204:207], v[30:33]
	v_mfma_f32_16x16x32_bf16 v[30:33], v[152:155], v[208:211], v[30:33]
	v_mfma_f32_16x16x32_bf16 v[22:25], v[156:159], v[204:207], v[22:25]
	v_mfma_f32_16x16x32_bf16 v[22:25], v[160:163], v[208:211], v[22:25]
	v_mfma_f32_16x16x32_bf16 v[14:17], v[148:151], v[212:215], v[14:17]
	v_mfma_f32_16x16x32_bf16 v[14:17], v[152:155], v[216:219], v[14:17]
	v_mfma_f32_16x16x32_bf16 v[6:9], v[156:159], v[212:215], v[6:9]
	v_mfma_f32_16x16x32_bf16 v[6:9], v[160:163], v[216:219], v[6:9]
	s_setprio 0
	s_setprio 1
	v_mfma_f32_16x16x32_bf16 v[58:61], v[172:175], v[188:191], v[58:61]
	v_mfma_f32_16x16x32_bf16 v[58:61], v[176:179], v[192:195], v[58:61]
	v_mfma_f32_16x16x32_bf16 v[50:53], v[180:183], v[188:191], v[50:53]
	v_mfma_f32_16x16x32_bf16 v[50:53], v[184:187], v[192:195], v[50:53]
	v_mfma_f32_16x16x32_bf16 v[42:45], v[172:175], v[196:199], v[42:45]
	v_mfma_f32_16x16x32_bf16 v[42:45], v[176:179], v[200:203], v[42:45]
	v_mfma_f32_16x16x32_bf16 v[34:37], v[180:183], v[196:199], v[34:37]
	v_mfma_f32_16x16x32_bf16 v[34:37], v[184:187], v[200:203], v[34:37]
	v_mfma_f32_16x16x32_bf16 v[26:29], v[172:175], v[204:207], v[26:29]
	v_mfma_f32_16x16x32_bf16 v[26:29], v[176:179], v[208:211], v[26:29]
	v_mfma_f32_16x16x32_bf16 v[18:21], v[180:183], v[204:207], v[18:21]
	v_mfma_f32_16x16x32_bf16 v[18:21], v[184:187], v[208:211], v[18:21]
	v_mfma_f32_16x16x32_bf16 v[10:13], v[172:175], v[212:215], v[10:13]
	v_mfma_f32_16x16x32_bf16 v[10:13], v[176:179], v[216:219], v[10:13]
	v_mfma_f32_16x16x32_bf16 v[2:5], v[180:183], v[212:215], v[2:5]
	v_mfma_f32_16x16x32_bf16 v[2:5], v[184:187], v[216:219], v[2:5]
	s_setprio 0
	s_barrier
	s_add_i32 s54, 0, 0x18000
	s_add_i32 s55, 0, 0x1c000
	v_add_u32_e32 v160, s54, v166
	v_add_u32_e32 v171, s55, v166
	ds_read_b128 v[148:151], v160
	ds_read_b128 v[152:155], v160 offset:1024
	ds_read_b128 v[156:159], v160 offset:2048
	ds_read_b128 v[160:163], v160 offset:3072
	ds_read_b128 v[172:175], v171
	ds_read_b128 v[176:179], v171 offset:1024
	ds_read_b128 v[180:183], v171 offset:2048
	ds_read_b128 v[184:187], v171 offset:3072
	s_add_u32 s0, s30, 0x40000
	s_addc_u32 s1, s31, 0
	s_mov_b32 m0, s39
	v_lshl_add_u64 v[228:229], s[0:1], 0, v[136:137]
	ds_read_b128 v[188:191], v169 offset:32768
	ds_read_b128 v[192:195], v169 offset:33792
	ds_read_b128 v[196:199], v169 offset:34816
	ds_read_b128 v[200:203], v169 offset:35840
	ds_read_b128 v[204:207], v169 offset:36864
	ds_read_b128 v[208:211], v169 offset:37888
	ds_read_b128 v[212:215], v169 offset:38912
	ds_read_b128 v[216:219], v169 offset:39936
	global_load_lds_dwordx4 v[228:229], off
	v_lshl_add_u64 v[228:229], s[0:1], 0, v[132:133]
	s_mov_b32 m0, s40
	s_nop 0
	global_load_lds_dwordx4 v[228:229], off
	s_waitcnt vmcnt(8)
	s_waitcnt lgkmcnt(0)
	s_barrier
	s_setprio 1
	v_mfma_f32_16x16x32_bf16 v[126:129], v[148:151], v[188:191], v[126:129]
	v_mfma_f32_16x16x32_bf16 v[126:129], v[152:155], v[192:195], v[126:129]
	v_mfma_f32_16x16x32_bf16 v[118:121], v[156:159], v[188:191], v[118:121]
	v_mfma_f32_16x16x32_bf16 v[118:121], v[160:163], v[192:195], v[118:121]
	v_mfma_f32_16x16x32_bf16 v[110:113], v[148:151], v[196:199], v[110:113]
	v_mfma_f32_16x16x32_bf16 v[110:113], v[152:155], v[200:203], v[110:113]
	v_mfma_f32_16x16x32_bf16 v[102:105], v[156:159], v[196:199], v[102:105]
	v_mfma_f32_16x16x32_bf16 v[102:105], v[160:163], v[200:203], v[102:105]
	v_mfma_f32_16x16x32_bf16 v[94:97], v[148:151], v[204:207], v[94:97]
	v_mfma_f32_16x16x32_bf16 v[94:97], v[152:155], v[208:211], v[94:97]
	v_mfma_f32_16x16x32_bf16 v[86:89], v[156:159], v[204:207], v[86:89]
	v_mfma_f32_16x16x32_bf16 v[86:89], v[160:163], v[208:211], v[86:89]
	v_mfma_f32_16x16x32_bf16 v[78:81], v[148:151], v[212:215], v[78:81]
	v_mfma_f32_16x16x32_bf16 v[78:81], v[152:155], v[216:219], v[78:81]
	v_mfma_f32_16x16x32_bf16 v[70:73], v[156:159], v[212:215], v[70:73]
	v_mfma_f32_16x16x32_bf16 v[70:73], v[160:163], v[216:219], v[70:73]
	s_setprio 0
	s_setprio 1
	v_mfma_f32_16x16x32_bf16 v[122:125], v[172:175], v[188:191], v[122:125]
	v_mfma_f32_16x16x32_bf16 v[122:125], v[176:179], v[192:195], v[122:125]
	v_mfma_f32_16x16x32_bf16 v[114:117], v[180:183], v[188:191], v[114:117]
	v_mfma_f32_16x16x32_bf16 v[114:117], v[184:187], v[192:195], v[114:117]
	v_mfma_f32_16x16x32_bf16 v[106:109], v[172:175], v[196:199], v[106:109]
	v_mfma_f32_16x16x32_bf16 v[106:109], v[176:179], v[200:203], v[106:109]
	v_mfma_f32_16x16x32_bf16 v[98:101], v[180:183], v[196:199], v[98:101]
	v_mfma_f32_16x16x32_bf16 v[98:101], v[184:187], v[200:203], v[98:101]
	v_mfma_f32_16x16x32_bf16 v[90:93], v[172:175], v[204:207], v[90:93]
	v_mfma_f32_16x16x32_bf16 v[90:93], v[176:179], v[208:211], v[90:93]
	v_mfma_f32_16x16x32_bf16 v[82:85], v[180:183], v[204:207], v[82:85]
	v_mfma_f32_16x16x32_bf16 v[82:85], v[184:187], v[208:211], v[82:85]
	v_mfma_f32_16x16x32_bf16 v[74:77], v[172:175], v[212:215], v[74:77]
	v_mfma_f32_16x16x32_bf16 v[74:77], v[176:179], v[216:219], v[74:77]
	v_mfma_f32_16x16x32_bf16 v[66:69], v[180:183], v[212:215], v[66:69]
	v_mfma_f32_16x16x32_bf16 v[66:69], v[184:187], v[216:219], v[66:69]
	s_setprio 0
	s_barrier
	s_add_i32 s0, s54, s35
	v_lshl_add_u64 v[220:221], v[220:221], 0, s[14:15]
	s_mov_b32 m0, s0
	ds_read_b128 v[188:191], v169 offset:49152
	ds_read_b128 v[192:195], v169 offset:50176
	ds_read_b128 v[196:199], v169 offset:51200
	ds_read_b128 v[200:203], v169 offset:52224
	ds_read_b128 v[204:207], v169 offset:53248
	ds_read_b128 v[208:211], v169 offset:54272
	ds_read_b128 v[212:215], v169 offset:55296
	ds_read_b128 v[216:219], v169 offset:56320
	global_load_lds_dwordx4 v[220:221], off
	s_add_i32 m0, s0, 0x2000
	s_add_u32 s0, s2, 0x40080
	v_lshl_add_u64 v[220:221], v[222:223], 0, s[14:15]
	s_addc_u32 s1, s3, 0
	s_add_i32 s2, s55, s35
	global_load_lds_dwordx4 v[220:221], off
	v_lshl_add_u64 v[220:221], s[0:1], 0, v[134:135]
	s_mov_b32 m0, s2
	s_nop 0
	global_load_lds_dwordx4 v[220:221], off
	v_lshl_add_u64 v[220:221], s[0:1], 0, v[130:131]
	s_add_i32 m0, s2, 0x2000
	s_nop 0
	global_load_lds_dwordx4 v[220:221], off
	v_lshl_add_u64 v[220:221], v[224:225], 0, s[14:15]
	s_mov_b32 m0, s41
	s_nop 0
	global_load_lds_dwordx4 v[220:221], off
	v_lshl_add_u64 v[220:221], v[226:227], 0, s[14:15]
	s_mov_b32 m0, s42
	s_nop 0
	global_load_lds_dwordx4 v[220:221], off
	s_waitcnt vmcnt(8)
	s_waitcnt lgkmcnt(0)
	s_barrier
	s_setprio 1
	v_mfma_f32_16x16x32_bf16 v[62:65], v[148:151], v[188:191], v[62:65]
	v_mfma_f32_16x16x32_bf16 v[62:65], v[152:155], v[192:195], v[62:65]
	v_mfma_f32_16x16x32_bf16 v[54:57], v[156:159], v[188:191], v[54:57]
	v_mfma_f32_16x16x32_bf16 v[54:57], v[160:163], v[192:195], v[54:57]
	v_mfma_f32_16x16x32_bf16 v[46:49], v[148:151], v[196:199], v[46:49]
	v_mfma_f32_16x16x32_bf16 v[46:49], v[152:155], v[200:203], v[46:49]
	v_mfma_f32_16x16x32_bf16 v[38:41], v[156:159], v[196:199], v[38:41]
	v_mfma_f32_16x16x32_bf16 v[38:41], v[160:163], v[200:203], v[38:41]
	v_mfma_f32_16x16x32_bf16 v[30:33], v[148:151], v[204:207], v[30:33]
	v_mfma_f32_16x16x32_bf16 v[30:33], v[152:155], v[208:211], v[30:33]
	v_mfma_f32_16x16x32_bf16 v[22:25], v[156:159], v[204:207], v[22:25]
	v_mfma_f32_16x16x32_bf16 v[22:25], v[160:163], v[208:211], v[22:25]
	v_mfma_f32_16x16x32_bf16 v[14:17], v[148:151], v[212:215], v[14:17]
	v_mfma_f32_16x16x32_bf16 v[14:17], v[152:155], v[216:219], v[14:17]
	v_mfma_f32_16x16x32_bf16 v[6:9], v[156:159], v[212:215], v[6:9]
	v_mfma_f32_16x16x32_bf16 v[6:9], v[160:163], v[216:219], v[6:9]
	s_setprio 0
	s_setprio 1
	v_mfma_f32_16x16x32_bf16 v[58:61], v[172:175], v[188:191], v[58:61]
	s_add_i32 s53, s53, 2
	s_add_u32 s28, s28, 0x100
	s_addc_u32 s29, s29, 0
	s_add_u32 s51, s51, 0x100
	s_addc_u32 s52, s52, 0
	s_cmp_gt_u32 s53, 13
	v_mfma_f32_16x16x32_bf16 v[58:61], v[176:179], v[192:195], v[58:61]
	v_mfma_f32_16x16x32_bf16 v[50:53], v[180:183], v[188:191], v[50:53]
	v_mfma_f32_16x16x32_bf16 v[50:53], v[184:187], v[192:195], v[50:53]
	v_mfma_f32_16x16x32_bf16 v[42:45], v[172:175], v[196:199], v[42:45]
	v_mfma_f32_16x16x32_bf16 v[42:45], v[176:179], v[200:203], v[42:45]
	v_mfma_f32_16x16x32_bf16 v[34:37], v[180:183], v[196:199], v[34:37]
	v_mfma_f32_16x16x32_bf16 v[34:37], v[184:187], v[200:203], v[34:37]
	v_mfma_f32_16x16x32_bf16 v[26:29], v[172:175], v[204:207], v[26:29]
	v_mfma_f32_16x16x32_bf16 v[26:29], v[176:179], v[208:211], v[26:29]
	v_mfma_f32_16x16x32_bf16 v[18:21], v[180:183], v[204:207], v[18:21]
	v_mfma_f32_16x16x32_bf16 v[18:21], v[184:187], v[208:211], v[18:21]
	v_mfma_f32_16x16x32_bf16 v[10:13], v[172:175], v[212:215], v[10:13]
	v_mfma_f32_16x16x32_bf16 v[10:13], v[176:179], v[216:219], v[10:13]
	v_mfma_f32_16x16x32_bf16 v[2:5], v[180:183], v[212:215], v[2:5]
	v_mfma_f32_16x16x32_bf16 v[2:5], v[184:187], v[216:219], v[2:5]
	s_setprio 0
	s_barrier
	s_cbranch_scc0 .LBB0_1009
	s_and_b64 vcc, exec, s[16:17]
	s_cbranch_vccz .LBB0_1012
	s_barrier

.LBB0_1123:
	ds_read_b128 v[130:133], v187
	ds_read_b128 v[134:137], v187 offset:1024
	ds_read_b128 v[138:141], v187 offset:2048
	ds_read_b128 v[142:145], v187 offset:3072
	ds_read_b128 v[146:149], v188
	ds_read_b128 v[150:153], v188 offset:1024
	ds_read_b128 v[170:173], v188 offset:2048
	ds_read_b128 v[174:177], v188 offset:3072
	s_add_u32 s0, s24, 0xfff50080
	s_addc_u32 s1, s25, -1
	s_cmp_eq_u32 s49, 40
	s_cselect_b32 s27, s9, s1
	s_cselect_b32 s26, s8, s0
	s_cselect_b32 s3, s23, s48
	s_cselect_b32 s2, s22, s47
	v_lshl_add_u64 v[220:221], s[24:25], 0, v[162:163]
	s_add_i32 m0, s34, 0xc000
	ds_read_b128 v[178:181], v189
	ds_read_b128 v[192:195], v189 offset:1024
	ds_read_b128 v[196:199], v189 offset:2048
	ds_read_b128 v[200:203], v189 offset:3072
	ds_read_b128 v[204:207], v189 offset:4096
	ds_read_b128 v[208:211], v189 offset:5120
	ds_read_b128 v[212:215], v189 offset:6144
	ds_read_b128 v[216:219], v189 offset:7168
	global_load_lds_dwordx4 v[220:221], off
	v_lshl_add_u64 v[220:221], s[24:25], 0, v[164:165]
	s_add_i32 m0, s34, 0xe000
	s_nop 0
	global_load_lds_dwordx4 v[220:221], off
	s_waitcnt vmcnt(8)
	s_waitcnt lgkmcnt(0)
	s_barrier
	s_setprio 1
	v_mfma_f32_16x16x32_bf16 v[126:129], v[130:133], v[178:181], v[126:129]
	v_mfma_f32_16x16x32_bf16 v[126:129], v[134:137], v[192:195], v[126:129]
	v_mfma_f32_16x16x32_bf16 v[122:125], v[138:141], v[178:181], v[122:125]
	v_mfma_f32_16x16x32_bf16 v[122:125], v[142:145], v[192:195], v[122:125]
	v_mfma_f32_16x16x32_bf16 v[110:113], v[130:133], v[196:199], v[110:113]
	v_mfma_f32_16x16x32_bf16 v[110:113], v[134:137], v[200:203], v[110:113]
	v_mfma_f32_16x16x32_bf16 v[106:109], v[138:141], v[196:199], v[106:109]
	v_mfma_f32_16x16x32_bf16 v[106:109], v[142:145], v[200:203], v[106:109]
	v_mfma_f32_16x16x32_bf16 v[94:97], v[130:133], v[204:207], v[94:97]
	v_mfma_f32_16x16x32_bf16 v[94:97], v[134:137], v[208:211], v[94:97]
	v_mfma_f32_16x16x32_bf16 v[90:93], v[138:141], v[204:207], v[90:93]
	v_mfma_f32_16x16x32_bf16 v[90:93], v[142:145], v[208:211], v[90:93]
	v_mfma_f32_16x16x32_bf16 v[78:81], v[130:133], v[212:215], v[78:81]
	v_mfma_f32_16x16x32_bf16 v[78:81], v[134:137], v[216:219], v[78:81]
	v_mfma_f32_16x16x32_bf16 v[74:77], v[138:141], v[212:215], v[74:77]
	v_mfma_f32_16x16x32_bf16 v[74:77], v[142:145], v[216:219], v[74:77]
	s_setprio 0
	s_setprio 1
	v_mfma_f32_16x16x32_bf16 v[118:121], v[146:149], v[178:181], v[118:121]
	v_mfma_f32_16x16x32_bf16 v[118:121], v[150:153], v[192:195], v[118:121]
	v_mfma_f32_16x16x32_bf16 v[114:117], v[170:173], v[178:181], v[114:117]
	v_mfma_f32_16x16x32_bf16 v[114:117], v[174:177], v[192:195], v[114:117]
	v_mfma_f32_16x16x32_bf16 v[102:105], v[146:149], v[196:199], v[102:105]
	v_mfma_f32_16x16x32_bf16 v[102:105], v[150:153], v[200:203], v[102:105]
	v_mfma_f32_16x16x32_bf16 v[98:101], v[170:173], v[196:199], v[98:101]
	v_mfma_f32_16x16x32_bf16 v[98:101], v[174:177], v[200:203], v[98:101]
	v_mfma_f32_16x16x32_bf16 v[86:89], v[146:149], v[204:207], v[86:89]
	v_mfma_f32_16x16x32_bf16 v[86:89], v[150:153], v[208:211], v[86:89]
	v_mfma_f32_16x16x32_bf16 v[82:85], v[170:173], v[204:207], v[82:85]
	v_mfma_f32_16x16x32_bf16 v[82:85], v[174:177], v[208:211], v[82:85]
	v_mfma_f32_16x16x32_bf16 v[70:73], v[146:149], v[212:215], v[70:73]
	v_mfma_f32_16x16x32_bf16 v[70:73], v[150:153], v[216:219], v[70:73]
	v_mfma_f32_16x16x32_bf16 v[66:69], v[170:173], v[212:215], v[66:69]
	v_mfma_f32_16x16x32_bf16 v[66:69], v[174:177], v[216:219], v[66:69]
	s_setprio 0
	s_barrier
	s_add_i32 s0, s43, s33
	v_lshl_add_u64 v[220:221], s[2:3], 0, v[156:157]
	s_mov_b32 m0, s0
	ds_read_b128 v[178:181], v189 offset:16384
	ds_read_b128 v[192:195], v189 offset:17408
	ds_read_b128 v[196:199], v189 offset:18432
	ds_read_b128 v[200:203], v189 offset:19456
	ds_read_b128 v[204:207], v189 offset:20480
	ds_read_b128 v[208:211], v189 offset:21504
	ds_read_b128 v[212:215], v189 offset:22528
	ds_read_b128 v[216:219], v189 offset:23552
	global_load_lds_dwordx4 v[220:221], off
	s_add_i32 m0, s0, 0x2000
	s_add_u32 s0, s2, 0xb0000
	v_lshl_add_u64 v[222:223], s[2:3], 0, v[160:161]
	s_addc_u32 s1, s3, 0
	s_add_i32 s50, s44, s33
	global_load_lds_dwordx4 v[222:223], off
	v_lshl_add_u64 v[224:225], s[0:1], 0, v[156:157]
	s_mov_b32 m0, s50
	v_lshl_add_u64 v[226:227], s[26:27], 0, v[158:159]
	global_load_lds_dwordx4 v[224:225], off
	v_lshl_add_u64 v[224:225], s[0:1], 0, v[160:161]
	s_add_i32 m0, s50, 0x2000
	s_nop 0
	global_load_lds_dwordx4 v[224:225], off
	v_lshl_add_u64 v[224:225], s[26:27], 0, v[154:155]
	s_mov_b32 m0, s34
	s_nop 0
	global_load_lds_dwordx4 v[224:225], off
	s_mov_b32 m0, s35
	s_nop 0
	global_load_lds_dwordx4 v[226:227], off
	s_waitcnt vmcnt(8)
	s_waitcnt lgkmcnt(0)
	s_barrier
	s_setprio 1
	v_mfma_f32_16x16x32_bf16 v[62:65], v[130:133], v[178:181], v[62:65]
	v_mfma_f32_16x16x32_bf16 v[62:65], v[134:137], v[192:195], v[62:65]
	v_mfma_f32_16x16x32_bf16 v[58:61], v[138:141], v[178:181], v[58:61]
	v_mfma_f32_16x16x32_bf16 v[58:61], v[142:145], v[192:195], v[58:61]
	v_mfma_f32_16x16x32_bf16 v[46:49], v[130:133], v[196:199], v[46:49]
	v_mfma_f32_16x16x32_bf16 v[46:49], v[134:137], v[200:203], v[46:49]
	v_mfma_f32_16x16x32_bf16 v[42:45], v[138:141], v[196:199], v[42:45]
	v_mfma_f32_16x16x32_bf16 v[42:45], v[142:145], v[200:203], v[42:45]
	v_mfma_f32_16x16x32_bf16 v[30:33], v[130:133], v[204:207], v[30:33]
	v_mfma_f32_16x16x32_bf16 v[30:33], v[134:137], v[208:211], v[30:33]
	v_mfma_f32_16x16x32_bf16 v[26:29], v[138:141], v[204:207], v[26:29]
	v_mfma_f32_16x16x32_bf16 v[26:29], v[142:145], v[208:211], v[26:29]
	v_mfma_f32_16x16x32_bf16 v[14:17], v[130:133], v[212:215], v[14:17]
	v_mfma_f32_16x16x32_bf16 v[14:17], v[134:137], v[216:219], v[14:17]
	v_mfma_f32_16x16x32_bf16 v[10:13], v[138:141], v[212:215], v[10:13]
	v_mfma_f32_16x16x32_bf16 v[10:13], v[142:145], v[216:219], v[10:13]
	s_setprio 0
	s_setprio 1
	v_mfma_f32_16x16x32_bf16 v[54:57], v[146:149], v[178:181], v[54:57]
	v_mfma_f32_16x16x32_bf16 v[54:57], v[150:153], v[192:195], v[54:57]
	v_mfma_f32_16x16x32_bf16 v[50:53], v[170:173], v[178:181], v[50:53]
	v_mfma_f32_16x16x32_bf16 v[50:53], v[174:177], v[192:195], v[50:53]
	v_mfma_f32_16x16x32_bf16 v[38:41], v[146:149], v[196:199], v[38:41]
	v_mfma_f32_16x16x32_bf16 v[38:41], v[150:153], v[200:203], v[38:41]
	v_mfma_f32_16x16x32_bf16 v[34:37], v[170:173], v[196:199], v[34:37]
	v_mfma_f32_16x16x32_bf16 v[34:37], v[174:177], v[200:203], v[34:37]
	v_mfma_f32_16x16x32_bf16 v[22:25], v[146:149], v[204:207], v[22:25]
	v_mfma_f32_16x16x32_bf16 v[22:25], v[150:153], v[208:211], v[22:25]
	v_mfma_f32_16x16x32_bf16 v[18:21], v[170:173], v[204:207], v[18:21]
	v_mfma_f32_16x16x32_bf16 v[18:21], v[174:177], v[208:211], v[18:21]
	v_mfma_f32_16x16x32_bf16 v[6:9], v[146:149], v[212:215], v[6:9]
	v_mfma_f32_16x16x32_bf16 v[6:9], v[150:153], v[216:219], v[6:9]
	v_mfma_f32_16x16x32_bf16 v[2:5], v[170:173], v[212:215], v[2:5]
	v_mfma_f32_16x16x32_bf16 v[2:5], v[174:177], v[216:219], v[2:5]
	s_setprio 0
	s_barrier
	s_add_i32 s50, 0, 0x18000
	s_add_i32 s51, 0, 0x1c000
	v_add_u32_e32 v142, s50, v183
	v_add_u32_e32 v174, s51, v183
	ds_read_b128 v[130:133], v142
	ds_read_b128 v[134:137], v142 offset:1024
	ds_read_b128 v[138:141], v142 offset:2048
	ds_read_b128 v[142:145], v142 offset:3072
	ds_read_b128 v[146:149], v174
	ds_read_b128 v[150:153], v174 offset:1024
	ds_read_b128 v[170:173], v174 offset:2048
	ds_read_b128 v[174:177], v174 offset:3072
	s_add_u32 s0, s26, 0xb0000
	s_addc_u32 s1, s27, 0
	s_mov_b32 m0, s36
	v_lshl_add_u64 v[228:229], s[0:1], 0, v[154:155]
	ds_read_b128 v[178:181], v189 offset:32768
	ds_read_b128 v[192:195], v189 offset:33792
	ds_read_b128 v[196:199], v189 offset:34816
	ds_read_b128 v[200:203], v189 offset:35840
	ds_read_b128 v[204:207], v189 offset:36864
	ds_read_b128 v[208:211], v189 offset:37888
	ds_read_b128 v[212:215], v189 offset:38912
	ds_read_b128 v[216:219], v189 offset:39936
	global_load_lds_dwordx4 v[228:229], off
	v_lshl_add_u64 v[228:229], s[0:1], 0, v[158:159]
	s_mov_b32 m0, s37
	s_nop 0
	global_load_lds_dwordx4 v[228:229], off
	s_waitcnt vmcnt(8)
	s_waitcnt lgkmcnt(0)
	s_barrier
	s_setprio 1
	v_mfma_f32_16x16x32_bf16 v[126:129], v[130:133], v[178:181], v[126:129]
	v_mfma_f32_16x16x32_bf16 v[126:129], v[134:137], v[192:195], v[126:129]
	v_mfma_f32_16x16x32_bf16 v[122:125], v[138:141], v[178:181], v[122:125]
	v_mfma_f32_16x16x32_bf16 v[122:125], v[142:145], v[192:195], v[122:125]
	v_mfma_f32_16x16x32_bf16 v[110:113], v[130:133], v[196:199], v[110:113]
	v_mfma_f32_16x16x32_bf16 v[110:113], v[134:137], v[200:203], v[110:113]
	v_mfma_f32_16x16x32_bf16 v[106:109], v[138:141], v[196:199], v[106:109]
	v_mfma_f32_16x16x32_bf16 v[106:109], v[142:145], v[200:203], v[106:109]
	v_mfma_f32_16x16x32_bf16 v[94:97], v[130:133], v[204:207], v[94:97]
	v_mfma_f32_16x16x32_bf16 v[94:97], v[134:137], v[208:211], v[94:97]
	v_mfma_f32_16x16x32_bf16 v[90:93], v[138:141], v[204:207], v[90:93]
	v_mfma_f32_16x16x32_bf16 v[90:93], v[142:145], v[208:211], v[90:93]
	v_mfma_f32_16x16x32_bf16 v[78:81], v[130:133], v[212:215], v[78:81]
	v_mfma_f32_16x16x32_bf16 v[78:81], v[134:137], v[216:219], v[78:81]
	v_mfma_f32_16x16x32_bf16 v[74:77], v[138:141], v[212:215], v[74:77]
	v_mfma_f32_16x16x32_bf16 v[74:77], v[142:145], v[216:219], v[74:77]
	s_setprio 0
	s_setprio 1
	v_mfma_f32_16x16x32_bf16 v[118:121], v[146:149], v[178:181], v[118:121]
	v_mfma_f32_16x16x32_bf16 v[118:121], v[150:153], v[192:195], v[118:121]
	v_mfma_f32_16x16x32_bf16 v[114:117], v[170:173], v[178:181], v[114:117]
	v_mfma_f32_16x16x32_bf16 v[114:117], v[174:177], v[192:195], v[114:117]
	v_mfma_f32_16x16x32_bf16 v[102:105], v[146:149], v[196:199], v[102:105]
	v_mfma_f32_16x16x32_bf16 v[102:105], v[150:153], v[200:203], v[102:105]
	v_mfma_f32_16x16x32_bf16 v[98:101], v[170:173], v[196:199], v[98:101]
	v_mfma_f32_16x16x32_bf16 v[98:101], v[174:177], v[200:203], v[98:101]
	v_mfma_f32_16x16x32_bf16 v[86:89], v[146:149], v[204:207], v[86:89]
	v_mfma_f32_16x16x32_bf16 v[86:89], v[150:153], v[208:211], v[86:89]
	v_mfma_f32_16x16x32_bf16 v[82:85], v[170:173], v[204:207], v[82:85]
	v_mfma_f32_16x16x32_bf16 v[82:85], v[174:177], v[208:211], v[82:85]
	v_mfma_f32_16x16x32_bf16 v[70:73], v[146:149], v[212:215], v[70:73]
	v_mfma_f32_16x16x32_bf16 v[70:73], v[150:153], v[216:219], v[70:73]
	v_mfma_f32_16x16x32_bf16 v[66:69], v[170:173], v[212:215], v[66:69]
	v_mfma_f32_16x16x32_bf16 v[66:69], v[174:177], v[216:219], v[66:69]
	s_setprio 0
	s_barrier
	s_add_i32 s0, s50, s33
	v_lshl_add_u64 v[220:221], v[220:221], 0, s[16:17]
	s_mov_b32 m0, s0
	ds_read_b128 v[178:181], v189 offset:49152
	ds_read_b128 v[192:195], v189 offset:50176
	ds_read_b128 v[196:199], v189 offset:51200
	ds_read_b128 v[200:203], v189 offset:52224
	ds_read_b128 v[204:207], v189 offset:53248
	ds_read_b128 v[208:211], v189 offset:54272
	ds_read_b128 v[212:215], v189 offset:55296
	ds_read_b128 v[216:219], v189 offset:56320
	global_load_lds_dwordx4 v[220:221], off
	s_add_i32 m0, s0, 0x2000
	s_add_u32 s0, s2, 0xb0080
	v_lshl_add_u64 v[220:221], v[222:223], 0, s[16:17]
	s_addc_u32 s1, s3, 0
	s_add_i32 s2, s51, s33
	global_load_lds_dwordx4 v[220:221], off
	v_lshl_add_u64 v[220:221], s[0:1], 0, v[156:157]
	s_mov_b32 m0, s2
	s_nop 0
	global_load_lds_dwordx4 v[220:221], off
	v_lshl_add_u64 v[220:221], s[0:1], 0, v[160:161]
	s_add_i32 m0, s2, 0x2000
	s_nop 0
	global_load_lds_dwordx4 v[220:221], off
	v_lshl_add_u64 v[220:221], v[224:225], 0, s[16:17]
	s_mov_b32 m0, s39
	s_nop 0
	global_load_lds_dwordx4 v[220:221], off
	v_lshl_add_u64 v[220:221], v[226:227], 0, s[16:17]
	s_mov_b32 m0, s40
	s_nop 0
	global_load_lds_dwordx4 v[220:221], off
	s_waitcnt vmcnt(8)
	s_waitcnt lgkmcnt(0)
	s_barrier
	s_setprio 1
	v_mfma_f32_16x16x32_bf16 v[62:65], v[130:133], v[178:181], v[62:65]
	v_mfma_f32_16x16x32_bf16 v[62:65], v[134:137], v[192:195], v[62:65]
	v_mfma_f32_16x16x32_bf16 v[58:61], v[138:141], v[178:181], v[58:61]
	v_mfma_f32_16x16x32_bf16 v[58:61], v[142:145], v[192:195], v[58:61]
	v_mfma_f32_16x16x32_bf16 v[46:49], v[130:133], v[196:199], v[46:49]
	v_mfma_f32_16x16x32_bf16 v[46:49], v[134:137], v[200:203], v[46:49]
	v_mfma_f32_16x16x32_bf16 v[42:45], v[138:141], v[196:199], v[42:45]
	v_mfma_f32_16x16x32_bf16 v[42:45], v[142:145], v[200:203], v[42:45]
	v_mfma_f32_16x16x32_bf16 v[30:33], v[130:133], v[204:207], v[30:33]
	v_mfma_f32_16x16x32_bf16 v[30:33], v[134:137], v[208:211], v[30:33]
	v_mfma_f32_16x16x32_bf16 v[26:29], v[138:141], v[204:207], v[26:29]
	v_mfma_f32_16x16x32_bf16 v[26:29], v[142:145], v[208:211], v[26:29]
	v_mfma_f32_16x16x32_bf16 v[14:17], v[130:133], v[212:215], v[14:17]
	v_mfma_f32_16x16x32_bf16 v[14:17], v[134:137], v[216:219], v[14:17]
	v_mfma_f32_16x16x32_bf16 v[10:13], v[138:141], v[212:215], v[10:13]
	v_mfma_f32_16x16x32_bf16 v[10:13], v[142:145], v[216:219], v[10:13]
	s_setprio 0
	s_setprio 1
	v_mfma_f32_16x16x32_bf16 v[54:57], v[146:149], v[178:181], v[54:57]
	s_add_i32 s49, s49, 2
	s_add_u32 s24, s24, 0x100
	s_addc_u32 s25, s25, 0
	s_add_u32 s47, s47, 0x100
	s_addc_u32 s48, s48, 0
	s_cmp_gt_u32 s49, 41
	v_mfma_f32_16x16x32_bf16 v[54:57], v[150:153], v[192:195], v[54:57]
	v_mfma_f32_16x16x32_bf16 v[50:53], v[170:173], v[178:181], v[50:53]
	v_mfma_f32_16x16x32_bf16 v[50:53], v[174:177], v[192:195], v[50:53]
	v_mfma_f32_16x16x32_bf16 v[38:41], v[146:149], v[196:199], v[38:41]
	v_mfma_f32_16x16x32_bf16 v[38:41], v[150:153], v[200:203], v[38:41]
	v_mfma_f32_16x16x32_bf16 v[34:37], v[170:173], v[196:199], v[34:37]
	v_mfma_f32_16x16x32_bf16 v[34:37], v[174:177], v[200:203], v[34:37]
	v_mfma_f32_16x16x32_bf16 v[22:25], v[146:149], v[204:207], v[22:25]
	v_mfma_f32_16x16x32_bf16 v[22:25], v[150:153], v[208:211], v[22:25]
	v_mfma_f32_16x16x32_bf16 v[18:21], v[170:173], v[204:207], v[18:21]
	v_mfma_f32_16x16x32_bf16 v[18:21], v[174:177], v[208:211], v[18:21]
	v_mfma_f32_16x16x32_bf16 v[6:9], v[146:149], v[212:215], v[6:9]
	v_mfma_f32_16x16x32_bf16 v[6:9], v[150:153], v[216:219], v[6:9]
	v_mfma_f32_16x16x32_bf16 v[2:5], v[170:173], v[212:215], v[2:5]
	v_mfma_f32_16x16x32_bf16 v[2:5], v[174:177], v[216:219], v[2:5]
	s_setprio 0
	s_barrier
	s_cbranch_scc0 .LBB0_1123
	s_and_b64 vcc, exec, s[18:19]
	s_cbranch_vccz .LBB0_1126
	s_barrier

.LBB0_1214:
	ds_read_b128 v[62:65], v208
	ds_read_b128 v[78:81], v208 offset:1024
	ds_read_b128 v[98:101], v208 offset:2048
	ds_read_b128 v[118:121], v208 offset:3072
	ds_read_b128 v[138:141], v209
	ds_read_b128 v[150:153], v209 offset:1024
	ds_read_b128 v[154:157], v209 offset:2048
	ds_read_b128 v[178:181], v209 offset:3072
	s_add_u32 s0, s38, 0xfffc0080
	s_addc_u32 s1, s39, -1
	s_cmp_eq_u32 s58, 12
	s_cselect_b32 s41, s7, s1
	s_cselect_b32 s40, s9, s0
	s_cselect_b32 s3, s10, s57
	s_cselect_b32 s2, s29, s31
	v_lshl_add_u64 v[202:203], s[38:39], 0, v[170:171]
	s_add_i32 m0, s43, 0xc000
	ds_read_b128 v[182:185], v210
	ds_read_b128 v[186:189], v210 offset:1024
	ds_read_b128 v[190:193], v210 offset:2048
	ds_read_b128 v[194:197], v210 offset:3072
	ds_read_b128 v[198:201], v210 offset:4096
	ds_read_b128 v[212:215], v210 offset:5120
	ds_read_b128 v[216:219], v210 offset:6144
	ds_read_b128 v[220:223], v210 offset:7168
	global_load_lds_dwordx4 v[202:203], off
	v_lshl_add_u64 v[202:203], s[38:39], 0, v[172:173]
	s_add_i32 m0, s43, 0xe000
	s_nop 0
	global_load_lds_dwordx4 v[202:203], off
	s_waitcnt vmcnt(8)
	s_waitcnt lgkmcnt(0)
	s_barrier
	s_setprio 1
	v_mfma_f32_16x16x32_bf16 v[146:149], v[62:65], v[182:185], v[146:149]
	v_mfma_f32_16x16x32_bf16 v[146:149], v[78:81], v[186:189], v[146:149]
	v_mfma_f32_16x16x32_bf16 v[142:145], v[98:101], v[182:185], v[142:145]
	v_mfma_f32_16x16x32_bf16 v[142:145], v[118:121], v[186:189], v[142:145]
	v_mfma_f32_16x16x32_bf16 v[126:129], v[62:65], v[190:193], v[126:129]
	v_mfma_f32_16x16x32_bf16 v[126:129], v[78:81], v[194:197], v[126:129]
	v_mfma_f32_16x16x32_bf16 v[122:125], v[98:101], v[190:193], v[122:125]
	v_mfma_f32_16x16x32_bf16 v[122:125], v[118:121], v[194:197], v[122:125]
	v_mfma_f32_16x16x32_bf16 v[106:109], v[62:65], v[198:201], v[106:109]
	v_mfma_f32_16x16x32_bf16 v[106:109], v[78:81], v[212:215], v[106:109]
	v_mfma_f32_16x16x32_bf16 v[102:105], v[98:101], v[198:201], v[102:105]
	v_mfma_f32_16x16x32_bf16 v[102:105], v[118:121], v[212:215], v[102:105]
	v_mfma_f32_16x16x32_bf16 v[86:89], v[62:65], v[216:219], v[86:89]
	v_mfma_f32_16x16x32_bf16 v[86:89], v[78:81], v[220:223], v[86:89]
	v_mfma_f32_16x16x32_bf16 v[82:85], v[98:101], v[216:219], v[82:85]
	v_mfma_f32_16x16x32_bf16 v[82:85], v[118:121], v[220:223], v[82:85]
	s_setprio 0
	s_setprio 1
	v_mfma_f32_16x16x32_bf16 v[134:137], v[138:141], v[182:185], v[134:137]
	v_mfma_f32_16x16x32_bf16 v[134:137], v[150:153], v[186:189], v[134:137]
	v_mfma_f32_16x16x32_bf16 v[130:133], v[154:157], v[182:185], v[130:133]
	v_mfma_f32_16x16x32_bf16 v[130:133], v[178:181], v[186:189], v[130:133]
	v_mfma_f32_16x16x32_bf16 v[114:117], v[138:141], v[190:193], v[114:117]
	v_mfma_f32_16x16x32_bf16 v[114:117], v[150:153], v[194:197], v[114:117]
	v_mfma_f32_16x16x32_bf16 v[110:113], v[154:157], v[190:193], v[110:113]
	v_mfma_f32_16x16x32_bf16 v[110:113], v[178:181], v[194:197], v[110:113]
	v_mfma_f32_16x16x32_bf16 v[94:97], v[138:141], v[198:201], v[94:97]
	v_mfma_f32_16x16x32_bf16 v[94:97], v[150:153], v[212:215], v[94:97]
	v_mfma_f32_16x16x32_bf16 v[90:93], v[154:157], v[198:201], v[90:93]
	v_mfma_f32_16x16x32_bf16 v[90:93], v[178:181], v[212:215], v[90:93]
	v_mfma_f32_16x16x32_bf16 v[74:77], v[138:141], v[216:219], v[74:77]
	v_mfma_f32_16x16x32_bf16 v[74:77], v[150:153], v[220:223], v[74:77]
	v_mfma_f32_16x16x32_bf16 v[70:73], v[154:157], v[216:219], v[70:73]
	v_mfma_f32_16x16x32_bf16 v[70:73], v[178:181], v[220:223], v[70:73]
	s_setprio 0
	s_barrier
	s_add_i32 s0, s53, s42
	v_lshl_add_u64 v[202:203], s[2:3], 0, v[162:163]
	s_mov_b32 m0, s0
	ds_read_b128 v[182:185], v210 offset:16384
	ds_read_b128 v[186:189], v210 offset:17408
	ds_read_b128 v[190:193], v210 offset:18432
	ds_read_b128 v[194:197], v210 offset:19456
	ds_read_b128 v[198:201], v210 offset:20480
	ds_read_b128 v[212:215], v210 offset:21504
	ds_read_b128 v[216:219], v210 offset:22528
	ds_read_b128 v[220:223], v210 offset:23552
	global_load_lds_dwordx4 v[202:203], off
	s_add_i32 m0, s0, 0x2000
	s_add_u32 s0, s2, 0x40000
	v_lshl_add_u64 v[224:225], s[2:3], 0, v[166:167]
	s_addc_u32 s1, s3, 0
	s_add_i32 s59, s54, s42
	global_load_lds_dwordx4 v[224:225], off
	v_lshl_add_u64 v[226:227], s[0:1], 0, v[162:163]
	s_mov_b32 m0, s59
	v_lshl_add_u64 v[228:229], s[40:41], 0, v[164:165]
	global_load_lds_dwordx4 v[226:227], off
	v_lshl_add_u64 v[226:227], s[0:1], 0, v[166:167]
	s_add_i32 m0, s59, 0x2000
	s_nop 0
	global_load_lds_dwordx4 v[226:227], off
	v_lshl_add_u64 v[226:227], s[40:41], 0, v[160:161]
	s_mov_b32 m0, s43
	s_nop 0
	global_load_lds_dwordx4 v[226:227], off
	s_mov_b32 m0, s44
	s_nop 0
	global_load_lds_dwordx4 v[228:229], off
	s_waitcnt vmcnt(8)
	s_waitcnt lgkmcnt(0)
	s_barrier
	s_setprio 1
	v_mfma_f32_16x16x32_bf16 v[66:69], v[62:65], v[182:185], v[66:69]
	v_mfma_f32_16x16x32_bf16 v[66:69], v[78:81], v[186:189], v[66:69]
	v_mfma_f32_16x16x32_bf16 v[58:61], v[98:101], v[182:185], v[58:61]
	v_mfma_f32_16x16x32_bf16 v[58:61], v[118:121], v[186:189], v[58:61]
	v_mfma_f32_16x16x32_bf16 v[46:49], v[62:65], v[190:193], v[46:49]
	v_mfma_f32_16x16x32_bf16 v[46:49], v[78:81], v[194:197], v[46:49]
	v_mfma_f32_16x16x32_bf16 v[42:45], v[98:101], v[190:193], v[42:45]
	v_mfma_f32_16x16x32_bf16 v[42:45], v[118:121], v[194:197], v[42:45]
	v_mfma_f32_16x16x32_bf16 v[30:33], v[62:65], v[198:201], v[30:33]
	v_mfma_f32_16x16x32_bf16 v[30:33], v[78:81], v[212:215], v[30:33]
	v_mfma_f32_16x16x32_bf16 v[26:29], v[98:101], v[198:201], v[26:29]
	v_mfma_f32_16x16x32_bf16 v[26:29], v[118:121], v[212:215], v[26:29]
	v_mfma_f32_16x16x32_bf16 v[14:17], v[62:65], v[216:219], v[14:17]
	v_mfma_f32_16x16x32_bf16 v[14:17], v[78:81], v[220:223], v[14:17]
	v_mfma_f32_16x16x32_bf16 v[10:13], v[98:101], v[216:219], v[10:13]
	v_mfma_f32_16x16x32_bf16 v[10:13], v[118:121], v[220:223], v[10:13]
	s_setprio 0
	s_setprio 1
	v_mfma_f32_16x16x32_bf16 v[54:57], v[138:141], v[182:185], v[54:57]
	v_mfma_f32_16x16x32_bf16 v[54:57], v[150:153], v[186:189], v[54:57]
	v_mfma_f32_16x16x32_bf16 v[50:53], v[154:157], v[182:185], v[50:53]
	v_mfma_f32_16x16x32_bf16 v[50:53], v[178:181], v[186:189], v[50:53]
	v_mfma_f32_16x16x32_bf16 v[38:41], v[138:141], v[190:193], v[38:41]
	v_mfma_f32_16x16x32_bf16 v[38:41], v[150:153], v[194:197], v[38:41]
	v_mfma_f32_16x16x32_bf16 v[34:37], v[154:157], v[190:193], v[34:37]
	v_mfma_f32_16x16x32_bf16 v[34:37], v[178:181], v[194:197], v[34:37]
	v_mfma_f32_16x16x32_bf16 v[22:25], v[138:141], v[198:201], v[22:25]
	v_mfma_f32_16x16x32_bf16 v[22:25], v[150:153], v[212:215], v[22:25]
	v_mfma_f32_16x16x32_bf16 v[18:21], v[154:157], v[198:201], v[18:21]
	v_mfma_f32_16x16x32_bf16 v[18:21], v[178:181], v[212:215], v[18:21]
	v_mfma_f32_16x16x32_bf16 v[6:9], v[138:141], v[216:219], v[6:9]
	v_mfma_f32_16x16x32_bf16 v[6:9], v[150:153], v[220:223], v[6:9]
	v_mfma_f32_16x16x32_bf16 v[2:5], v[154:157], v[216:219], v[2:5]
	v_mfma_f32_16x16x32_bf16 v[2:5], v[178:181], v[220:223], v[2:5]
	s_setprio 0
	s_barrier
	s_add_i32 s59, 0, 0x18000
	s_add_i32 s60, 0, 0x1c000
	v_add_u32_e32 v118, s59, v206
	v_add_u32_e32 v168, s60, v206
	ds_read_b128 v[62:65], v118
	ds_read_b128 v[78:81], v118 offset:1024
	ds_read_b128 v[98:101], v118 offset:2048
	ds_read_b128 v[118:121], v118 offset:3072
	ds_read_b128 v[138:141], v168
	ds_read_b128 v[150:153], v168 offset:1024
	ds_read_b128 v[154:157], v168 offset:2048
	ds_read_b128 v[178:181], v168 offset:3072
	s_add_u32 s0, s40, 0x40000
	s_addc_u32 s1, s41, 0
	s_mov_b32 m0, s45
	v_lshl_add_u64 v[230:231], s[0:1], 0, v[160:161]
	ds_read_b128 v[182:185], v210 offset:32768
	ds_read_b128 v[186:189], v210 offset:33792
	ds_read_b128 v[190:193], v210 offset:34816
	ds_read_b128 v[194:197], v210 offset:35840
	ds_read_b128 v[198:201], v210 offset:36864
	ds_read_b128 v[212:215], v210 offset:37888
	ds_read_b128 v[216:219], v210 offset:38912
	ds_read_b128 v[220:223], v210 offset:39936
	global_load_lds_dwordx4 v[230:231], off
	v_lshl_add_u64 v[230:231], s[0:1], 0, v[164:165]
	s_mov_b32 m0, s46
	s_nop 0
	global_load_lds_dwordx4 v[230:231], off
	s_waitcnt vmcnt(8)
	s_waitcnt lgkmcnt(0)
	s_barrier
	s_setprio 1
	v_mfma_f32_16x16x32_bf16 v[146:149], v[62:65], v[182:185], v[146:149]
	v_mfma_f32_16x16x32_bf16 v[146:149], v[78:81], v[186:189], v[146:149]
	v_mfma_f32_16x16x32_bf16 v[142:145], v[98:101], v[182:185], v[142:145]
	v_mfma_f32_16x16x32_bf16 v[142:145], v[118:121], v[186:189], v[142:145]
	v_mfma_f32_16x16x32_bf16 v[126:129], v[62:65], v[190:193], v[126:129]
	v_mfma_f32_16x16x32_bf16 v[126:129], v[78:81], v[194:197], v[126:129]
	v_mfma_f32_16x16x32_bf16 v[122:125], v[98:101], v[190:193], v[122:125]
	v_mfma_f32_16x16x32_bf16 v[122:125], v[118:121], v[194:197], v[122:125]
	v_mfma_f32_16x16x32_bf16 v[106:109], v[62:65], v[198:201], v[106:109]
	v_mfma_f32_16x16x32_bf16 v[106:109], v[78:81], v[212:215], v[106:109]
	v_mfma_f32_16x16x32_bf16 v[102:105], v[98:101], v[198:201], v[102:105]
	v_mfma_f32_16x16x32_bf16 v[102:105], v[118:121], v[212:215], v[102:105]
	v_mfma_f32_16x16x32_bf16 v[86:89], v[62:65], v[216:219], v[86:89]
	v_mfma_f32_16x16x32_bf16 v[86:89], v[78:81], v[220:223], v[86:89]
	v_mfma_f32_16x16x32_bf16 v[82:85], v[98:101], v[216:219], v[82:85]
	v_mfma_f32_16x16x32_bf16 v[82:85], v[118:121], v[220:223], v[82:85]
	s_setprio 0
	s_setprio 1
	v_mfma_f32_16x16x32_bf16 v[134:137], v[138:141], v[182:185], v[134:137]
	v_mfma_f32_16x16x32_bf16 v[134:137], v[150:153], v[186:189], v[134:137]
	v_mfma_f32_16x16x32_bf16 v[130:133], v[154:157], v[182:185], v[130:133]
	v_mfma_f32_16x16x32_bf16 v[130:133], v[178:181], v[186:189], v[130:133]
	v_mfma_f32_16x16x32_bf16 v[114:117], v[138:141], v[190:193], v[114:117]
	v_mfma_f32_16x16x32_bf16 v[114:117], v[150:153], v[194:197], v[114:117]
	v_mfma_f32_16x16x32_bf16 v[110:113], v[154:157], v[190:193], v[110:113]
	v_mfma_f32_16x16x32_bf16 v[110:113], v[178:181], v[194:197], v[110:113]
	v_mfma_f32_16x16x32_bf16 v[94:97], v[138:141], v[198:201], v[94:97]
	v_mfma_f32_16x16x32_bf16 v[94:97], v[150:153], v[212:215], v[94:97]
	v_mfma_f32_16x16x32_bf16 v[90:93], v[154:157], v[198:201], v[90:93]
	v_mfma_f32_16x16x32_bf16 v[90:93], v[178:181], v[212:215], v[90:93]
	v_mfma_f32_16x16x32_bf16 v[74:77], v[138:141], v[216:219], v[74:77]
	v_mfma_f32_16x16x32_bf16 v[74:77], v[150:153], v[220:223], v[74:77]
	v_mfma_f32_16x16x32_bf16 v[70:73], v[154:157], v[216:219], v[70:73]
	v_mfma_f32_16x16x32_bf16 v[70:73], v[178:181], v[220:223], v[70:73]
	s_setprio 0
	s_barrier
	s_add_i32 s0, s59, s42
	v_lshl_add_u64 v[202:203], v[202:203], 0, s[22:23]
	s_mov_b32 m0, s0
	ds_read_b128 v[182:185], v210 offset:49152
	ds_read_b128 v[186:189], v210 offset:50176
	ds_read_b128 v[190:193], v210 offset:51200
	ds_read_b128 v[194:197], v210 offset:52224
	ds_read_b128 v[198:201], v210 offset:53248
	ds_read_b128 v[212:215], v210 offset:54272
	ds_read_b128 v[216:219], v210 offset:55296
	ds_read_b128 v[220:223], v210 offset:56320
	global_load_lds_dwordx4 v[202:203], off
	s_add_i32 m0, s0, 0x2000
	s_add_u32 s0, s2, 0x40080
	v_lshl_add_u64 v[202:203], v[224:225], 0, s[22:23]
	s_addc_u32 s1, s3, 0
	s_add_i32 s2, s60, s42
	global_load_lds_dwordx4 v[202:203], off
	v_lshl_add_u64 v[202:203], s[0:1], 0, v[162:163]
	s_mov_b32 m0, s2
	s_nop 0
	global_load_lds_dwordx4 v[202:203], off
	v_lshl_add_u64 v[202:203], s[0:1], 0, v[166:167]
	s_add_i32 m0, s2, 0x2000
	s_nop 0
	global_load_lds_dwordx4 v[202:203], off
	v_lshl_add_u64 v[202:203], v[226:227], 0, s[22:23]
	s_mov_b32 m0, s49
	s_nop 0
	global_load_lds_dwordx4 v[202:203], off
	v_lshl_add_u64 v[202:203], v[228:229], 0, s[22:23]
	s_mov_b32 m0, s50
	s_nop 0
	global_load_lds_dwordx4 v[202:203], off
	s_waitcnt vmcnt(8)
	s_waitcnt lgkmcnt(0)
	s_barrier
	s_setprio 1
	v_mfma_f32_16x16x32_bf16 v[66:69], v[62:65], v[182:185], v[66:69]
	v_mfma_f32_16x16x32_bf16 v[66:69], v[78:81], v[186:189], v[66:69]
	v_mfma_f32_16x16x32_bf16 v[58:61], v[98:101], v[182:185], v[58:61]
	v_mfma_f32_16x16x32_bf16 v[58:61], v[118:121], v[186:189], v[58:61]
	v_mfma_f32_16x16x32_bf16 v[46:49], v[62:65], v[190:193], v[46:49]
	v_mfma_f32_16x16x32_bf16 v[46:49], v[78:81], v[194:197], v[46:49]
	v_mfma_f32_16x16x32_bf16 v[42:45], v[98:101], v[190:193], v[42:45]
	v_mfma_f32_16x16x32_bf16 v[42:45], v[118:121], v[194:197], v[42:45]
	v_mfma_f32_16x16x32_bf16 v[30:33], v[62:65], v[198:201], v[30:33]
	v_mfma_f32_16x16x32_bf16 v[30:33], v[78:81], v[212:215], v[30:33]
	v_mfma_f32_16x16x32_bf16 v[26:29], v[98:101], v[198:201], v[26:29]
	v_mfma_f32_16x16x32_bf16 v[26:29], v[118:121], v[212:215], v[26:29]
	v_mfma_f32_16x16x32_bf16 v[14:17], v[62:65], v[216:219], v[14:17]
	v_mfma_f32_16x16x32_bf16 v[14:17], v[78:81], v[220:223], v[14:17]
	v_mfma_f32_16x16x32_bf16 v[10:13], v[98:101], v[216:219], v[10:13]
	v_mfma_f32_16x16x32_bf16 v[10:13], v[118:121], v[220:223], v[10:13]
	s_setprio 0
	s_setprio 1
	v_mfma_f32_16x16x32_bf16 v[54:57], v[138:141], v[182:185], v[54:57]
	s_add_i32 s58, s58, 2
	s_add_u32 s38, s38, 0x100
	s_addc_u32 s39, s39, 0
	s_add_u32 s31, s31, 0x100
	s_addc_u32 s57, s57, 0
	s_cmp_gt_u32 s58, 13
	v_mfma_f32_16x16x32_bf16 v[54:57], v[150:153], v[186:189], v[54:57]
	v_mfma_f32_16x16x32_bf16 v[50:53], v[154:157], v[182:185], v[50:53]
	v_mfma_f32_16x16x32_bf16 v[50:53], v[178:181], v[186:189], v[50:53]
	v_mfma_f32_16x16x32_bf16 v[38:41], v[138:141], v[190:193], v[38:41]
	v_mfma_f32_16x16x32_bf16 v[38:41], v[150:153], v[194:197], v[38:41]
	v_mfma_f32_16x16x32_bf16 v[34:37], v[154:157], v[190:193], v[34:37]
	v_mfma_f32_16x16x32_bf16 v[34:37], v[178:181], v[194:197], v[34:37]
	v_mfma_f32_16x16x32_bf16 v[22:25], v[138:141], v[198:201], v[22:25]
	v_mfma_f32_16x16x32_bf16 v[22:25], v[150:153], v[212:215], v[22:25]
	v_mfma_f32_16x16x32_bf16 v[18:21], v[154:157], v[198:201], v[18:21]
	v_mfma_f32_16x16x32_bf16 v[18:21], v[178:181], v[212:215], v[18:21]
	v_mfma_f32_16x16x32_bf16 v[6:9], v[138:141], v[216:219], v[6:9]
	v_mfma_f32_16x16x32_bf16 v[6:9], v[150:153], v[220:223], v[6:9]
	v_mfma_f32_16x16x32_bf16 v[2:5], v[154:157], v[216:219], v[2:5]
	v_mfma_f32_16x16x32_bf16 v[2:5], v[178:181], v[220:223], v[2:5]
	s_setprio 0
	s_barrier
	s_cbranch_scc0 .LBB0_1214
	s_and_b64 vcc, exec, s[24:25]
	s_cbranch_vccz .LBB0_1217
	s_barrier

.LBB0_1626:
	ds_read_b128 v[130:133], v186
	ds_read_b128 v[134:137], v186 offset:1024
	ds_read_b128 v[138:141], v186 offset:2048
	ds_read_b128 v[142:145], v186 offset:3072
	ds_read_b128 v[146:149], v187
	ds_read_b128 v[150:153], v187 offset:1024
	ds_read_b128 v[170:173], v187 offset:2048
	ds_read_b128 v[174:177], v187 offset:3072
	s_add_u32 s0, s38, 0xfff80080
	s_addc_u32 s1, s39, -1
	s_cmp_eq_u32 s59, 28
	s_cselect_b32 s41, s11, s1
	s_cselect_b32 s40, s29, s0
	s_cselect_b32 s3, s27, s58
	s_cselect_b32 s2, s56, s57
	v_lshl_add_u64 v[218:219], s[38:39], 0, v[162:163]
	s_add_i32 m0, s37, 0xc000
	ds_read_b128 v[178:181], v188
	ds_read_b128 v[190:193], v188 offset:1024
	ds_read_b128 v[194:197], v188 offset:2048
	ds_read_b128 v[198:201], v188 offset:3072
	ds_read_b128 v[202:205], v188 offset:4096
	ds_read_b128 v[206:209], v188 offset:5120
	ds_read_b128 v[210:213], v188 offset:6144
	ds_read_b128 v[214:217], v188 offset:7168
	global_load_lds_dwordx4 v[218:219], off
	v_lshl_add_u64 v[218:219], s[38:39], 0, v[164:165]
	s_add_i32 m0, s37, 0xe000
	s_nop 0
	global_load_lds_dwordx4 v[218:219], off
	s_waitcnt vmcnt(8)
	s_waitcnt lgkmcnt(0)
	s_barrier
	s_setprio 1
	v_mfma_f32_16x16x32_bf16 v[126:129], v[130:133], v[178:181], v[126:129]
	v_mfma_f32_16x16x32_bf16 v[126:129], v[134:137], v[190:193], v[126:129]
	v_mfma_f32_16x16x32_bf16 v[122:125], v[138:141], v[178:181], v[122:125]
	v_mfma_f32_16x16x32_bf16 v[122:125], v[142:145], v[190:193], v[122:125]
	v_mfma_f32_16x16x32_bf16 v[110:113], v[130:133], v[194:197], v[110:113]
	v_mfma_f32_16x16x32_bf16 v[110:113], v[134:137], v[198:201], v[110:113]
	v_mfma_f32_16x16x32_bf16 v[106:109], v[138:141], v[194:197], v[106:109]
	v_mfma_f32_16x16x32_bf16 v[106:109], v[142:145], v[198:201], v[106:109]
	v_mfma_f32_16x16x32_bf16 v[94:97], v[130:133], v[202:205], v[94:97]
	v_mfma_f32_16x16x32_bf16 v[94:97], v[134:137], v[206:209], v[94:97]
	v_mfma_f32_16x16x32_bf16 v[90:93], v[138:141], v[202:205], v[90:93]
	v_mfma_f32_16x16x32_bf16 v[90:93], v[142:145], v[206:209], v[90:93]
	v_mfma_f32_16x16x32_bf16 v[78:81], v[130:133], v[210:213], v[78:81]
	v_mfma_f32_16x16x32_bf16 v[78:81], v[134:137], v[214:217], v[78:81]
	v_mfma_f32_16x16x32_bf16 v[74:77], v[138:141], v[210:213], v[74:77]
	v_mfma_f32_16x16x32_bf16 v[74:77], v[142:145], v[214:217], v[74:77]
	s_setprio 0
	s_setprio 1
	v_mfma_f32_16x16x32_bf16 v[118:121], v[146:149], v[178:181], v[118:121]
	v_mfma_f32_16x16x32_bf16 v[118:121], v[150:153], v[190:193], v[118:121]
	v_mfma_f32_16x16x32_bf16 v[114:117], v[170:173], v[178:181], v[114:117]
	v_mfma_f32_16x16x32_bf16 v[114:117], v[174:177], v[190:193], v[114:117]
	v_mfma_f32_16x16x32_bf16 v[102:105], v[146:149], v[194:197], v[102:105]
	v_mfma_f32_16x16x32_bf16 v[102:105], v[150:153], v[198:201], v[102:105]
	v_mfma_f32_16x16x32_bf16 v[98:101], v[170:173], v[194:197], v[98:101]
	v_mfma_f32_16x16x32_bf16 v[98:101], v[174:177], v[198:201], v[98:101]
	v_mfma_f32_16x16x32_bf16 v[86:89], v[146:149], v[202:205], v[86:89]
	v_mfma_f32_16x16x32_bf16 v[86:89], v[150:153], v[206:209], v[86:89]
	v_mfma_f32_16x16x32_bf16 v[82:85], v[170:173], v[202:205], v[82:85]
	v_mfma_f32_16x16x32_bf16 v[82:85], v[174:177], v[206:209], v[82:85]
	v_mfma_f32_16x16x32_bf16 v[70:73], v[146:149], v[210:213], v[70:73]
	v_mfma_f32_16x16x32_bf16 v[70:73], v[150:153], v[214:217], v[70:73]
	v_mfma_f32_16x16x32_bf16 v[66:69], v[170:173], v[210:213], v[66:69]
	v_mfma_f32_16x16x32_bf16 v[66:69], v[174:177], v[214:217], v[66:69]
	s_setprio 0
	s_barrier
	s_add_i32 s0, s54, s45
	v_lshl_add_u64 v[218:219], s[2:3], 0, v[156:157]
	s_mov_b32 m0, s0
	ds_read_b128 v[178:181], v188 offset:16384
	ds_read_b128 v[190:193], v188 offset:17408
	ds_read_b128 v[194:197], v188 offset:18432
	ds_read_b128 v[198:201], v188 offset:19456
	ds_read_b128 v[202:205], v188 offset:20480
	ds_read_b128 v[206:209], v188 offset:21504
	ds_read_b128 v[210:213], v188 offset:22528
	ds_read_b128 v[214:217], v188 offset:23552
	global_load_lds_dwordx4 v[218:219], off
	s_add_i32 m0, s0, 0x2000
	s_add_u32 s0, s2, 0x80000
	v_lshl_add_u64 v[220:221], s[2:3], 0, v[160:161]
	s_addc_u32 s1, s3, 0
	s_add_i32 s60, s55, s45
	global_load_lds_dwordx4 v[220:221], off
	v_lshl_add_u64 v[222:223], s[0:1], 0, v[156:157]
	s_mov_b32 m0, s60
	v_lshl_add_u64 v[224:225], s[40:41], 0, v[158:159]
	global_load_lds_dwordx4 v[222:223], off
	v_lshl_add_u64 v[222:223], s[0:1], 0, v[160:161]
	s_add_i32 m0, s60, 0x2000
	s_nop 0
	global_load_lds_dwordx4 v[222:223], off
	v_lshl_add_u64 v[222:223], s[40:41], 0, v[154:155]
	s_mov_b32 m0, s37
	s_nop 0
	global_load_lds_dwordx4 v[222:223], off
	s_mov_b32 m0, s46
	s_nop 0
	global_load_lds_dwordx4 v[224:225], off
	s_waitcnt vmcnt(8)
	s_waitcnt lgkmcnt(0)
	s_barrier
	s_setprio 1
	v_mfma_f32_16x16x32_bf16 v[62:65], v[130:133], v[178:181], v[62:65]
	v_mfma_f32_16x16x32_bf16 v[62:65], v[134:137], v[190:193], v[62:65]
	v_mfma_f32_16x16x32_bf16 v[58:61], v[138:141], v[178:181], v[58:61]
	v_mfma_f32_16x16x32_bf16 v[58:61], v[142:145], v[190:193], v[58:61]
	v_mfma_f32_16x16x32_bf16 v[46:49], v[130:133], v[194:197], v[46:49]
	v_mfma_f32_16x16x32_bf16 v[46:49], v[134:137], v[198:201], v[46:49]
	v_mfma_f32_16x16x32_bf16 v[42:45], v[138:141], v[194:197], v[42:45]
	v_mfma_f32_16x16x32_bf16 v[42:45], v[142:145], v[198:201], v[42:45]
	v_mfma_f32_16x16x32_bf16 v[30:33], v[130:133], v[202:205], v[30:33]
	v_mfma_f32_16x16x32_bf16 v[30:33], v[134:137], v[206:209], v[30:33]
	v_mfma_f32_16x16x32_bf16 v[26:29], v[138:141], v[202:205], v[26:29]
	v_mfma_f32_16x16x32_bf16 v[26:29], v[142:145], v[206:209], v[26:29]
	v_mfma_f32_16x16x32_bf16 v[14:17], v[130:133], v[210:213], v[14:17]
	v_mfma_f32_16x16x32_bf16 v[14:17], v[134:137], v[214:217], v[14:17]
	v_mfma_f32_16x16x32_bf16 v[10:13], v[138:141], v[210:213], v[10:13]
	v_mfma_f32_16x16x32_bf16 v[10:13], v[142:145], v[214:217], v[10:13]
	s_setprio 0
	s_setprio 1
	v_mfma_f32_16x16x32_bf16 v[54:57], v[146:149], v[178:181], v[54:57]
	v_mfma_f32_16x16x32_bf16 v[54:57], v[150:153], v[190:193], v[54:57]
	v_mfma_f32_16x16x32_bf16 v[50:53], v[170:173], v[178:181], v[50:53]
	v_mfma_f32_16x16x32_bf16 v[50:53], v[174:177], v[190:193], v[50:53]
	v_mfma_f32_16x16x32_bf16 v[38:41], v[146:149], v[194:197], v[38:41]
	v_mfma_f32_16x16x32_bf16 v[38:41], v[150:153], v[198:201], v[38:41]
	v_mfma_f32_16x16x32_bf16 v[34:37], v[170:173], v[194:197], v[34:37]
	v_mfma_f32_16x16x32_bf16 v[34:37], v[174:177], v[198:201], v[34:37]
	v_mfma_f32_16x16x32_bf16 v[22:25], v[146:149], v[202:205], v[22:25]
	v_mfma_f32_16x16x32_bf16 v[22:25], v[150:153], v[206:209], v[22:25]
	v_mfma_f32_16x16x32_bf16 v[18:21], v[170:173], v[202:205], v[18:21]
	v_mfma_f32_16x16x32_bf16 v[18:21], v[174:177], v[206:209], v[18:21]
	v_mfma_f32_16x16x32_bf16 v[6:9], v[146:149], v[210:213], v[6:9]
	v_mfma_f32_16x16x32_bf16 v[6:9], v[150:153], v[214:217], v[6:9]
	v_mfma_f32_16x16x32_bf16 v[2:5], v[170:173], v[210:213], v[2:5]
	v_mfma_f32_16x16x32_bf16 v[2:5], v[174:177], v[214:217], v[2:5]
	s_setprio 0
	s_barrier
	s_add_i32 s60, 0, 0x18000
	s_add_i32 s61, 0, 0x1c000
	v_add_u32_e32 v142, s60, v182
	v_add_u32_e32 v174, s61, v182
	ds_read_b128 v[130:133], v142
	ds_read_b128 v[134:137], v142 offset:1024
	ds_read_b128 v[138:141], v142 offset:2048
	ds_read_b128 v[142:145], v142 offset:3072
	ds_read_b128 v[146:149], v174
	ds_read_b128 v[150:153], v174 offset:1024
	ds_read_b128 v[170:173], v174 offset:2048
	ds_read_b128 v[174:177], v174 offset:3072
	s_add_u32 s0, s40, 0x80000
	s_addc_u32 s1, s41, 0
	s_mov_b32 m0, s47
	v_lshl_add_u64 v[226:227], s[0:1], 0, v[154:155]
	ds_read_b128 v[178:181], v188 offset:32768
	ds_read_b128 v[190:193], v188 offset:33792
	ds_read_b128 v[194:197], v188 offset:34816
	ds_read_b128 v[198:201], v188 offset:35840
	ds_read_b128 v[202:205], v188 offset:36864
	ds_read_b128 v[206:209], v188 offset:37888
	ds_read_b128 v[210:213], v188 offset:38912
	ds_read_b128 v[214:217], v188 offset:39936
	global_load_lds_dwordx4 v[226:227], off
	v_lshl_add_u64 v[226:227], s[0:1], 0, v[158:159]
	s_mov_b32 m0, s48
	s_nop 0
	global_load_lds_dwordx4 v[226:227], off
	s_waitcnt vmcnt(8)
	s_waitcnt lgkmcnt(0)
	s_barrier
	s_setprio 1
	v_mfma_f32_16x16x32_bf16 v[126:129], v[130:133], v[178:181], v[126:129]
	v_mfma_f32_16x16x32_bf16 v[126:129], v[134:137], v[190:193], v[126:129]
	v_mfma_f32_16x16x32_bf16 v[122:125], v[138:141], v[178:181], v[122:125]
	v_mfma_f32_16x16x32_bf16 v[122:125], v[142:145], v[190:193], v[122:125]
	v_mfma_f32_16x16x32_bf16 v[110:113], v[130:133], v[194:197], v[110:113]
	v_mfma_f32_16x16x32_bf16 v[110:113], v[134:137], v[198:201], v[110:113]
	v_mfma_f32_16x16x32_bf16 v[106:109], v[138:141], v[194:197], v[106:109]
	v_mfma_f32_16x16x32_bf16 v[106:109], v[142:145], v[198:201], v[106:109]
	v_mfma_f32_16x16x32_bf16 v[94:97], v[130:133], v[202:205], v[94:97]
	v_mfma_f32_16x16x32_bf16 v[94:97], v[134:137], v[206:209], v[94:97]
	v_mfma_f32_16x16x32_bf16 v[90:93], v[138:141], v[202:205], v[90:93]
	v_mfma_f32_16x16x32_bf16 v[90:93], v[142:145], v[206:209], v[90:93]
	v_mfma_f32_16x16x32_bf16 v[78:81], v[130:133], v[210:213], v[78:81]
	v_mfma_f32_16x16x32_bf16 v[78:81], v[134:137], v[214:217], v[78:81]
	v_mfma_f32_16x16x32_bf16 v[74:77], v[138:141], v[210:213], v[74:77]
	v_mfma_f32_16x16x32_bf16 v[74:77], v[142:145], v[214:217], v[74:77]
	s_setprio 0
	s_setprio 1
	v_mfma_f32_16x16x32_bf16 v[118:121], v[146:149], v[178:181], v[118:121]
	v_mfma_f32_16x16x32_bf16 v[118:121], v[150:153], v[190:193], v[118:121]
	v_mfma_f32_16x16x32_bf16 v[114:117], v[170:173], v[178:181], v[114:117]
	v_mfma_f32_16x16x32_bf16 v[114:117], v[174:177], v[190:193], v[114:117]
	v_mfma_f32_16x16x32_bf16 v[102:105], v[146:149], v[194:197], v[102:105]
	v_mfma_f32_16x16x32_bf16 v[102:105], v[150:153], v[198:201], v[102:105]
	v_mfma_f32_16x16x32_bf16 v[98:101], v[170:173], v[194:197], v[98:101]
	v_mfma_f32_16x16x32_bf16 v[98:101], v[174:177], v[198:201], v[98:101]
	v_mfma_f32_16x16x32_bf16 v[86:89], v[146:149], v[202:205], v[86:89]
	v_mfma_f32_16x16x32_bf16 v[86:89], v[150:153], v[206:209], v[86:89]
	v_mfma_f32_16x16x32_bf16 v[82:85], v[170:173], v[202:205], v[82:85]
	v_mfma_f32_16x16x32_bf16 v[82:85], v[174:177], v[206:209], v[82:85]
	v_mfma_f32_16x16x32_bf16 v[70:73], v[146:149], v[210:213], v[70:73]
	v_mfma_f32_16x16x32_bf16 v[70:73], v[150:153], v[214:217], v[70:73]
	v_mfma_f32_16x16x32_bf16 v[66:69], v[170:173], v[210:213], v[66:69]
	v_mfma_f32_16x16x32_bf16 v[66:69], v[174:177], v[214:217], v[66:69]
	s_setprio 0
	s_barrier
	s_add_i32 s0, s60, s45
	v_lshl_add_u64 v[218:219], v[218:219], 0, s[14:15]
	s_mov_b32 m0, s0
	ds_read_b128 v[178:181], v188 offset:49152
	ds_read_b128 v[190:193], v188 offset:50176
	ds_read_b128 v[194:197], v188 offset:51200
	ds_read_b128 v[198:201], v188 offset:52224
	ds_read_b128 v[202:205], v188 offset:53248
	ds_read_b128 v[206:209], v188 offset:54272
	ds_read_b128 v[210:213], v188 offset:55296
	ds_read_b128 v[214:217], v188 offset:56320
	global_load_lds_dwordx4 v[218:219], off
	s_add_i32 m0, s0, 0x2000
	s_add_u32 s0, s2, 0x80080
	v_lshl_add_u64 v[218:219], v[220:221], 0, s[14:15]
	s_addc_u32 s1, s3, 0
	s_add_i32 s2, s61, s45
	global_load_lds_dwordx4 v[218:219], off
	v_lshl_add_u64 v[218:219], s[0:1], 0, v[156:157]
	s_mov_b32 m0, s2
	s_nop 0
	global_load_lds_dwordx4 v[218:219], off
	v_lshl_add_u64 v[218:219], s[0:1], 0, v[160:161]
	s_add_i32 m0, s2, 0x2000
	s_nop 0
	global_load_lds_dwordx4 v[218:219], off
	v_lshl_add_u64 v[218:219], v[222:223], 0, s[14:15]
	s_mov_b32 m0, s50
	s_nop 0
	global_load_lds_dwordx4 v[218:219], off
	v_lshl_add_u64 v[218:219], v[224:225], 0, s[14:15]
	s_mov_b32 m0, s51
	s_nop 0
	global_load_lds_dwordx4 v[218:219], off
	s_waitcnt vmcnt(8)
	s_waitcnt lgkmcnt(0)
	s_barrier
	s_setprio 1
	v_mfma_f32_16x16x32_bf16 v[62:65], v[130:133], v[178:181], v[62:65]
	v_mfma_f32_16x16x32_bf16 v[62:65], v[134:137], v[190:193], v[62:65]
	v_mfma_f32_16x16x32_bf16 v[58:61], v[138:141], v[178:181], v[58:61]
	v_mfma_f32_16x16x32_bf16 v[58:61], v[142:145], v[190:193], v[58:61]
	v_mfma_f32_16x16x32_bf16 v[46:49], v[130:133], v[194:197], v[46:49]
	v_mfma_f32_16x16x32_bf16 v[46:49], v[134:137], v[198:201], v[46:49]
	v_mfma_f32_16x16x32_bf16 v[42:45], v[138:141], v[194:197], v[42:45]
	v_mfma_f32_16x16x32_bf16 v[42:45], v[142:145], v[198:201], v[42:45]
	v_mfma_f32_16x16x32_bf16 v[30:33], v[130:133], v[202:205], v[30:33]
	v_mfma_f32_16x16x32_bf16 v[30:33], v[134:137], v[206:209], v[30:33]
	v_mfma_f32_16x16x32_bf16 v[26:29], v[138:141], v[202:205], v[26:29]
	v_mfma_f32_16x16x32_bf16 v[26:29], v[142:145], v[206:209], v[26:29]
	v_mfma_f32_16x16x32_bf16 v[14:17], v[130:133], v[210:213], v[14:17]
	v_mfma_f32_16x16x32_bf16 v[14:17], v[134:137], v[214:217], v[14:17]
	v_mfma_f32_16x16x32_bf16 v[10:13], v[138:141], v[210:213], v[10:13]
	v_mfma_f32_16x16x32_bf16 v[10:13], v[142:145], v[214:217], v[10:13]
	s_setprio 0
	s_setprio 1
	v_mfma_f32_16x16x32_bf16 v[54:57], v[146:149], v[178:181], v[54:57]
	s_add_i32 s59, s59, 2
	s_add_u32 s38, s38, 0x100
	s_addc_u32 s39, s39, 0
	s_add_u32 s57, s57, 0x100
	s_addc_u32 s58, s58, 0
	s_cmp_gt_u32 s59, 29
	v_mfma_f32_16x16x32_bf16 v[54:57], v[150:153], v[190:193], v[54:57]
	v_mfma_f32_16x16x32_bf16 v[50:53], v[170:173], v[178:181], v[50:53]
	v_mfma_f32_16x16x32_bf16 v[50:53], v[174:177], v[190:193], v[50:53]
	v_mfma_f32_16x16x32_bf16 v[38:41], v[146:149], v[194:197], v[38:41]
	v_mfma_f32_16x16x32_bf16 v[38:41], v[150:153], v[198:201], v[38:41]
	v_mfma_f32_16x16x32_bf16 v[34:37], v[170:173], v[194:197], v[34:37]
	v_mfma_f32_16x16x32_bf16 v[34:37], v[174:177], v[198:201], v[34:37]
	v_mfma_f32_16x16x32_bf16 v[22:25], v[146:149], v[202:205], v[22:25]
	v_mfma_f32_16x16x32_bf16 v[22:25], v[150:153], v[206:209], v[22:25]
	v_mfma_f32_16x16x32_bf16 v[18:21], v[170:173], v[202:205], v[18:21]
	v_mfma_f32_16x16x32_bf16 v[18:21], v[174:177], v[206:209], v[18:21]
	v_mfma_f32_16x16x32_bf16 v[6:9], v[146:149], v[210:213], v[6:9]
	v_mfma_f32_16x16x32_bf16 v[6:9], v[150:153], v[214:217], v[6:9]
	v_mfma_f32_16x16x32_bf16 v[2:5], v[170:173], v[210:213], v[2:5]
	v_mfma_f32_16x16x32_bf16 v[2:5], v[174:177], v[214:217], v[2:5]
	s_setprio 0
	s_barrier
	s_cbranch_scc0 .LBB0_1626
	s_and_b64 vcc, exec, s[16:17]
	s_cbranch_vccz .LBB0_1629
	s_barrier

.LBB0_1715:
	ds_read_b128 v[148:151], v166
	ds_read_b128 v[152:155], v166 offset:1024
	ds_read_b128 v[156:159], v166 offset:2048
	ds_read_b128 v[160:163], v166 offset:3072
	ds_read_b128 v[170:173], v167
	ds_read_b128 v[174:177], v167 offset:1024
	ds_read_b128 v[178:181], v167 offset:2048
	ds_read_b128 v[182:185], v167 offset:3072
	s_add_u32 s0, s28, 0xfffc0080
	s_addc_u32 s1, s29, -1
	s_cmp_eq_u32 s53, 12
	s_cselect_b32 s31, s21, s1
	s_cselect_b32 s30, s49, s0
	s_cselect_b32 s3, s19, s52
	s_cselect_b32 s2, s50, s51
	v_lshl_add_u64 v[218:219], s[28:29], 0, v[140:141]
	s_add_i32 m0, s27, 0xc000
	ds_read_b128 v[186:189], v168
	ds_read_b128 v[190:193], v168 offset:1024
	ds_read_b128 v[194:197], v168 offset:2048
	ds_read_b128 v[198:201], v168 offset:3072
	ds_read_b128 v[202:205], v168 offset:4096
	ds_read_b128 v[206:209], v168 offset:5120
	ds_read_b128 v[210:213], v168 offset:6144
	ds_read_b128 v[214:217], v168 offset:7168
	global_load_lds_dwordx4 v[218:219], off
	v_lshl_add_u64 v[218:219], s[28:29], 0, v[142:143]
	s_add_i32 m0, s27, 0xe000
	s_nop 0
	global_load_lds_dwordx4 v[218:219], off
	s_waitcnt vmcnt(8)
	s_waitcnt lgkmcnt(0)
	s_barrier
	s_setprio 1
	v_mfma_f32_16x16x32_bf16 v[126:129], v[148:151], v[186:189], v[126:129]
	v_mfma_f32_16x16x32_bf16 v[126:129], v[152:155], v[190:193], v[126:129]
	v_mfma_f32_16x16x32_bf16 v[118:121], v[156:159], v[186:189], v[118:121]
	v_mfma_f32_16x16x32_bf16 v[118:121], v[160:163], v[190:193], v[118:121]
	v_mfma_f32_16x16x32_bf16 v[110:113], v[148:151], v[194:197], v[110:113]
	v_mfma_f32_16x16x32_bf16 v[110:113], v[152:155], v[198:201], v[110:113]
	v_mfma_f32_16x16x32_bf16 v[102:105], v[156:159], v[194:197], v[102:105]
	v_mfma_f32_16x16x32_bf16 v[102:105], v[160:163], v[198:201], v[102:105]
	v_mfma_f32_16x16x32_bf16 v[94:97], v[148:151], v[202:205], v[94:97]
	v_mfma_f32_16x16x32_bf16 v[94:97], v[152:155], v[206:209], v[94:97]
	v_mfma_f32_16x16x32_bf16 v[86:89], v[156:159], v[202:205], v[86:89]
	v_mfma_f32_16x16x32_bf16 v[86:89], v[160:163], v[206:209], v[86:89]
	v_mfma_f32_16x16x32_bf16 v[78:81], v[148:151], v[210:213], v[78:81]
	v_mfma_f32_16x16x32_bf16 v[78:81], v[152:155], v[214:217], v[78:81]
	v_mfma_f32_16x16x32_bf16 v[70:73], v[156:159], v[210:213], v[70:73]
	v_mfma_f32_16x16x32_bf16 v[70:73], v[160:163], v[214:217], v[70:73]
	s_setprio 0
	s_setprio 1
	v_mfma_f32_16x16x32_bf16 v[122:125], v[170:173], v[186:189], v[122:125]
	v_mfma_f32_16x16x32_bf16 v[122:125], v[174:177], v[190:193], v[122:125]
	v_mfma_f32_16x16x32_bf16 v[114:117], v[178:181], v[186:189], v[114:117]
	v_mfma_f32_16x16x32_bf16 v[114:117], v[182:185], v[190:193], v[114:117]
	v_mfma_f32_16x16x32_bf16 v[106:109], v[170:173], v[194:197], v[106:109]
	v_mfma_f32_16x16x32_bf16 v[106:109], v[174:177], v[198:201], v[106:109]
	v_mfma_f32_16x16x32_bf16 v[98:101], v[178:181], v[194:197], v[98:101]
	v_mfma_f32_16x16x32_bf16 v[98:101], v[182:185], v[198:201], v[98:101]
	v_mfma_f32_16x16x32_bf16 v[90:93], v[170:173], v[202:205], v[90:93]
	v_mfma_f32_16x16x32_bf16 v[90:93], v[174:177], v[206:209], v[90:93]
	v_mfma_f32_16x16x32_bf16 v[82:85], v[178:181], v[202:205], v[82:85]
	v_mfma_f32_16x16x32_bf16 v[82:85], v[182:185], v[206:209], v[82:85]
	v_mfma_f32_16x16x32_bf16 v[74:77], v[170:173], v[210:213], v[74:77]
	v_mfma_f32_16x16x32_bf16 v[74:77], v[174:177], v[214:217], v[74:77]
	v_mfma_f32_16x16x32_bf16 v[66:69], v[178:181], v[210:213], v[66:69]
	v_mfma_f32_16x16x32_bf16 v[66:69], v[182:185], v[214:217], v[66:69]
	s_setprio 0
	s_barrier
	s_add_i32 s0, s44, s35
	v_lshl_add_u64 v[218:219], s[2:3], 0, v[134:135]
	s_mov_b32 m0, s0
	ds_read_b128 v[186:189], v168 offset:16384
	ds_read_b128 v[190:193], v168 offset:17408
	ds_read_b128 v[194:197], v168 offset:18432
	ds_read_b128 v[198:201], v168 offset:19456
	ds_read_b128 v[202:205], v168 offset:20480
	ds_read_b128 v[206:209], v168 offset:21504
	ds_read_b128 v[210:213], v168 offset:22528
	ds_read_b128 v[214:217], v168 offset:23552
	global_load_lds_dwordx4 v[218:219], off
	s_add_i32 m0, s0, 0x2000
	s_add_u32 s0, s2, 0x40000
	v_lshl_add_u64 v[220:221], s[2:3], 0, v[130:131]
	s_addc_u32 s1, s3, 0
	s_add_i32 s54, s45, s35
	global_load_lds_dwordx4 v[220:221], off
	v_lshl_add_u64 v[222:223], s[0:1], 0, v[134:135]
	s_mov_b32 m0, s54
	v_lshl_add_u64 v[224:225], s[30:31], 0, v[132:133]
	global_load_lds_dwordx4 v[222:223], off
	v_lshl_add_u64 v[222:223], s[0:1], 0, v[130:131]
	s_add_i32 m0, s54, 0x2000
	s_nop 0
	global_load_lds_dwordx4 v[222:223], off
	v_lshl_add_u64 v[222:223], s[30:31], 0, v[136:137]
	s_mov_b32 m0, s27
	s_nop 0
	global_load_lds_dwordx4 v[222:223], off
	s_mov_b32 m0, s38
	s_nop 0
	global_load_lds_dwordx4 v[224:225], off
	s_waitcnt vmcnt(8)
	s_waitcnt lgkmcnt(0)
	s_barrier
	s_setprio 1
	v_mfma_f32_16x16x32_bf16 v[62:65], v[148:151], v[186:189], v[62:65]
	v_mfma_f32_16x16x32_bf16 v[62:65], v[152:155], v[190:193], v[62:65]
	v_mfma_f32_16x16x32_bf16 v[54:57], v[156:159], v[186:189], v[54:57]
	v_mfma_f32_16x16x32_bf16 v[54:57], v[160:163], v[190:193], v[54:57]
	v_mfma_f32_16x16x32_bf16 v[46:49], v[148:151], v[194:197], v[46:49]
	v_mfma_f32_16x16x32_bf16 v[46:49], v[152:155], v[198:201], v[46:49]
	v_mfma_f32_16x16x32_bf16 v[38:41], v[156:159], v[194:197], v[38:41]
	v_mfma_f32_16x16x32_bf16 v[38:41], v[160:163], v[198:201], v[38:41]
	v_mfma_f32_16x16x32_bf16 v[30:33], v[148:151], v[202:205], v[30:33]
	v_mfma_f32_16x16x32_bf16 v[30:33], v[152:155], v[206:209], v[30:33]
	v_mfma_f32_16x16x32_bf16 v[22:25], v[156:159], v[202:205], v[22:25]
	v_mfma_f32_16x16x32_bf16 v[22:25], v[160:163], v[206:209], v[22:25]
	v_mfma_f32_16x16x32_bf16 v[14:17], v[148:151], v[210:213], v[14:17]
	v_mfma_f32_16x16x32_bf16 v[14:17], v[152:155], v[214:217], v[14:17]
	v_mfma_f32_16x16x32_bf16 v[6:9], v[156:159], v[210:213], v[6:9]
	v_mfma_f32_16x16x32_bf16 v[6:9], v[160:163], v[214:217], v[6:9]
	s_setprio 0
	s_setprio 1
	v_mfma_f32_16x16x32_bf16 v[58:61], v[170:173], v[186:189], v[58:61]
	v_mfma_f32_16x16x32_bf16 v[58:61], v[174:177], v[190:193], v[58:61]
	v_mfma_f32_16x16x32_bf16 v[50:53], v[178:181], v[186:189], v[50:53]
	v_mfma_f32_16x16x32_bf16 v[50:53], v[182:185], v[190:193], v[50:53]
	v_mfma_f32_16x16x32_bf16 v[42:45], v[170:173], v[194:197], v[42:45]
	v_mfma_f32_16x16x32_bf16 v[42:45], v[174:177], v[198:201], v[42:45]
	v_mfma_f32_16x16x32_bf16 v[34:37], v[178:181], v[194:197], v[34:37]
	v_mfma_f32_16x16x32_bf16 v[34:37], v[182:185], v[198:201], v[34:37]
	v_mfma_f32_16x16x32_bf16 v[26:29], v[170:173], v[202:205], v[26:29]
	v_mfma_f32_16x16x32_bf16 v[26:29], v[174:177], v[206:209], v[26:29]
	v_mfma_f32_16x16x32_bf16 v[18:21], v[178:181], v[202:205], v[18:21]
	v_mfma_f32_16x16x32_bf16 v[18:21], v[182:185], v[206:209], v[18:21]
	v_mfma_f32_16x16x32_bf16 v[10:13], v[170:173], v[210:213], v[10:13]
	v_mfma_f32_16x16x32_bf16 v[10:13], v[174:177], v[214:217], v[10:13]
	v_mfma_f32_16x16x32_bf16 v[2:5], v[178:181], v[210:213], v[2:5]
	v_mfma_f32_16x16x32_bf16 v[2:5], v[182:185], v[214:217], v[2:5]
	s_setprio 0
	s_barrier
	s_add_i32 s54, 0, 0x18000
	s_add_i32 s55, 0, 0x1c000
	v_add_u32_e32 v160, s54, v165
	v_add_u32_e32 v182, s55, v165
	ds_read_b128 v[148:151], v160
	ds_read_b128 v[152:155], v160 offset:1024
	ds_read_b128 v[156:159], v160 offset:2048
	ds_read_b128 v[160:163], v160 offset:3072
	ds_read_b128 v[170:173], v182
	ds_read_b128 v[174:177], v182 offset:1024
	ds_read_b128 v[178:181], v182 offset:2048
	ds_read_b128 v[182:185], v182 offset:3072
	s_add_u32 s0, s30, 0x40000
	s_addc_u32 s1, s31, 0
	s_mov_b32 m0, s39
	v_lshl_add_u64 v[226:227], s[0:1], 0, v[136:137]
	ds_read_b128 v[186:189], v168 offset:32768
	ds_read_b128 v[190:193], v168 offset:33792
	ds_read_b128 v[194:197], v168 offset:34816
	ds_read_b128 v[198:201], v168 offset:35840
	ds_read_b128 v[202:205], v168 offset:36864
	ds_read_b128 v[206:209], v168 offset:37888
	ds_read_b128 v[210:213], v168 offset:38912
	ds_read_b128 v[214:217], v168 offset:39936
	global_load_lds_dwordx4 v[226:227], off
	v_lshl_add_u64 v[226:227], s[0:1], 0, v[132:133]
	s_mov_b32 m0, s40
	s_nop 0
	global_load_lds_dwordx4 v[226:227], off
	s_waitcnt vmcnt(8)
	s_waitcnt lgkmcnt(0)
	s_barrier
	s_setprio 1
	v_mfma_f32_16x16x32_bf16 v[126:129], v[148:151], v[186:189], v[126:129]
	v_mfma_f32_16x16x32_bf16 v[126:129], v[152:155], v[190:193], v[126:129]
	v_mfma_f32_16x16x32_bf16 v[118:121], v[156:159], v[186:189], v[118:121]
	v_mfma_f32_16x16x32_bf16 v[118:121], v[160:163], v[190:193], v[118:121]
	v_mfma_f32_16x16x32_bf16 v[110:113], v[148:151], v[194:197], v[110:113]
	v_mfma_f32_16x16x32_bf16 v[110:113], v[152:155], v[198:201], v[110:113]
	v_mfma_f32_16x16x32_bf16 v[102:105], v[156:159], v[194:197], v[102:105]
	v_mfma_f32_16x16x32_bf16 v[102:105], v[160:163], v[198:201], v[102:105]
	v_mfma_f32_16x16x32_bf16 v[94:97], v[148:151], v[202:205], v[94:97]
	v_mfma_f32_16x16x32_bf16 v[94:97], v[152:155], v[206:209], v[94:97]
	v_mfma_f32_16x16x32_bf16 v[86:89], v[156:159], v[202:205], v[86:89]
	v_mfma_f32_16x16x32_bf16 v[86:89], v[160:163], v[206:209], v[86:89]
	v_mfma_f32_16x16x32_bf16 v[78:81], v[148:151], v[210:213], v[78:81]
	v_mfma_f32_16x16x32_bf16 v[78:81], v[152:155], v[214:217], v[78:81]
	v_mfma_f32_16x16x32_bf16 v[70:73], v[156:159], v[210:213], v[70:73]
	v_mfma_f32_16x16x32_bf16 v[70:73], v[160:163], v[214:217], v[70:73]
	s_setprio 0
	s_setprio 1
	v_mfma_f32_16x16x32_bf16 v[122:125], v[170:173], v[186:189], v[122:125]
	v_mfma_f32_16x16x32_bf16 v[122:125], v[174:177], v[190:193], v[122:125]
	v_mfma_f32_16x16x32_bf16 v[114:117], v[178:181], v[186:189], v[114:117]
	v_mfma_f32_16x16x32_bf16 v[114:117], v[182:185], v[190:193], v[114:117]
	v_mfma_f32_16x16x32_bf16 v[106:109], v[170:173], v[194:197], v[106:109]
	v_mfma_f32_16x16x32_bf16 v[106:109], v[174:177], v[198:201], v[106:109]
	v_mfma_f32_16x16x32_bf16 v[98:101], v[178:181], v[194:197], v[98:101]
	v_mfma_f32_16x16x32_bf16 v[98:101], v[182:185], v[198:201], v[98:101]
	v_mfma_f32_16x16x32_bf16 v[90:93], v[170:173], v[202:205], v[90:93]
	v_mfma_f32_16x16x32_bf16 v[90:93], v[174:177], v[206:209], v[90:93]
	v_mfma_f32_16x16x32_bf16 v[82:85], v[178:181], v[202:205], v[82:85]
	v_mfma_f32_16x16x32_bf16 v[82:85], v[182:185], v[206:209], v[82:85]
	v_mfma_f32_16x16x32_bf16 v[74:77], v[170:173], v[210:213], v[74:77]
	v_mfma_f32_16x16x32_bf16 v[74:77], v[174:177], v[214:217], v[74:77]
	v_mfma_f32_16x16x32_bf16 v[66:69], v[178:181], v[210:213], v[66:69]
	v_mfma_f32_16x16x32_bf16 v[66:69], v[182:185], v[214:217], v[66:69]
	s_setprio 0
	s_barrier
	s_add_i32 s0, s54, s35
	v_lshl_add_u64 v[218:219], v[218:219], 0, s[14:15]
	s_mov_b32 m0, s0
	ds_read_b128 v[186:189], v168 offset:49152
	ds_read_b128 v[190:193], v168 offset:50176
	ds_read_b128 v[194:197], v168 offset:51200
	ds_read_b128 v[198:201], v168 offset:52224
	ds_read_b128 v[202:205], v168 offset:53248
	ds_read_b128 v[206:209], v168 offset:54272
	ds_read_b128 v[210:213], v168 offset:55296
	ds_read_b128 v[214:217], v168 offset:56320
	global_load_lds_dwordx4 v[218:219], off
	s_add_i32 m0, s0, 0x2000
	s_add_u32 s0, s2, 0x40080
	v_lshl_add_u64 v[218:219], v[220:221], 0, s[14:15]
	s_addc_u32 s1, s3, 0
	s_add_i32 s2, s55, s35
	global_load_lds_dwordx4 v[218:219], off
	v_lshl_add_u64 v[218:219], s[0:1], 0, v[134:135]
	s_mov_b32 m0, s2
	s_nop 0
	global_load_lds_dwordx4 v[218:219], off
	v_lshl_add_u64 v[218:219], s[0:1], 0, v[130:131]
	s_add_i32 m0, s2, 0x2000
	s_nop 0
	global_load_lds_dwordx4 v[218:219], off
	v_lshl_add_u64 v[218:219], v[222:223], 0, s[14:15]
	s_mov_b32 m0, s41
	s_nop 0
	global_load_lds_dwordx4 v[218:219], off
	v_lshl_add_u64 v[218:219], v[224:225], 0, s[14:15]
	s_mov_b32 m0, s42
	s_nop 0
	global_load_lds_dwordx4 v[218:219], off
	s_waitcnt vmcnt(8)
	s_waitcnt lgkmcnt(0)
	s_barrier
	s_setprio 1
	v_mfma_f32_16x16x32_bf16 v[62:65], v[148:151], v[186:189], v[62:65]
	v_mfma_f32_16x16x32_bf16 v[62:65], v[152:155], v[190:193], v[62:65]
	v_mfma_f32_16x16x32_bf16 v[54:57], v[156:159], v[186:189], v[54:57]
	v_mfma_f32_16x16x32_bf16 v[54:57], v[160:163], v[190:193], v[54:57]
	v_mfma_f32_16x16x32_bf16 v[46:49], v[148:151], v[194:197], v[46:49]
	v_mfma_f32_16x16x32_bf16 v[46:49], v[152:155], v[198:201], v[46:49]
	v_mfma_f32_16x16x32_bf16 v[38:41], v[156:159], v[194:197], v[38:41]
	v_mfma_f32_16x16x32_bf16 v[38:41], v[160:163], v[198:201], v[38:41]
	v_mfma_f32_16x16x32_bf16 v[30:33], v[148:151], v[202:205], v[30:33]
	v_mfma_f32_16x16x32_bf16 v[30:33], v[152:155], v[206:209], v[30:33]
	v_mfma_f32_16x16x32_bf16 v[22:25], v[156:159], v[202:205], v[22:25]
	v_mfma_f32_16x16x32_bf16 v[22:25], v[160:163], v[206:209], v[22:25]
	v_mfma_f32_16x16x32_bf16 v[14:17], v[148:151], v[210:213], v[14:17]
	v_mfma_f32_16x16x32_bf16 v[14:17], v[152:155], v[214:217], v[14:17]
	v_mfma_f32_16x16x32_bf16 v[6:9], v[156:159], v[210:213], v[6:9]
	v_mfma_f32_16x16x32_bf16 v[6:9], v[160:163], v[214:217], v[6:9]
	s_setprio 0
	s_setprio 1
	v_mfma_f32_16x16x32_bf16 v[58:61], v[170:173], v[186:189], v[58:61]
	s_add_i32 s53, s53, 2
	s_add_u32 s28, s28, 0x100
	s_addc_u32 s29, s29, 0
	s_add_u32 s51, s51, 0x100
	s_addc_u32 s52, s52, 0
	s_cmp_gt_u32 s53, 13
	v_mfma_f32_16x16x32_bf16 v[58:61], v[174:177], v[190:193], v[58:61]
	v_mfma_f32_16x16x32_bf16 v[50:53], v[178:181], v[186:189], v[50:53]
	v_mfma_f32_16x16x32_bf16 v[50:53], v[182:185], v[190:193], v[50:53]
	v_mfma_f32_16x16x32_bf16 v[42:45], v[170:173], v[194:197], v[42:45]
	v_mfma_f32_16x16x32_bf16 v[42:45], v[174:177], v[198:201], v[42:45]
	v_mfma_f32_16x16x32_bf16 v[34:37], v[178:181], v[194:197], v[34:37]
	v_mfma_f32_16x16x32_bf16 v[34:37], v[182:185], v[198:201], v[34:37]
	v_mfma_f32_16x16x32_bf16 v[26:29], v[170:173], v[202:205], v[26:29]
	v_mfma_f32_16x16x32_bf16 v[26:29], v[174:177], v[206:209], v[26:29]
	v_mfma_f32_16x16x32_bf16 v[18:21], v[178:181], v[202:205], v[18:21]
	v_mfma_f32_16x16x32_bf16 v[18:21], v[182:185], v[206:209], v[18:21]
	v_mfma_f32_16x16x32_bf16 v[10:13], v[170:173], v[210:213], v[10:13]
	v_mfma_f32_16x16x32_bf16 v[10:13], v[174:177], v[214:217], v[10:13]
	v_mfma_f32_16x16x32_bf16 v[2:5], v[178:181], v[210:213], v[2:5]
	v_mfma_f32_16x16x32_bf16 v[2:5], v[182:185], v[214:217], v[2:5]
	s_setprio 0
	s_barrier
	s_cbranch_scc0 .LBB0_1715
	s_and_b64 vcc, exec, s[16:17]
	s_cbranch_vccz .LBB0_1718
	s_barrier

.LBB0_1841:
	ds_read_b128 v[130:133], v186
	ds_read_b128 v[134:137], v186 offset:1024
	ds_read_b128 v[138:141], v186 offset:2048
	ds_read_b128 v[142:145], v186 offset:3072
	ds_read_b128 v[146:149], v187
	ds_read_b128 v[150:153], v187 offset:1024
	ds_read_b128 v[170:173], v187 offset:2048
	ds_read_b128 v[174:177], v187 offset:3072
	s_add_u32 s0, s30, 0xfff50080
	s_addc_u32 s1, s31, -1
	s_cmp_eq_u32 s55, 40
	s_cselect_b32 s35, s9, s1
	s_cselect_b32 s34, s8, s0
	s_cselect_b32 s3, s29, s54
	s_cselect_b32 s2, s28, s53
	v_lshl_add_u64 v[218:219], s[30:31], 0, v[162:163]
	s_add_i32 m0, s40, 0xc000
	ds_read_b128 v[178:181], v188
	ds_read_b128 v[190:193], v188 offset:1024
	ds_read_b128 v[194:197], v188 offset:2048
	ds_read_b128 v[198:201], v188 offset:3072
	ds_read_b128 v[202:205], v188 offset:4096
	ds_read_b128 v[206:209], v188 offset:5120
	ds_read_b128 v[210:213], v188 offset:6144
	ds_read_b128 v[214:217], v188 offset:7168
	global_load_lds_dwordx4 v[218:219], off
	v_lshl_add_u64 v[218:219], s[30:31], 0, v[164:165]
	s_add_i32 m0, s40, 0xe000
	s_nop 0
	global_load_lds_dwordx4 v[218:219], off
	s_waitcnt vmcnt(8)
	s_waitcnt lgkmcnt(0)
	s_barrier
	s_setprio 1
	v_mfma_f32_16x16x32_bf16 v[126:129], v[130:133], v[178:181], v[126:129]
	v_mfma_f32_16x16x32_bf16 v[126:129], v[134:137], v[190:193], v[126:129]
	v_mfma_f32_16x16x32_bf16 v[122:125], v[138:141], v[178:181], v[122:125]
	v_mfma_f32_16x16x32_bf16 v[122:125], v[142:145], v[190:193], v[122:125]
	v_mfma_f32_16x16x32_bf16 v[110:113], v[130:133], v[194:197], v[110:113]
	v_mfma_f32_16x16x32_bf16 v[110:113], v[134:137], v[198:201], v[110:113]
	v_mfma_f32_16x16x32_bf16 v[106:109], v[138:141], v[194:197], v[106:109]
	v_mfma_f32_16x16x32_bf16 v[106:109], v[142:145], v[198:201], v[106:109]
	v_mfma_f32_16x16x32_bf16 v[94:97], v[130:133], v[202:205], v[94:97]
	v_mfma_f32_16x16x32_bf16 v[94:97], v[134:137], v[206:209], v[94:97]
	v_mfma_f32_16x16x32_bf16 v[90:93], v[138:141], v[202:205], v[90:93]
	v_mfma_f32_16x16x32_bf16 v[90:93], v[142:145], v[206:209], v[90:93]
	v_mfma_f32_16x16x32_bf16 v[78:81], v[130:133], v[210:213], v[78:81]
	v_mfma_f32_16x16x32_bf16 v[78:81], v[134:137], v[214:217], v[78:81]
	v_mfma_f32_16x16x32_bf16 v[74:77], v[138:141], v[210:213], v[74:77]
	v_mfma_f32_16x16x32_bf16 v[74:77], v[142:145], v[214:217], v[74:77]
	s_setprio 0
	s_setprio 1
	v_mfma_f32_16x16x32_bf16 v[118:121], v[146:149], v[178:181], v[118:121]
	v_mfma_f32_16x16x32_bf16 v[118:121], v[150:153], v[190:193], v[118:121]
	v_mfma_f32_16x16x32_bf16 v[114:117], v[170:173], v[178:181], v[114:117]
	v_mfma_f32_16x16x32_bf16 v[114:117], v[174:177], v[190:193], v[114:117]
	v_mfma_f32_16x16x32_bf16 v[102:105], v[146:149], v[194:197], v[102:105]
	v_mfma_f32_16x16x32_bf16 v[102:105], v[150:153], v[198:201], v[102:105]
	v_mfma_f32_16x16x32_bf16 v[98:101], v[170:173], v[194:197], v[98:101]
	v_mfma_f32_16x16x32_bf16 v[98:101], v[174:177], v[198:201], v[98:101]
	v_mfma_f32_16x16x32_bf16 v[86:89], v[146:149], v[202:205], v[86:89]
	v_mfma_f32_16x16x32_bf16 v[86:89], v[150:153], v[206:209], v[86:89]
	v_mfma_f32_16x16x32_bf16 v[82:85], v[170:173], v[202:205], v[82:85]
	v_mfma_f32_16x16x32_bf16 v[82:85], v[174:177], v[206:209], v[82:85]
	v_mfma_f32_16x16x32_bf16 v[70:73], v[146:149], v[210:213], v[70:73]
	v_mfma_f32_16x16x32_bf16 v[70:73], v[150:153], v[214:217], v[70:73]
	v_mfma_f32_16x16x32_bf16 v[66:69], v[170:173], v[210:213], v[66:69]
	v_mfma_f32_16x16x32_bf16 v[66:69], v[174:177], v[214:217], v[66:69]
	s_setprio 0
	s_barrier
	s_add_i32 s0, s49, s39
	v_lshl_add_u64 v[218:219], s[2:3], 0, v[156:157]
	s_mov_b32 m0, s0
	ds_read_b128 v[178:181], v188 offset:16384
	ds_read_b128 v[190:193], v188 offset:17408
	ds_read_b128 v[194:197], v188 offset:18432
	ds_read_b128 v[198:201], v188 offset:19456
	ds_read_b128 v[202:205], v188 offset:20480
	ds_read_b128 v[206:209], v188 offset:21504
	ds_read_b128 v[210:213], v188 offset:22528
	ds_read_b128 v[214:217], v188 offset:23552
	global_load_lds_dwordx4 v[218:219], off
	s_add_i32 m0, s0, 0x2000
	s_add_u32 s0, s2, 0xb0000
	v_lshl_add_u64 v[220:221], s[2:3], 0, v[160:161]
	s_addc_u32 s1, s3, 0
	s_add_i32 s56, s50, s39
	global_load_lds_dwordx4 v[220:221], off
	v_lshl_add_u64 v[222:223], s[0:1], 0, v[156:157]
	s_mov_b32 m0, s56
	v_lshl_add_u64 v[224:225], s[34:35], 0, v[158:159]
	global_load_lds_dwordx4 v[222:223], off
	v_lshl_add_u64 v[222:223], s[0:1], 0, v[160:161]
	s_add_i32 m0, s56, 0x2000
	s_nop 0
	global_load_lds_dwordx4 v[222:223], off
	v_lshl_add_u64 v[222:223], s[34:35], 0, v[154:155]
	s_mov_b32 m0, s40
	s_nop 0
	global_load_lds_dwordx4 v[222:223], off
	s_mov_b32 m0, s41
	s_nop 0
	global_load_lds_dwordx4 v[224:225], off
	s_waitcnt vmcnt(8)
	s_waitcnt lgkmcnt(0)
	s_barrier
	s_setprio 1
	v_mfma_f32_16x16x32_bf16 v[62:65], v[130:133], v[178:181], v[62:65]
	v_mfma_f32_16x16x32_bf16 v[62:65], v[134:137], v[190:193], v[62:65]
	v_mfma_f32_16x16x32_bf16 v[58:61], v[138:141], v[178:181], v[58:61]
	v_mfma_f32_16x16x32_bf16 v[58:61], v[142:145], v[190:193], v[58:61]
	v_mfma_f32_16x16x32_bf16 v[46:49], v[130:133], v[194:197], v[46:49]
	v_mfma_f32_16x16x32_bf16 v[46:49], v[134:137], v[198:201], v[46:49]
	v_mfma_f32_16x16x32_bf16 v[42:45], v[138:141], v[194:197], v[42:45]
	v_mfma_f32_16x16x32_bf16 v[42:45], v[142:145], v[198:201], v[42:45]
	v_mfma_f32_16x16x32_bf16 v[30:33], v[130:133], v[202:205], v[30:33]
	v_mfma_f32_16x16x32_bf16 v[30:33], v[134:137], v[206:209], v[30:33]
	v_mfma_f32_16x16x32_bf16 v[26:29], v[138:141], v[202:205], v[26:29]
	v_mfma_f32_16x16x32_bf16 v[26:29], v[142:145], v[206:209], v[26:29]
	v_mfma_f32_16x16x32_bf16 v[14:17], v[130:133], v[210:213], v[14:17]
	v_mfma_f32_16x16x32_bf16 v[14:17], v[134:137], v[214:217], v[14:17]
	v_mfma_f32_16x16x32_bf16 v[10:13], v[138:141], v[210:213], v[10:13]
	v_mfma_f32_16x16x32_bf16 v[10:13], v[142:145], v[214:217], v[10:13]
	s_setprio 0
	s_setprio 1
	v_mfma_f32_16x16x32_bf16 v[54:57], v[146:149], v[178:181], v[54:57]
	v_mfma_f32_16x16x32_bf16 v[54:57], v[150:153], v[190:193], v[54:57]
	v_mfma_f32_16x16x32_bf16 v[50:53], v[170:173], v[178:181], v[50:53]
	v_mfma_f32_16x16x32_bf16 v[50:53], v[174:177], v[190:193], v[50:53]
	v_mfma_f32_16x16x32_bf16 v[38:41], v[146:149], v[194:197], v[38:41]
	v_mfma_f32_16x16x32_bf16 v[38:41], v[150:153], v[198:201], v[38:41]
	v_mfma_f32_16x16x32_bf16 v[34:37], v[170:173], v[194:197], v[34:37]
	v_mfma_f32_16x16x32_bf16 v[34:37], v[174:177], v[198:201], v[34:37]
	v_mfma_f32_16x16x32_bf16 v[22:25], v[146:149], v[202:205], v[22:25]
	v_mfma_f32_16x16x32_bf16 v[22:25], v[150:153], v[206:209], v[22:25]
	v_mfma_f32_16x16x32_bf16 v[18:21], v[170:173], v[202:205], v[18:21]
	v_mfma_f32_16x16x32_bf16 v[18:21], v[174:177], v[206:209], v[18:21]
	v_mfma_f32_16x16x32_bf16 v[6:9], v[146:149], v[210:213], v[6:9]
	v_mfma_f32_16x16x32_bf16 v[6:9], v[150:153], v[214:217], v[6:9]
	v_mfma_f32_16x16x32_bf16 v[2:5], v[170:173], v[210:213], v[2:5]
	v_mfma_f32_16x16x32_bf16 v[2:5], v[174:177], v[214:217], v[2:5]
	s_setprio 0
	s_barrier
	s_add_i32 s56, 0, 0x18000
	s_add_i32 s57, 0, 0x1c000
	v_add_u32_e32 v142, s56, v182
	v_add_u32_e32 v174, s57, v182
	ds_read_b128 v[130:133], v142
	ds_read_b128 v[134:137], v142 offset:1024
	ds_read_b128 v[138:141], v142 offset:2048
	ds_read_b128 v[142:145], v142 offset:3072
	ds_read_b128 v[146:149], v174
	ds_read_b128 v[150:153], v174 offset:1024
	ds_read_b128 v[170:173], v174 offset:2048
	ds_read_b128 v[174:177], v174 offset:3072
	s_add_u32 s0, s34, 0xb0000
	s_addc_u32 s1, s35, 0
	s_mov_b32 m0, s42
	v_lshl_add_u64 v[226:227], s[0:1], 0, v[154:155]
	ds_read_b128 v[178:181], v188 offset:32768
	ds_read_b128 v[190:193], v188 offset:33792
	ds_read_b128 v[194:197], v188 offset:34816
	ds_read_b128 v[198:201], v188 offset:35840
	ds_read_b128 v[202:205], v188 offset:36864
	ds_read_b128 v[206:209], v188 offset:37888
	ds_read_b128 v[210:213], v188 offset:38912
	ds_read_b128 v[214:217], v188 offset:39936
	global_load_lds_dwordx4 v[226:227], off
	v_lshl_add_u64 v[226:227], s[0:1], 0, v[158:159]
	s_mov_b32 m0, s43
	s_nop 0
	global_load_lds_dwordx4 v[226:227], off
	s_waitcnt vmcnt(8)
	s_waitcnt lgkmcnt(0)
	s_barrier
	s_setprio 1
	v_mfma_f32_16x16x32_bf16 v[126:129], v[130:133], v[178:181], v[126:129]
	v_mfma_f32_16x16x32_bf16 v[126:129], v[134:137], v[190:193], v[126:129]
	v_mfma_f32_16x16x32_bf16 v[122:125], v[138:141], v[178:181], v[122:125]
	v_mfma_f32_16x16x32_bf16 v[122:125], v[142:145], v[190:193], v[122:125]
	v_mfma_f32_16x16x32_bf16 v[110:113], v[130:133], v[194:197], v[110:113]
	v_mfma_f32_16x16x32_bf16 v[110:113], v[134:137], v[198:201], v[110:113]
	v_mfma_f32_16x16x32_bf16 v[106:109], v[138:141], v[194:197], v[106:109]
	v_mfma_f32_16x16x32_bf16 v[106:109], v[142:145], v[198:201], v[106:109]
	v_mfma_f32_16x16x32_bf16 v[94:97], v[130:133], v[202:205], v[94:97]
	v_mfma_f32_16x16x32_bf16 v[94:97], v[134:137], v[206:209], v[94:97]
	v_mfma_f32_16x16x32_bf16 v[90:93], v[138:141], v[202:205], v[90:93]
	v_mfma_f32_16x16x32_bf16 v[90:93], v[142:145], v[206:209], v[90:93]
	v_mfma_f32_16x16x32_bf16 v[78:81], v[130:133], v[210:213], v[78:81]
	v_mfma_f32_16x16x32_bf16 v[78:81], v[134:137], v[214:217], v[78:81]
	v_mfma_f32_16x16x32_bf16 v[74:77], v[138:141], v[210:213], v[74:77]
	v_mfma_f32_16x16x32_bf16 v[74:77], v[142:145], v[214:217], v[74:77]
	s_setprio 0
	s_setprio 1
	v_mfma_f32_16x16x32_bf16 v[118:121], v[146:149], v[178:181], v[118:121]
	v_mfma_f32_16x16x32_bf16 v[118:121], v[150:153], v[190:193], v[118:121]
	v_mfma_f32_16x16x32_bf16 v[114:117], v[170:173], v[178:181], v[114:117]
	v_mfma_f32_16x16x32_bf16 v[114:117], v[174:177], v[190:193], v[114:117]
	v_mfma_f32_16x16x32_bf16 v[102:105], v[146:149], v[194:197], v[102:105]
	v_mfma_f32_16x16x32_bf16 v[102:105], v[150:153], v[198:201], v[102:105]
	v_mfma_f32_16x16x32_bf16 v[98:101], v[170:173], v[194:197], v[98:101]
	v_mfma_f32_16x16x32_bf16 v[98:101], v[174:177], v[198:201], v[98:101]
	v_mfma_f32_16x16x32_bf16 v[86:89], v[146:149], v[202:205], v[86:89]
	v_mfma_f32_16x16x32_bf16 v[86:89], v[150:153], v[206:209], v[86:89]
	v_mfma_f32_16x16x32_bf16 v[82:85], v[170:173], v[202:205], v[82:85]
	v_mfma_f32_16x16x32_bf16 v[82:85], v[174:177], v[206:209], v[82:85]
	v_mfma_f32_16x16x32_bf16 v[70:73], v[146:149], v[210:213], v[70:73]
	v_mfma_f32_16x16x32_bf16 v[70:73], v[150:153], v[214:217], v[70:73]
	v_mfma_f32_16x16x32_bf16 v[66:69], v[170:173], v[210:213], v[66:69]
	v_mfma_f32_16x16x32_bf16 v[66:69], v[174:177], v[214:217], v[66:69]
	s_setprio 0
	s_barrier
	s_add_i32 s0, s56, s39
	v_lshl_add_u64 v[218:219], v[218:219], 0, s[16:17]
	s_mov_b32 m0, s0
	ds_read_b128 v[178:181], v188 offset:49152
	ds_read_b128 v[190:193], v188 offset:50176
	ds_read_b128 v[194:197], v188 offset:51200
	ds_read_b128 v[198:201], v188 offset:52224
	ds_read_b128 v[202:205], v188 offset:53248
	ds_read_b128 v[206:209], v188 offset:54272
	ds_read_b128 v[210:213], v188 offset:55296
	ds_read_b128 v[214:217], v188 offset:56320
	global_load_lds_dwordx4 v[218:219], off
	s_add_i32 m0, s0, 0x2000
	s_add_u32 s0, s2, 0xb0080
	v_lshl_add_u64 v[218:219], v[220:221], 0, s[16:17]
	s_addc_u32 s1, s3, 0
	s_add_i32 s2, s57, s39
	global_load_lds_dwordx4 v[218:219], off
	v_lshl_add_u64 v[218:219], s[0:1], 0, v[156:157]
	s_mov_b32 m0, s2
	s_nop 0
	global_load_lds_dwordx4 v[218:219], off
	v_lshl_add_u64 v[218:219], s[0:1], 0, v[160:161]
	s_add_i32 m0, s2, 0x2000
	s_nop 0
	global_load_lds_dwordx4 v[218:219], off
	v_lshl_add_u64 v[218:219], v[222:223], 0, s[16:17]
	s_mov_b32 m0, s45
	s_nop 0
	global_load_lds_dwordx4 v[218:219], off
	v_lshl_add_u64 v[218:219], v[224:225], 0, s[16:17]
	s_mov_b32 m0, s46
	s_nop 0
	global_load_lds_dwordx4 v[218:219], off
	s_waitcnt vmcnt(8)
	s_waitcnt lgkmcnt(0)
	s_barrier
	s_setprio 1
	v_mfma_f32_16x16x32_bf16 v[62:65], v[130:133], v[178:181], v[62:65]
	v_mfma_f32_16x16x32_bf16 v[62:65], v[134:137], v[190:193], v[62:65]
	v_mfma_f32_16x16x32_bf16 v[58:61], v[138:141], v[178:181], v[58:61]
	v_mfma_f32_16x16x32_bf16 v[58:61], v[142:145], v[190:193], v[58:61]
	v_mfma_f32_16x16x32_bf16 v[46:49], v[130:133], v[194:197], v[46:49]
	v_mfma_f32_16x16x32_bf16 v[46:49], v[134:137], v[198:201], v[46:49]
	v_mfma_f32_16x16x32_bf16 v[42:45], v[138:141], v[194:197], v[42:45]
	v_mfma_f32_16x16x32_bf16 v[42:45], v[142:145], v[198:201], v[42:45]
	v_mfma_f32_16x16x32_bf16 v[30:33], v[130:133], v[202:205], v[30:33]
	v_mfma_f32_16x16x32_bf16 v[30:33], v[134:137], v[206:209], v[30:33]
	v_mfma_f32_16x16x32_bf16 v[26:29], v[138:141], v[202:205], v[26:29]
	v_mfma_f32_16x16x32_bf16 v[26:29], v[142:145], v[206:209], v[26:29]
	v_mfma_f32_16x16x32_bf16 v[14:17], v[130:133], v[210:213], v[14:17]
	v_mfma_f32_16x16x32_bf16 v[14:17], v[134:137], v[214:217], v[14:17]
	v_mfma_f32_16x16x32_bf16 v[10:13], v[138:141], v[210:213], v[10:13]
	v_mfma_f32_16x16x32_bf16 v[10:13], v[142:145], v[214:217], v[10:13]
	s_setprio 0
	s_setprio 1
	v_mfma_f32_16x16x32_bf16 v[54:57], v[146:149], v[178:181], v[54:57]
	s_add_i32 s55, s55, 2
	s_add_u32 s30, s30, 0x100
	s_addc_u32 s31, s31, 0
	s_add_u32 s53, s53, 0x100
	s_addc_u32 s54, s54, 0
	s_cmp_gt_u32 s55, 41
	v_mfma_f32_16x16x32_bf16 v[54:57], v[150:153], v[190:193], v[54:57]
	v_mfma_f32_16x16x32_bf16 v[50:53], v[170:173], v[178:181], v[50:53]
	v_mfma_f32_16x16x32_bf16 v[50:53], v[174:177], v[190:193], v[50:53]
	v_mfma_f32_16x16x32_bf16 v[38:41], v[146:149], v[194:197], v[38:41]
	v_mfma_f32_16x16x32_bf16 v[38:41], v[150:153], v[198:201], v[38:41]
	v_mfma_f32_16x16x32_bf16 v[34:37], v[170:173], v[194:197], v[34:37]
	v_mfma_f32_16x16x32_bf16 v[34:37], v[174:177], v[198:201], v[34:37]
	v_mfma_f32_16x16x32_bf16 v[22:25], v[146:149], v[202:205], v[22:25]
	v_mfma_f32_16x16x32_bf16 v[22:25], v[150:153], v[206:209], v[22:25]
	v_mfma_f32_16x16x32_bf16 v[18:21], v[170:173], v[202:205], v[18:21]
	v_mfma_f32_16x16x32_bf16 v[18:21], v[174:177], v[206:209], v[18:21]
	v_mfma_f32_16x16x32_bf16 v[6:9], v[146:149], v[210:213], v[6:9]
	v_mfma_f32_16x16x32_bf16 v[6:9], v[150:153], v[214:217], v[6:9]
	v_mfma_f32_16x16x32_bf16 v[2:5], v[170:173], v[210:213], v[2:5]
	v_mfma_f32_16x16x32_bf16 v[2:5], v[174:177], v[214:217], v[2:5]
	s_setprio 0
	s_barrier
	s_cbranch_scc0 .LBB0_1841
	s_and_b64 vcc, exec, s[18:19]
	s_cbranch_vccz .LBB0_1844
	s_barrier

.LBB0_1938:
	ds_read_b128 v[148:151], v161
	ds_read_b128 v[152:155], v161 offset:1024
	ds_read_b128 v[156:159], v161 offset:2048
	ds_read_b128 v[166:169], v161 offset:3072
	ds_read_b128 v[170:173], v162
	ds_read_b128 v[174:177], v162 offset:1024
	ds_read_b128 v[178:181], v162 offset:2048
	ds_read_b128 v[182:185], v162 offset:3072
	s_add_u32 s0, s28, 0xfffc0080
	s_addc_u32 s1, s29, -1
	s_cmp_eq_u32 s51, 12
	s_cselect_b32 s31, s21, s1
	s_cselect_b32 s30, s47, s0
	s_cselect_b32 s3, s19, s50
	s_cselect_b32 s2, s48, s49
	v_lshl_add_u64 v[218:219], s[28:29], 0, v[140:141]
	s_add_i32 m0, s27, 0xc000
	ds_read_b128 v[186:189], v163
	ds_read_b128 v[190:193], v163 offset:1024
	ds_read_b128 v[194:197], v163 offset:2048
	ds_read_b128 v[198:201], v163 offset:3072
	ds_read_b128 v[202:205], v163 offset:4096
	ds_read_b128 v[206:209], v163 offset:5120
	ds_read_b128 v[210:213], v163 offset:6144
	ds_read_b128 v[214:217], v163 offset:7168
	global_load_lds_dwordx4 v[218:219], off
	v_lshl_add_u64 v[218:219], s[28:29], 0, v[142:143]
	s_add_i32 m0, s27, 0xe000
	s_nop 0
	global_load_lds_dwordx4 v[218:219], off
	s_waitcnt vmcnt(8)
	s_waitcnt lgkmcnt(0)
	s_barrier
	s_setprio 1
	v_mfma_f32_16x16x32_bf16 v[126:129], v[148:151], v[186:189], v[126:129]
	v_mfma_f32_16x16x32_bf16 v[126:129], v[152:155], v[190:193], v[126:129]
	v_mfma_f32_16x16x32_bf16 v[118:121], v[156:159], v[186:189], v[118:121]
	v_mfma_f32_16x16x32_bf16 v[118:121], v[166:169], v[190:193], v[118:121]
	v_mfma_f32_16x16x32_bf16 v[110:113], v[148:151], v[194:197], v[110:113]
	v_mfma_f32_16x16x32_bf16 v[110:113], v[152:155], v[198:201], v[110:113]
	v_mfma_f32_16x16x32_bf16 v[106:109], v[156:159], v[194:197], v[106:109]
	v_mfma_f32_16x16x32_bf16 v[106:109], v[166:169], v[198:201], v[106:109]
	v_mfma_f32_16x16x32_bf16 v[94:97], v[148:151], v[202:205], v[94:97]
	v_mfma_f32_16x16x32_bf16 v[94:97], v[152:155], v[206:209], v[94:97]
	v_mfma_f32_16x16x32_bf16 v[90:93], v[156:159], v[202:205], v[90:93]
	v_mfma_f32_16x16x32_bf16 v[90:93], v[166:169], v[206:209], v[90:93]
	v_mfma_f32_16x16x32_bf16 v[78:81], v[148:151], v[210:213], v[78:81]
	v_mfma_f32_16x16x32_bf16 v[78:81], v[152:155], v[214:217], v[78:81]
	v_mfma_f32_16x16x32_bf16 v[74:77], v[156:159], v[210:213], v[74:77]
	v_mfma_f32_16x16x32_bf16 v[74:77], v[166:169], v[214:217], v[74:77]
	s_setprio 0
	s_setprio 1
	v_mfma_f32_16x16x32_bf16 v[122:125], v[170:173], v[186:189], v[122:125]
	v_mfma_f32_16x16x32_bf16 v[122:125], v[174:177], v[190:193], v[122:125]
	v_mfma_f32_16x16x32_bf16 v[114:117], v[178:181], v[186:189], v[114:117]
	v_mfma_f32_16x16x32_bf16 v[114:117], v[182:185], v[190:193], v[114:117]
	v_mfma_f32_16x16x32_bf16 v[102:105], v[170:173], v[194:197], v[102:105]
	v_mfma_f32_16x16x32_bf16 v[102:105], v[174:177], v[198:201], v[102:105]
	v_mfma_f32_16x16x32_bf16 v[98:101], v[178:181], v[194:197], v[98:101]
	v_mfma_f32_16x16x32_bf16 v[98:101], v[182:185], v[198:201], v[98:101]
	v_mfma_f32_16x16x32_bf16 v[86:89], v[170:173], v[202:205], v[86:89]
	v_mfma_f32_16x16x32_bf16 v[86:89], v[174:177], v[206:209], v[86:89]
	v_mfma_f32_16x16x32_bf16 v[82:85], v[178:181], v[202:205], v[82:85]
	v_mfma_f32_16x16x32_bf16 v[82:85], v[182:185], v[206:209], v[82:85]
	v_mfma_f32_16x16x32_bf16 v[70:73], v[170:173], v[210:213], v[70:73]
	v_mfma_f32_16x16x32_bf16 v[70:73], v[174:177], v[214:217], v[70:73]
	v_mfma_f32_16x16x32_bf16 v[66:69], v[178:181], v[210:213], v[66:69]
	v_mfma_f32_16x16x32_bf16 v[66:69], v[182:185], v[214:217], v[66:69]
	s_setprio 0
	s_barrier
	s_add_i32 s0, s43, s36
	v_lshl_add_u64 v[218:219], s[2:3], 0, v[132:133]
	s_mov_b32 m0, s0
	ds_read_b128 v[186:189], v163 offset:16384
	ds_read_b128 v[190:193], v163 offset:17408
	ds_read_b128 v[194:197], v163 offset:18432
	ds_read_b128 v[198:201], v163 offset:19456
	ds_read_b128 v[202:205], v163 offset:20480
	ds_read_b128 v[206:209], v163 offset:21504
	ds_read_b128 v[210:213], v163 offset:22528
	ds_read_b128 v[214:217], v163 offset:23552
	global_load_lds_dwordx4 v[218:219], off
	s_add_i32 m0, s0, 0x2000
	s_add_u32 s0, s2, 0x40000
	v_lshl_add_u64 v[220:221], s[2:3], 0, v[136:137]
	s_addc_u32 s1, s3, 0
	s_add_i32 s52, s44, s36
	global_load_lds_dwordx4 v[220:221], off
	v_lshl_add_u64 v[222:223], s[0:1], 0, v[132:133]
	s_mov_b32 m0, s52
	v_lshl_add_u64 v[224:225], s[30:31], 0, v[134:135]
	global_load_lds_dwordx4 v[222:223], off
	v_lshl_add_u64 v[222:223], s[0:1], 0, v[136:137]
	s_add_i32 m0, s52, 0x2000
	s_nop 0
	global_load_lds_dwordx4 v[222:223], off
	v_lshl_add_u64 v[222:223], s[30:31], 0, v[130:131]
	s_mov_b32 m0, s27
	s_nop 0
	global_load_lds_dwordx4 v[222:223], off
	s_mov_b32 m0, s37
	s_nop 0
	global_load_lds_dwordx4 v[224:225], off
	s_waitcnt vmcnt(8)
	s_waitcnt lgkmcnt(0)
	s_barrier
	s_setprio 1
	v_mfma_f32_16x16x32_bf16 v[62:65], v[148:151], v[186:189], v[62:65]
	v_mfma_f32_16x16x32_bf16 v[62:65], v[152:155], v[190:193], v[62:65]
	v_mfma_f32_16x16x32_bf16 v[58:61], v[156:159], v[186:189], v[58:61]
	v_mfma_f32_16x16x32_bf16 v[58:61], v[166:169], v[190:193], v[58:61]
	v_mfma_f32_16x16x32_bf16 v[46:49], v[148:151], v[194:197], v[46:49]
	v_mfma_f32_16x16x32_bf16 v[46:49], v[152:155], v[198:201], v[46:49]
	v_mfma_f32_16x16x32_bf16 v[42:45], v[156:159], v[194:197], v[42:45]
	v_mfma_f32_16x16x32_bf16 v[42:45], v[166:169], v[198:201], v[42:45]
	v_mfma_f32_16x16x32_bf16 v[30:33], v[148:151], v[202:205], v[30:33]
	v_mfma_f32_16x16x32_bf16 v[30:33], v[152:155], v[206:209], v[30:33]
	v_mfma_f32_16x16x32_bf16 v[26:29], v[156:159], v[202:205], v[26:29]
	v_mfma_f32_16x16x32_bf16 v[26:29], v[166:169], v[206:209], v[26:29]
	v_mfma_f32_16x16x32_bf16 v[14:17], v[148:151], v[210:213], v[14:17]
	v_mfma_f32_16x16x32_bf16 v[14:17], v[152:155], v[214:217], v[14:17]
	v_mfma_f32_16x16x32_bf16 v[10:13], v[156:159], v[210:213], v[10:13]
	v_mfma_f32_16x16x32_bf16 v[10:13], v[166:169], v[214:217], v[10:13]
	s_setprio 0
	s_setprio 1
	v_mfma_f32_16x16x32_bf16 v[54:57], v[170:173], v[186:189], v[54:57]
	v_mfma_f32_16x16x32_bf16 v[54:57], v[174:177], v[190:193], v[54:57]
	v_mfma_f32_16x16x32_bf16 v[50:53], v[178:181], v[186:189], v[50:53]
	v_mfma_f32_16x16x32_bf16 v[50:53], v[182:185], v[190:193], v[50:53]
	v_mfma_f32_16x16x32_bf16 v[38:41], v[170:173], v[194:197], v[38:41]
	v_mfma_f32_16x16x32_bf16 v[38:41], v[174:177], v[198:201], v[38:41]
	v_mfma_f32_16x16x32_bf16 v[34:37], v[178:181], v[194:197], v[34:37]
	v_mfma_f32_16x16x32_bf16 v[34:37], v[182:185], v[198:201], v[34:37]
	v_mfma_f32_16x16x32_bf16 v[22:25], v[170:173], v[202:205], v[22:25]
	v_mfma_f32_16x16x32_bf16 v[22:25], v[174:177], v[206:209], v[22:25]
	v_mfma_f32_16x16x32_bf16 v[18:21], v[178:181], v[202:205], v[18:21]
	v_mfma_f32_16x16x32_bf16 v[18:21], v[182:185], v[206:209], v[18:21]
	v_mfma_f32_16x16x32_bf16 v[6:9], v[170:173], v[210:213], v[6:9]
	v_mfma_f32_16x16x32_bf16 v[6:9], v[174:177], v[214:217], v[6:9]
	v_mfma_f32_16x16x32_bf16 v[2:5], v[178:181], v[210:213], v[2:5]
	v_mfma_f32_16x16x32_bf16 v[2:5], v[182:185], v[214:217], v[2:5]
	s_setprio 0
	s_barrier
	s_add_i32 s52, 0, 0x18000
	v_add_u32_e32 v165, s52, v160
	s_add_i32 s53, 0, 0x1c000
	ds_read_b128 v[148:151], v165
	ds_read_b128 v[152:155], v165 offset:1024
	ds_read_b128 v[156:159], v165 offset:2048
	ds_read_b128 v[166:169], v165 offset:3072
	v_add_u32_e32 v165, s53, v160
	ds_read_b128 v[170:173], v165
	ds_read_b128 v[174:177], v165 offset:1024
	ds_read_b128 v[178:181], v165 offset:2048
	ds_read_b128 v[182:185], v165 offset:3072
	s_add_u32 s0, s30, 0x40000
	s_addc_u32 s1, s31, 0
	s_mov_b32 m0, s38
	v_lshl_add_u64 v[226:227], s[0:1], 0, v[130:131]
	ds_read_b128 v[186:189], v163 offset:32768
	ds_read_b128 v[190:193], v163 offset:33792
	ds_read_b128 v[194:197], v163 offset:34816
	ds_read_b128 v[198:201], v163 offset:35840
	ds_read_b128 v[202:205], v163 offset:36864
	ds_read_b128 v[206:209], v163 offset:37888
	ds_read_b128 v[210:213], v163 offset:38912
	ds_read_b128 v[214:217], v163 offset:39936
	global_load_lds_dwordx4 v[226:227], off
	v_lshl_add_u64 v[226:227], s[0:1], 0, v[134:135]
	s_mov_b32 m0, s39
	s_nop 0
	global_load_lds_dwordx4 v[226:227], off
	s_waitcnt vmcnt(8)
	s_waitcnt lgkmcnt(0)
	s_barrier
	s_setprio 1
	v_mfma_f32_16x16x32_bf16 v[126:129], v[148:151], v[186:189], v[126:129]
	v_mfma_f32_16x16x32_bf16 v[126:129], v[152:155], v[190:193], v[126:129]
	v_mfma_f32_16x16x32_bf16 v[118:121], v[156:159], v[186:189], v[118:121]
	v_mfma_f32_16x16x32_bf16 v[118:121], v[166:169], v[190:193], v[118:121]
	v_mfma_f32_16x16x32_bf16 v[110:113], v[148:151], v[194:197], v[110:113]
	v_mfma_f32_16x16x32_bf16 v[110:113], v[152:155], v[198:201], v[110:113]
	v_mfma_f32_16x16x32_bf16 v[106:109], v[156:159], v[194:197], v[106:109]
	v_mfma_f32_16x16x32_bf16 v[106:109], v[166:169], v[198:201], v[106:109]
	v_mfma_f32_16x16x32_bf16 v[94:97], v[148:151], v[202:205], v[94:97]
	v_mfma_f32_16x16x32_bf16 v[94:97], v[152:155], v[206:209], v[94:97]
	v_mfma_f32_16x16x32_bf16 v[90:93], v[156:159], v[202:205], v[90:93]
	v_mfma_f32_16x16x32_bf16 v[90:93], v[166:169], v[206:209], v[90:93]
	v_mfma_f32_16x16x32_bf16 v[78:81], v[148:151], v[210:213], v[78:81]
	v_mfma_f32_16x16x32_bf16 v[78:81], v[152:155], v[214:217], v[78:81]
	v_mfma_f32_16x16x32_bf16 v[74:77], v[156:159], v[210:213], v[74:77]
	v_mfma_f32_16x16x32_bf16 v[74:77], v[166:169], v[214:217], v[74:77]
	s_setprio 0
	s_setprio 1
	v_mfma_f32_16x16x32_bf16 v[122:125], v[170:173], v[186:189], v[122:125]
	v_mfma_f32_16x16x32_bf16 v[122:125], v[174:177], v[190:193], v[122:125]
	v_mfma_f32_16x16x32_bf16 v[114:117], v[178:181], v[186:189], v[114:117]
	v_mfma_f32_16x16x32_bf16 v[114:117], v[182:185], v[190:193], v[114:117]
	v_mfma_f32_16x16x32_bf16 v[102:105], v[170:173], v[194:197], v[102:105]
	v_mfma_f32_16x16x32_bf16 v[102:105], v[174:177], v[198:201], v[102:105]
	v_mfma_f32_16x16x32_bf16 v[98:101], v[178:181], v[194:197], v[98:101]
	v_mfma_f32_16x16x32_bf16 v[98:101], v[182:185], v[198:201], v[98:101]
	v_mfma_f32_16x16x32_bf16 v[86:89], v[170:173], v[202:205], v[86:89]
	v_mfma_f32_16x16x32_bf16 v[86:89], v[174:177], v[206:209], v[86:89]
	v_mfma_f32_16x16x32_bf16 v[82:85], v[178:181], v[202:205], v[82:85]
	v_mfma_f32_16x16x32_bf16 v[82:85], v[182:185], v[206:209], v[82:85]
	v_mfma_f32_16x16x32_bf16 v[70:73], v[170:173], v[210:213], v[70:73]
	v_mfma_f32_16x16x32_bf16 v[70:73], v[174:177], v[214:217], v[70:73]
	v_mfma_f32_16x16x32_bf16 v[66:69], v[178:181], v[210:213], v[66:69]
	v_mfma_f32_16x16x32_bf16 v[66:69], v[182:185], v[214:217], v[66:69]
	s_setprio 0
	s_barrier
	s_add_i32 s0, s52, s36
	v_lshl_add_u64 v[218:219], v[218:219], 0, s[14:15]
	s_mov_b32 m0, s0
	ds_read_b128 v[186:189], v163 offset:49152
	ds_read_b128 v[190:193], v163 offset:50176
	ds_read_b128 v[194:197], v163 offset:51200
	ds_read_b128 v[198:201], v163 offset:52224
	ds_read_b128 v[202:205], v163 offset:53248
	ds_read_b128 v[206:209], v163 offset:54272
	ds_read_b128 v[210:213], v163 offset:55296
	ds_read_b128 v[214:217], v163 offset:56320
	global_load_lds_dwordx4 v[218:219], off
	s_add_i32 m0, s0, 0x2000
	s_add_u32 s0, s2, 0x40080
	v_lshl_add_u64 v[218:219], v[220:221], 0, s[14:15]
	s_addc_u32 s1, s3, 0
	s_add_i32 s2, s53, s36
	global_load_lds_dwordx4 v[218:219], off
	v_lshl_add_u64 v[218:219], s[0:1], 0, v[132:133]
	s_mov_b32 m0, s2
	s_nop 0
	global_load_lds_dwordx4 v[218:219], off
	v_lshl_add_u64 v[218:219], s[0:1], 0, v[136:137]
	s_add_i32 m0, s2, 0x2000
	s_nop 0
	global_load_lds_dwordx4 v[218:219], off
	v_lshl_add_u64 v[218:219], v[222:223], 0, s[14:15]
	s_mov_b32 m0, s40
	s_nop 0
	global_load_lds_dwordx4 v[218:219], off
	v_lshl_add_u64 v[218:219], v[224:225], 0, s[14:15]
	s_mov_b32 m0, s41
	s_nop 0
	global_load_lds_dwordx4 v[218:219], off
	s_waitcnt vmcnt(8)
	s_waitcnt lgkmcnt(0)
	s_barrier
	s_setprio 1
	v_mfma_f32_16x16x32_bf16 v[62:65], v[148:151], v[186:189], v[62:65]
	v_mfma_f32_16x16x32_bf16 v[62:65], v[152:155], v[190:193], v[62:65]
	v_mfma_f32_16x16x32_bf16 v[58:61], v[156:159], v[186:189], v[58:61]
	v_mfma_f32_16x16x32_bf16 v[58:61], v[166:169], v[190:193], v[58:61]
	v_mfma_f32_16x16x32_bf16 v[46:49], v[148:151], v[194:197], v[46:49]
	v_mfma_f32_16x16x32_bf16 v[46:49], v[152:155], v[198:201], v[46:49]
	v_mfma_f32_16x16x32_bf16 v[42:45], v[156:159], v[194:197], v[42:45]
	v_mfma_f32_16x16x32_bf16 v[42:45], v[166:169], v[198:201], v[42:45]
	v_mfma_f32_16x16x32_bf16 v[30:33], v[148:151], v[202:205], v[30:33]
	v_mfma_f32_16x16x32_bf16 v[30:33], v[152:155], v[206:209], v[30:33]
	v_mfma_f32_16x16x32_bf16 v[26:29], v[156:159], v[202:205], v[26:29]
	v_mfma_f32_16x16x32_bf16 v[26:29], v[166:169], v[206:209], v[26:29]
	v_mfma_f32_16x16x32_bf16 v[14:17], v[148:151], v[210:213], v[14:17]
	v_mfma_f32_16x16x32_bf16 v[14:17], v[152:155], v[214:217], v[14:17]
	v_mfma_f32_16x16x32_bf16 v[10:13], v[156:159], v[210:213], v[10:13]
	v_mfma_f32_16x16x32_bf16 v[10:13], v[166:169], v[214:217], v[10:13]
	s_setprio 0
	s_setprio 1
	v_mfma_f32_16x16x32_bf16 v[54:57], v[170:173], v[186:189], v[54:57]
	s_add_i32 s51, s51, 2
	s_add_u32 s28, s28, 0x100
	s_addc_u32 s29, s29, 0
	s_add_u32 s49, s49, 0x100
	s_addc_u32 s50, s50, 0
	s_cmp_gt_u32 s51, 13
	v_mfma_f32_16x16x32_bf16 v[54:57], v[174:177], v[190:193], v[54:57]
	v_mfma_f32_16x16x32_bf16 v[50:53], v[178:181], v[186:189], v[50:53]
	v_mfma_f32_16x16x32_bf16 v[50:53], v[182:185], v[190:193], v[50:53]
	v_mfma_f32_16x16x32_bf16 v[38:41], v[170:173], v[194:197], v[38:41]
	v_mfma_f32_16x16x32_bf16 v[38:41], v[174:177], v[198:201], v[38:41]
	v_mfma_f32_16x16x32_bf16 v[34:37], v[178:181], v[194:197], v[34:37]
	v_mfma_f32_16x16x32_bf16 v[34:37], v[182:185], v[198:201], v[34:37]
	v_mfma_f32_16x16x32_bf16 v[22:25], v[170:173], v[202:205], v[22:25]
	v_mfma_f32_16x16x32_bf16 v[22:25], v[174:177], v[206:209], v[22:25]
	v_mfma_f32_16x16x32_bf16 v[18:21], v[178:181], v[202:205], v[18:21]
	v_mfma_f32_16x16x32_bf16 v[18:21], v[182:185], v[206:209], v[18:21]
	v_mfma_f32_16x16x32_bf16 v[6:9], v[170:173], v[210:213], v[6:9]
	v_mfma_f32_16x16x32_bf16 v[6:9], v[174:177], v[214:217], v[6:9]
	v_mfma_f32_16x16x32_bf16 v[2:5], v[178:181], v[210:213], v[2:5]
	v_mfma_f32_16x16x32_bf16 v[2:5], v[182:185], v[214:217], v[2:5]
	s_setprio 0
	s_barrier
	s_cbranch_scc0 .LBB0_1938
	s_and_b64 vcc, exec, s[16:17]
	s_cbranch_vccz .LBB0_1941
	s_barrier

.LBB0_2019:
	ds_read_b128 v[110:113], v227
	ds_read_b128 v[114:117], v227 offset:1024
	ds_read_b128 v[122:125], v227 offset:2048
	ds_read_b128 v[126:129], v227 offset:3072
	ds_read_b128 v[146:149], v228
	ds_read_b128 v[150:153], v228 offset:1024
	ds_read_b128 v[154:157], v228 offset:2048
	ds_read_b128 v[158:161], v228 offset:3072
	s_add_u32 s0, s10, 0xfffc0080
	s_addc_u32 s1, s11, -1
	s_cmp_eq_u32 s77, 12
	s_cselect_b32 s13, s7, s1
	s_cselect_b32 s12, s9, s0
	s_cselect_b32 s3, s55, s63
	s_cselect_b32 s2, s57, s62
	v_lshl_add_u64 v[212:213], s[10:11], 0, v[180:181]
	s_add_i32 m0, s66, 0xc000
	ds_read_b128 v[162:165], v229
	ds_read_b128 v[166:169], v229 offset:1024
	ds_read_b128 v[188:191], v229 offset:2048
	ds_read_b128 v[192:195], v229 offset:3072
	ds_read_b128 v[196:199], v229 offset:4096
	ds_read_b128 v[200:203], v229 offset:5120
	ds_read_b128 v[204:207], v229 offset:6144
	ds_read_b128 v[208:211], v229 offset:7168
	global_load_lds_dwordx4 v[212:213], off
	v_lshl_add_u64 v[212:213], s[10:11], 0, v[182:183]
	s_add_i32 m0, s66, 0xe000
	s_nop 0
	global_load_lds_dwordx4 v[212:213], off
	s_waitcnt vmcnt(8)
	s_waitcnt lgkmcnt(0)
	s_barrier
	s_setprio 1
	v_mfma_f32_16x16x32_bf16 v[142:145], v[110:113], v[162:165], v[142:145]
	v_mfma_f32_16x16x32_bf16 v[142:145], v[114:117], v[166:169], v[142:145]
	v_mfma_f32_16x16x32_bf16 v[138:141], v[122:125], v[162:165], v[138:141]
	v_mfma_f32_16x16x32_bf16 v[138:141], v[126:129], v[166:169], v[138:141]
	v_mfma_f32_16x16x32_bf16 v[134:137], v[110:113], v[188:191], v[134:137]
	v_mfma_f32_16x16x32_bf16 v[134:137], v[114:117], v[192:195], v[134:137]
	v_mfma_f32_16x16x32_bf16 v[130:133], v[122:125], v[188:191], v[130:133]
	v_mfma_f32_16x16x32_bf16 v[130:133], v[126:129], v[192:195], v[130:133]
	v_mfma_f32_16x16x32_bf16 v[118:121], v[110:113], v[196:199], v[118:121]
	v_mfma_f32_16x16x32_bf16 v[118:121], v[114:117], v[200:203], v[118:121]
	v_mfma_f32_16x16x32_bf16 v[106:109], v[122:125], v[196:199], v[106:109]
	v_mfma_f32_16x16x32_bf16 v[106:109], v[126:129], v[200:203], v[106:109]
	v_mfma_f32_16x16x32_bf16 v[102:105], v[110:113], v[204:207], v[102:105]
	v_mfma_f32_16x16x32_bf16 v[102:105], v[114:117], v[208:211], v[102:105]
	v_mfma_f32_16x16x32_bf16 v[98:101], v[122:125], v[204:207], v[98:101]
	v_mfma_f32_16x16x32_bf16 v[98:101], v[126:129], v[208:211], v[98:101]
	s_setprio 0
	s_setprio 1
	v_mfma_f32_16x16x32_bf16 v[62:65], v[146:149], v[162:165], v[62:65]
	v_mfma_f32_16x16x32_bf16 v[62:65], v[150:153], v[166:169], v[62:65]
	v_mfma_f32_16x16x32_bf16 v[58:61], v[154:157], v[162:165], v[58:61]
	v_mfma_f32_16x16x32_bf16 v[58:61], v[158:161], v[166:169], v[58:61]
	v_mfma_f32_16x16x32_bf16 v[54:57], v[146:149], v[188:191], v[54:57]
	v_mfma_f32_16x16x32_bf16 v[54:57], v[150:153], v[192:195], v[54:57]
	v_mfma_f32_16x16x32_bf16 v[50:53], v[154:157], v[188:191], v[50:53]
	v_mfma_f32_16x16x32_bf16 v[50:53], v[158:161], v[192:195], v[50:53]
	v_mfma_f32_16x16x32_bf16 v[46:49], v[146:149], v[196:199], v[46:49]
	v_mfma_f32_16x16x32_bf16 v[46:49], v[150:153], v[200:203], v[46:49]
	v_mfma_f32_16x16x32_bf16 v[42:45], v[154:157], v[196:199], v[42:45]
	v_mfma_f32_16x16x32_bf16 v[42:45], v[158:161], v[200:203], v[42:45]
	v_mfma_f32_16x16x32_bf16 v[38:41], v[146:149], v[204:207], v[38:41]
	v_mfma_f32_16x16x32_bf16 v[38:41], v[150:153], v[208:211], v[38:41]
	v_mfma_f32_16x16x32_bf16 v[34:37], v[154:157], v[204:207], v[34:37]
	v_mfma_f32_16x16x32_bf16 v[34:37], v[158:161], v[208:211], v[34:37]
	s_setprio 0
	s_barrier
	s_add_i32 s0, s75, s65
	v_lshl_add_u64 v[212:213], s[2:3], 0, v[172:173]
	s_mov_b32 m0, s0
	ds_read_b128 v[162:165], v229 offset:16384
	ds_read_b128 v[166:169], v229 offset:17408
	ds_read_b128 v[188:191], v229 offset:18432
	ds_read_b128 v[192:195], v229 offset:19456
	ds_read_b128 v[196:199], v229 offset:20480
	ds_read_b128 v[200:203], v229 offset:21504
	ds_read_b128 v[204:207], v229 offset:22528
	ds_read_b128 v[208:211], v229 offset:23552
	global_load_lds_dwordx4 v[212:213], off
	s_add_i32 m0, s0, 0x2000
	s_add_u32 s0, s2, 0x40000
	v_lshl_add_u64 v[214:215], s[2:3], 0, v[176:177]
	s_addc_u32 s1, s3, 0
	s_add_i32 s78, s76, s65
	global_load_lds_dwordx4 v[214:215], off
	v_lshl_add_u64 v[216:217], s[0:1], 0, v[172:173]
	s_mov_b32 m0, s78
	v_lshl_add_u64 v[218:219], s[12:13], 0, v[174:175]
	global_load_lds_dwordx4 v[216:217], off
	v_lshl_add_u64 v[216:217], s[0:1], 0, v[176:177]
	s_add_i32 m0, s78, 0x2000
	s_nop 0
	global_load_lds_dwordx4 v[216:217], off
	v_lshl_add_u64 v[216:217], s[12:13], 0, v[170:171]
	s_mov_b32 m0, s66
	s_nop 0
	global_load_lds_dwordx4 v[216:217], off
	s_mov_b32 m0, s67
	s_nop 0
	global_load_lds_dwordx4 v[218:219], off
	s_waitcnt vmcnt(8)
	s_waitcnt lgkmcnt(0)
	s_barrier
	s_setprio 1
	v_mfma_f32_16x16x32_bf16 v[94:97], v[110:113], v[162:165], v[94:97]
	v_mfma_f32_16x16x32_bf16 v[94:97], v[114:117], v[166:169], v[94:97]
	v_mfma_f32_16x16x32_bf16 v[90:93], v[122:125], v[162:165], v[90:93]
	v_mfma_f32_16x16x32_bf16 v[90:93], v[126:129], v[166:169], v[90:93]
	v_mfma_f32_16x16x32_bf16 v[86:89], v[110:113], v[188:191], v[86:89]
	v_mfma_f32_16x16x32_bf16 v[86:89], v[114:117], v[192:195], v[86:89]
	v_mfma_f32_16x16x32_bf16 v[82:85], v[122:125], v[188:191], v[82:85]
	v_mfma_f32_16x16x32_bf16 v[82:85], v[126:129], v[192:195], v[82:85]
	v_mfma_f32_16x16x32_bf16 v[78:81], v[110:113], v[196:199], v[78:81]
	v_mfma_f32_16x16x32_bf16 v[78:81], v[114:117], v[200:203], v[78:81]
	v_mfma_f32_16x16x32_bf16 v[74:77], v[122:125], v[196:199], v[74:77]
	v_mfma_f32_16x16x32_bf16 v[74:77], v[126:129], v[200:203], v[74:77]
	v_mfma_f32_16x16x32_bf16 v[70:73], v[110:113], v[204:207], v[70:73]
	v_mfma_f32_16x16x32_bf16 v[70:73], v[114:117], v[208:211], v[70:73]
	v_mfma_f32_16x16x32_bf16 v[66:69], v[122:125], v[204:207], v[66:69]
	v_mfma_f32_16x16x32_bf16 v[66:69], v[126:129], v[208:211], v[66:69]
	s_setprio 0
	s_setprio 1
	v_mfma_f32_16x16x32_bf16 v[30:33], v[146:149], v[162:165], v[30:33]
	v_mfma_f32_16x16x32_bf16 v[30:33], v[150:153], v[166:169], v[30:33]
	v_mfma_f32_16x16x32_bf16 v[26:29], v[154:157], v[162:165], v[26:29]
	v_mfma_f32_16x16x32_bf16 v[26:29], v[158:161], v[166:169], v[26:29]
	v_mfma_f32_16x16x32_bf16 v[22:25], v[146:149], v[188:191], v[22:25]
	v_mfma_f32_16x16x32_bf16 v[22:25], v[150:153], v[192:195], v[22:25]
	v_mfma_f32_16x16x32_bf16 v[18:21], v[154:157], v[188:191], v[18:21]
	v_mfma_f32_16x16x32_bf16 v[18:21], v[158:161], v[192:195], v[18:21]
	v_mfma_f32_16x16x32_bf16 v[14:17], v[146:149], v[196:199], v[14:17]
	v_mfma_f32_16x16x32_bf16 v[14:17], v[150:153], v[200:203], v[14:17]
	v_mfma_f32_16x16x32_bf16 v[10:13], v[154:157], v[196:199], v[10:13]
	v_mfma_f32_16x16x32_bf16 v[10:13], v[158:161], v[200:203], v[10:13]
	v_mfma_f32_16x16x32_bf16 v[6:9], v[146:149], v[204:207], v[6:9]
	v_mfma_f32_16x16x32_bf16 v[6:9], v[150:153], v[208:211], v[6:9]
	v_mfma_f32_16x16x32_bf16 v[2:5], v[154:157], v[204:207], v[2:5]
	v_mfma_f32_16x16x32_bf16 v[2:5], v[158:161], v[208:211], v[2:5]
	s_setprio 0
	s_barrier
	s_add_i32 s78, 0, 0x18000
	s_add_i32 s79, 0, 0x1c000
	v_add_u32_e32 v126, s78, v222
	v_add_u32_e32 v158, s79, v222
	ds_read_b128 v[110:113], v126
	ds_read_b128 v[114:117], v126 offset:1024
	ds_read_b128 v[122:125], v126 offset:2048
	ds_read_b128 v[126:129], v126 offset:3072
	ds_read_b128 v[146:149], v158
	ds_read_b128 v[150:153], v158 offset:1024
	ds_read_b128 v[154:157], v158 offset:2048
	ds_read_b128 v[158:161], v158 offset:3072
	s_add_u32 s0, s12, 0x40000
	s_addc_u32 s1, s13, 0
	s_mov_b32 m0, s68
	v_lshl_add_u64 v[220:221], s[0:1], 0, v[170:171]
	ds_read_b128 v[162:165], v229 offset:32768
	ds_read_b128 v[166:169], v229 offset:33792
	ds_read_b128 v[188:191], v229 offset:34816
	ds_read_b128 v[192:195], v229 offset:35840
	ds_read_b128 v[196:199], v229 offset:36864
	ds_read_b128 v[200:203], v229 offset:37888
	ds_read_b128 v[204:207], v229 offset:38912
	ds_read_b128 v[208:211], v229 offset:39936
	global_load_lds_dwordx4 v[220:221], off
	v_lshl_add_u64 v[220:221], s[0:1], 0, v[174:175]
	s_mov_b32 m0, s69
	s_nop 0
	global_load_lds_dwordx4 v[220:221], off
	s_waitcnt vmcnt(8)
	s_waitcnt lgkmcnt(0)
	s_barrier
	s_setprio 1
	v_mfma_f32_16x16x32_bf16 v[142:145], v[110:113], v[162:165], v[142:145]
	v_mfma_f32_16x16x32_bf16 v[142:145], v[114:117], v[166:169], v[142:145]
	v_mfma_f32_16x16x32_bf16 v[138:141], v[122:125], v[162:165], v[138:141]
	v_mfma_f32_16x16x32_bf16 v[138:141], v[126:129], v[166:169], v[138:141]
	v_mfma_f32_16x16x32_bf16 v[134:137], v[110:113], v[188:191], v[134:137]
	v_mfma_f32_16x16x32_bf16 v[134:137], v[114:117], v[192:195], v[134:137]
	v_mfma_f32_16x16x32_bf16 v[130:133], v[122:125], v[188:191], v[130:133]
	v_mfma_f32_16x16x32_bf16 v[130:133], v[126:129], v[192:195], v[130:133]
	v_mfma_f32_16x16x32_bf16 v[118:121], v[110:113], v[196:199], v[118:121]
	v_mfma_f32_16x16x32_bf16 v[118:121], v[114:117], v[200:203], v[118:121]
	v_mfma_f32_16x16x32_bf16 v[106:109], v[122:125], v[196:199], v[106:109]
	v_mfma_f32_16x16x32_bf16 v[106:109], v[126:129], v[200:203], v[106:109]
	v_mfma_f32_16x16x32_bf16 v[102:105], v[110:113], v[204:207], v[102:105]
	v_mfma_f32_16x16x32_bf16 v[102:105], v[114:117], v[208:211], v[102:105]
	v_mfma_f32_16x16x32_bf16 v[98:101], v[122:125], v[204:207], v[98:101]
	v_mfma_f32_16x16x32_bf16 v[98:101], v[126:129], v[208:211], v[98:101]
	s_setprio 0
	s_setprio 1
	v_mfma_f32_16x16x32_bf16 v[62:65], v[146:149], v[162:165], v[62:65]
	v_mfma_f32_16x16x32_bf16 v[62:65], v[150:153], v[166:169], v[62:65]
	v_mfma_f32_16x16x32_bf16 v[58:61], v[154:157], v[162:165], v[58:61]
	v_mfma_f32_16x16x32_bf16 v[58:61], v[158:161], v[166:169], v[58:61]
	v_mfma_f32_16x16x32_bf16 v[54:57], v[146:149], v[188:191], v[54:57]
	v_mfma_f32_16x16x32_bf16 v[54:57], v[150:153], v[192:195], v[54:57]
	v_mfma_f32_16x16x32_bf16 v[50:53], v[154:157], v[188:191], v[50:53]
	v_mfma_f32_16x16x32_bf16 v[50:53], v[158:161], v[192:195], v[50:53]
	v_mfma_f32_16x16x32_bf16 v[46:49], v[146:149], v[196:199], v[46:49]
	v_mfma_f32_16x16x32_bf16 v[46:49], v[150:153], v[200:203], v[46:49]
	v_mfma_f32_16x16x32_bf16 v[42:45], v[154:157], v[196:199], v[42:45]
	v_mfma_f32_16x16x32_bf16 v[42:45], v[158:161], v[200:203], v[42:45]
	v_mfma_f32_16x16x32_bf16 v[38:41], v[146:149], v[204:207], v[38:41]
	v_mfma_f32_16x16x32_bf16 v[38:41], v[150:153], v[208:211], v[38:41]
	v_mfma_f32_16x16x32_bf16 v[34:37], v[154:157], v[204:207], v[34:37]
	v_mfma_f32_16x16x32_bf16 v[34:37], v[158:161], v[208:211], v[34:37]
	s_setprio 0
	s_barrier
	s_add_i32 s0, s78, s65
	v_lshl_add_u64 v[212:213], v[212:213], 0, s[24:25]
	s_mov_b32 m0, s0
	ds_read_b128 v[162:165], v229 offset:49152
	ds_read_b128 v[166:169], v229 offset:50176
	ds_read_b128 v[188:191], v229 offset:51200
	ds_read_b128 v[192:195], v229 offset:52224
	ds_read_b128 v[196:199], v229 offset:53248
	ds_read_b128 v[200:203], v229 offset:54272
	ds_read_b128 v[204:207], v229 offset:55296
	ds_read_b128 v[208:211], v229 offset:56320
	global_load_lds_dwordx4 v[212:213], off
	s_add_i32 m0, s0, 0x2000
	s_add_u32 s0, s2, 0x40080
	v_lshl_add_u64 v[212:213], v[214:215], 0, s[24:25]
	s_addc_u32 s1, s3, 0
	s_add_i32 s2, s79, s65
	global_load_lds_dwordx4 v[212:213], off
	v_lshl_add_u64 v[212:213], s[0:1], 0, v[172:173]
	s_mov_b32 m0, s2
	s_nop 0
	global_load_lds_dwordx4 v[212:213], off
	v_lshl_add_u64 v[212:213], s[0:1], 0, v[176:177]
	s_add_i32 m0, s2, 0x2000
	s_nop 0
	global_load_lds_dwordx4 v[212:213], off
	v_lshl_add_u64 v[212:213], v[216:217], 0, s[24:25]
	s_mov_b32 m0, s71
	s_nop 0
	global_load_lds_dwordx4 v[212:213], off
	v_lshl_add_u64 v[212:213], v[218:219], 0, s[24:25]
	s_mov_b32 m0, s72
	s_nop 0
	global_load_lds_dwordx4 v[212:213], off
	s_waitcnt vmcnt(8)
	s_waitcnt lgkmcnt(0)
	s_barrier
	s_setprio 1
	v_mfma_f32_16x16x32_bf16 v[94:97], v[110:113], v[162:165], v[94:97]
	v_mfma_f32_16x16x32_bf16 v[94:97], v[114:117], v[166:169], v[94:97]
	v_mfma_f32_16x16x32_bf16 v[90:93], v[122:125], v[162:165], v[90:93]
	v_mfma_f32_16x16x32_bf16 v[90:93], v[126:129], v[166:169], v[90:93]
	v_mfma_f32_16x16x32_bf16 v[86:89], v[110:113], v[188:191], v[86:89]
	v_mfma_f32_16x16x32_bf16 v[86:89], v[114:117], v[192:195], v[86:89]
	v_mfma_f32_16x16x32_bf16 v[82:85], v[122:125], v[188:191], v[82:85]
	v_mfma_f32_16x16x32_bf16 v[82:85], v[126:129], v[192:195], v[82:85]
	v_mfma_f32_16x16x32_bf16 v[78:81], v[110:113], v[196:199], v[78:81]
	v_mfma_f32_16x16x32_bf16 v[78:81], v[114:117], v[200:203], v[78:81]
	v_mfma_f32_16x16x32_bf16 v[74:77], v[122:125], v[196:199], v[74:77]
	v_mfma_f32_16x16x32_bf16 v[74:77], v[126:129], v[200:203], v[74:77]
	v_mfma_f32_16x16x32_bf16 v[70:73], v[110:113], v[204:207], v[70:73]
	v_mfma_f32_16x16x32_bf16 v[70:73], v[114:117], v[208:211], v[70:73]
	v_mfma_f32_16x16x32_bf16 v[66:69], v[122:125], v[204:207], v[66:69]
	v_mfma_f32_16x16x32_bf16 v[66:69], v[126:129], v[208:211], v[66:69]
	s_setprio 0
	s_setprio 1
	v_mfma_f32_16x16x32_bf16 v[30:33], v[146:149], v[162:165], v[30:33]
	s_add_i32 s77, s77, 2
	s_add_u32 s10, s10, 0x100
	s_addc_u32 s11, s11, 0
	s_add_u32 s62, s62, 0x100
	s_addc_u32 s63, s63, 0
	s_cmp_gt_u32 s77, 13
	v_mfma_f32_16x16x32_bf16 v[30:33], v[150:153], v[166:169], v[30:33]
	v_mfma_f32_16x16x32_bf16 v[26:29], v[154:157], v[162:165], v[26:29]
	v_mfma_f32_16x16x32_bf16 v[26:29], v[158:161], v[166:169], v[26:29]
	v_mfma_f32_16x16x32_bf16 v[22:25], v[146:149], v[188:191], v[22:25]
	v_mfma_f32_16x16x32_bf16 v[22:25], v[150:153], v[192:195], v[22:25]
	v_mfma_f32_16x16x32_bf16 v[18:21], v[154:157], v[188:191], v[18:21]
	v_mfma_f32_16x16x32_bf16 v[18:21], v[158:161], v[192:195], v[18:21]
	v_mfma_f32_16x16x32_bf16 v[14:17], v[146:149], v[196:199], v[14:17]
	v_mfma_f32_16x16x32_bf16 v[14:17], v[150:153], v[200:203], v[14:17]
	v_mfma_f32_16x16x32_bf16 v[10:13], v[154:157], v[196:199], v[10:13]
	v_mfma_f32_16x16x32_bf16 v[10:13], v[158:161], v[200:203], v[10:13]
	v_mfma_f32_16x16x32_bf16 v[6:9], v[146:149], v[204:207], v[6:9]
	v_mfma_f32_16x16x32_bf16 v[6:9], v[150:153], v[208:211], v[6:9]
	v_mfma_f32_16x16x32_bf16 v[2:5], v[154:157], v[204:207], v[2:5]
	v_mfma_f32_16x16x32_bf16 v[2:5], v[158:161], v[208:211], v[2:5]
	s_setprio 0
	s_barrier
	s_cbranch_scc0 .LBB0_2019
	s_and_b64 vcc, exec, s[26:27]
	s_cbranch_vccz .LBB0_2022
	s_barrier

.LBB0_2118:
	ds_read_b128 v[130:133], v186
	ds_read_b128 v[134:137], v186 offset:1024
	ds_read_b128 v[138:141], v186 offset:2048
	ds_read_b128 v[142:145], v186 offset:3072
	ds_read_b128 v[146:149], v187
	ds_read_b128 v[150:153], v187 offset:1024
	ds_read_b128 v[170:173], v187 offset:2048
	ds_read_b128 v[174:177], v187 offset:3072
	s_add_u32 s0, s38, 0xfffc0080
	s_addc_u32 s1, s39, -1
	s_cmp_eq_u32 s59, 12
	s_cselect_b32 s41, s11, s1
	s_cselect_b32 s40, s29, s0
	s_cselect_b32 s3, s27, s58
	s_cselect_b32 s2, s56, s57
	v_lshl_add_u64 v[218:219], s[38:39], 0, v[162:163]
	s_add_i32 m0, s37, 0xc000
	ds_read_b128 v[178:181], v188
	ds_read_b128 v[190:193], v188 offset:1024
	ds_read_b128 v[194:197], v188 offset:2048
	ds_read_b128 v[198:201], v188 offset:3072
	ds_read_b128 v[202:205], v188 offset:4096
	ds_read_b128 v[206:209], v188 offset:5120
	ds_read_b128 v[210:213], v188 offset:6144
	ds_read_b128 v[214:217], v188 offset:7168
	global_load_lds_dwordx4 v[218:219], off
	v_lshl_add_u64 v[218:219], s[38:39], 0, v[164:165]
	s_add_i32 m0, s37, 0xe000
	s_nop 0
	global_load_lds_dwordx4 v[218:219], off
	s_waitcnt vmcnt(8)
	s_waitcnt lgkmcnt(0)
	s_barrier
	s_setprio 1
	v_mfma_f32_16x16x32_bf16 v[126:129], v[130:133], v[178:181], v[126:129]
	v_mfma_f32_16x16x32_bf16 v[126:129], v[134:137], v[190:193], v[126:129]
	v_mfma_f32_16x16x32_bf16 v[122:125], v[138:141], v[178:181], v[122:125]
	v_mfma_f32_16x16x32_bf16 v[122:125], v[142:145], v[190:193], v[122:125]
	v_mfma_f32_16x16x32_bf16 v[110:113], v[130:133], v[194:197], v[110:113]
	v_mfma_f32_16x16x32_bf16 v[110:113], v[134:137], v[198:201], v[110:113]
	v_mfma_f32_16x16x32_bf16 v[106:109], v[138:141], v[194:197], v[106:109]
	v_mfma_f32_16x16x32_bf16 v[106:109], v[142:145], v[198:201], v[106:109]
	v_mfma_f32_16x16x32_bf16 v[94:97], v[130:133], v[202:205], v[94:97]
	v_mfma_f32_16x16x32_bf16 v[94:97], v[134:137], v[206:209], v[94:97]
	v_mfma_f32_16x16x32_bf16 v[90:93], v[138:141], v[202:205], v[90:93]
	v_mfma_f32_16x16x32_bf16 v[90:93], v[142:145], v[206:209], v[90:93]
	v_mfma_f32_16x16x32_bf16 v[78:81], v[130:133], v[210:213], v[78:81]
	v_mfma_f32_16x16x32_bf16 v[78:81], v[134:137], v[214:217], v[78:81]
	v_mfma_f32_16x16x32_bf16 v[74:77], v[138:141], v[210:213], v[74:77]
	v_mfma_f32_16x16x32_bf16 v[74:77], v[142:145], v[214:217], v[74:77]
	s_setprio 0
	s_setprio 1
	v_mfma_f32_16x16x32_bf16 v[118:121], v[146:149], v[178:181], v[118:121]
	v_mfma_f32_16x16x32_bf16 v[118:121], v[150:153], v[190:193], v[118:121]
	v_mfma_f32_16x16x32_bf16 v[114:117], v[170:173], v[178:181], v[114:117]
	v_mfma_f32_16x16x32_bf16 v[114:117], v[174:177], v[190:193], v[114:117]
	v_mfma_f32_16x16x32_bf16 v[102:105], v[146:149], v[194:197], v[102:105]
	v_mfma_f32_16x16x32_bf16 v[102:105], v[150:153], v[198:201], v[102:105]
	v_mfma_f32_16x16x32_bf16 v[98:101], v[170:173], v[194:197], v[98:101]
	v_mfma_f32_16x16x32_bf16 v[98:101], v[174:177], v[198:201], v[98:101]
	v_mfma_f32_16x16x32_bf16 v[86:89], v[146:149], v[202:205], v[86:89]
	v_mfma_f32_16x16x32_bf16 v[86:89], v[150:153], v[206:209], v[86:89]
	v_mfma_f32_16x16x32_bf16 v[82:85], v[170:173], v[202:205], v[82:85]
	v_mfma_f32_16x16x32_bf16 v[82:85], v[174:177], v[206:209], v[82:85]
	v_mfma_f32_16x16x32_bf16 v[70:73], v[146:149], v[210:213], v[70:73]
	v_mfma_f32_16x16x32_bf16 v[70:73], v[150:153], v[214:217], v[70:73]
	v_mfma_f32_16x16x32_bf16 v[66:69], v[170:173], v[210:213], v[66:69]
	v_mfma_f32_16x16x32_bf16 v[66:69], v[174:177], v[214:217], v[66:69]
	s_setprio 0
	s_barrier
	s_add_i32 s0, s54, s45
	v_lshl_add_u64 v[218:219], s[2:3], 0, v[156:157]
	s_mov_b32 m0, s0
	ds_read_b128 v[178:181], v188 offset:16384
	ds_read_b128 v[190:193], v188 offset:17408
	ds_read_b128 v[194:197], v188 offset:18432
	ds_read_b128 v[198:201], v188 offset:19456
	ds_read_b128 v[202:205], v188 offset:20480
	ds_read_b128 v[206:209], v188 offset:21504
	ds_read_b128 v[210:213], v188 offset:22528
	ds_read_b128 v[214:217], v188 offset:23552
	global_load_lds_dwordx4 v[218:219], off
	s_add_i32 m0, s0, 0x2000
	s_add_u32 s0, s2, 0x40000
	v_lshl_add_u64 v[220:221], s[2:3], 0, v[160:161]
	s_addc_u32 s1, s3, 0
	s_add_i32 s60, s55, s45
	global_load_lds_dwordx4 v[220:221], off
	v_lshl_add_u64 v[222:223], s[0:1], 0, v[156:157]
	s_mov_b32 m0, s60
	v_lshl_add_u64 v[224:225], s[40:41], 0, v[158:159]
	global_load_lds_dwordx4 v[222:223], off
	v_lshl_add_u64 v[222:223], s[0:1], 0, v[160:161]
	s_add_i32 m0, s60, 0x2000
	s_nop 0
	global_load_lds_dwordx4 v[222:223], off
	v_lshl_add_u64 v[222:223], s[40:41], 0, v[154:155]
	s_mov_b32 m0, s37
	s_nop 0
	global_load_lds_dwordx4 v[222:223], off
	s_mov_b32 m0, s46
	s_nop 0
	global_load_lds_dwordx4 v[224:225], off
	s_waitcnt vmcnt(8)
	s_waitcnt lgkmcnt(0)
	s_barrier
	s_setprio 1
	v_mfma_f32_16x16x32_bf16 v[62:65], v[130:133], v[178:181], v[62:65]
	v_mfma_f32_16x16x32_bf16 v[62:65], v[134:137], v[190:193], v[62:65]
	v_mfma_f32_16x16x32_bf16 v[58:61], v[138:141], v[178:181], v[58:61]
	v_mfma_f32_16x16x32_bf16 v[58:61], v[142:145], v[190:193], v[58:61]
	v_mfma_f32_16x16x32_bf16 v[46:49], v[130:133], v[194:197], v[46:49]
	v_mfma_f32_16x16x32_bf16 v[46:49], v[134:137], v[198:201], v[46:49]
	v_mfma_f32_16x16x32_bf16 v[42:45], v[138:141], v[194:197], v[42:45]
	v_mfma_f32_16x16x32_bf16 v[42:45], v[142:145], v[198:201], v[42:45]
	v_mfma_f32_16x16x32_bf16 v[30:33], v[130:133], v[202:205], v[30:33]
	v_mfma_f32_16x16x32_bf16 v[30:33], v[134:137], v[206:209], v[30:33]
	v_mfma_f32_16x16x32_bf16 v[26:29], v[138:141], v[202:205], v[26:29]
	v_mfma_f32_16x16x32_bf16 v[26:29], v[142:145], v[206:209], v[26:29]
	v_mfma_f32_16x16x32_bf16 v[14:17], v[130:133], v[210:213], v[14:17]
	v_mfma_f32_16x16x32_bf16 v[14:17], v[134:137], v[214:217], v[14:17]
	v_mfma_f32_16x16x32_bf16 v[10:13], v[138:141], v[210:213], v[10:13]
	v_mfma_f32_16x16x32_bf16 v[10:13], v[142:145], v[214:217], v[10:13]
	s_setprio 0
	s_setprio 1
	v_mfma_f32_16x16x32_bf16 v[54:57], v[146:149], v[178:181], v[54:57]
	v_mfma_f32_16x16x32_bf16 v[54:57], v[150:153], v[190:193], v[54:57]
	v_mfma_f32_16x16x32_bf16 v[50:53], v[170:173], v[178:181], v[50:53]
	v_mfma_f32_16x16x32_bf16 v[50:53], v[174:177], v[190:193], v[50:53]
	v_mfma_f32_16x16x32_bf16 v[38:41], v[146:149], v[194:197], v[38:41]
	v_mfma_f32_16x16x32_bf16 v[38:41], v[150:153], v[198:201], v[38:41]
	v_mfma_f32_16x16x32_bf16 v[34:37], v[170:173], v[194:197], v[34:37]
	v_mfma_f32_16x16x32_bf16 v[34:37], v[174:177], v[198:201], v[34:37]
	v_mfma_f32_16x16x32_bf16 v[22:25], v[146:149], v[202:205], v[22:25]
	v_mfma_f32_16x16x32_bf16 v[22:25], v[150:153], v[206:209], v[22:25]
	v_mfma_f32_16x16x32_bf16 v[18:21], v[170:173], v[202:205], v[18:21]
	v_mfma_f32_16x16x32_bf16 v[18:21], v[174:177], v[206:209], v[18:21]
	v_mfma_f32_16x16x32_bf16 v[6:9], v[146:149], v[210:213], v[6:9]
	v_mfma_f32_16x16x32_bf16 v[6:9], v[150:153], v[214:217], v[6:9]
	v_mfma_f32_16x16x32_bf16 v[2:5], v[170:173], v[210:213], v[2:5]
	v_mfma_f32_16x16x32_bf16 v[2:5], v[174:177], v[214:217], v[2:5]
	s_setprio 0
	s_barrier
	s_add_i32 s60, 0, 0x18000
	s_add_i32 s61, 0, 0x1c000
	v_add_u32_e32 v142, s60, v182
	v_add_u32_e32 v174, s61, v182
	ds_read_b128 v[130:133], v142
	ds_read_b128 v[134:137], v142 offset:1024
	ds_read_b128 v[138:141], v142 offset:2048
	ds_read_b128 v[142:145], v142 offset:3072
	ds_read_b128 v[146:149], v174
	ds_read_b128 v[150:153], v174 offset:1024
	ds_read_b128 v[170:173], v174 offset:2048
	ds_read_b128 v[174:177], v174 offset:3072
	s_add_u32 s0, s40, 0x40000
	s_addc_u32 s1, s41, 0
	s_mov_b32 m0, s47
	v_lshl_add_u64 v[226:227], s[0:1], 0, v[154:155]
	ds_read_b128 v[178:181], v188 offset:32768
	ds_read_b128 v[190:193], v188 offset:33792
	ds_read_b128 v[194:197], v188 offset:34816
	ds_read_b128 v[198:201], v188 offset:35840
	ds_read_b128 v[202:205], v188 offset:36864
	ds_read_b128 v[206:209], v188 offset:37888
	ds_read_b128 v[210:213], v188 offset:38912
	ds_read_b128 v[214:217], v188 offset:39936
	global_load_lds_dwordx4 v[226:227], off
	v_lshl_add_u64 v[226:227], s[0:1], 0, v[158:159]
	s_mov_b32 m0, s48
	s_nop 0
	global_load_lds_dwordx4 v[226:227], off
	s_waitcnt vmcnt(8)
	s_waitcnt lgkmcnt(0)
	s_barrier
	s_setprio 1
	v_mfma_f32_16x16x32_bf16 v[126:129], v[130:133], v[178:181], v[126:129]
	v_mfma_f32_16x16x32_bf16 v[126:129], v[134:137], v[190:193], v[126:129]
	v_mfma_f32_16x16x32_bf16 v[122:125], v[138:141], v[178:181], v[122:125]
	v_mfma_f32_16x16x32_bf16 v[122:125], v[142:145], v[190:193], v[122:125]
	v_mfma_f32_16x16x32_bf16 v[110:113], v[130:133], v[194:197], v[110:113]
	v_mfma_f32_16x16x32_bf16 v[110:113], v[134:137], v[198:201], v[110:113]
	v_mfma_f32_16x16x32_bf16 v[106:109], v[138:141], v[194:197], v[106:109]
	v_mfma_f32_16x16x32_bf16 v[106:109], v[142:145], v[198:201], v[106:109]
	v_mfma_f32_16x16x32_bf16 v[94:97], v[130:133], v[202:205], v[94:97]
	v_mfma_f32_16x16x32_bf16 v[94:97], v[134:137], v[206:209], v[94:97]
	v_mfma_f32_16x16x32_bf16 v[90:93], v[138:141], v[202:205], v[90:93]
	v_mfma_f32_16x16x32_bf16 v[90:93], v[142:145], v[206:209], v[90:93]
	v_mfma_f32_16x16x32_bf16 v[78:81], v[130:133], v[210:213], v[78:81]
	v_mfma_f32_16x16x32_bf16 v[78:81], v[134:137], v[214:217], v[78:81]
	v_mfma_f32_16x16x32_bf16 v[74:77], v[138:141], v[210:213], v[74:77]
	v_mfma_f32_16x16x32_bf16 v[74:77], v[142:145], v[214:217], v[74:77]
	s_setprio 0
	s_setprio 1
	v_mfma_f32_16x16x32_bf16 v[118:121], v[146:149], v[178:181], v[118:121]
	v_mfma_f32_16x16x32_bf16 v[118:121], v[150:153], v[190:193], v[118:121]
	v_mfma_f32_16x16x32_bf16 v[114:117], v[170:173], v[178:181], v[114:117]
	v_mfma_f32_16x16x32_bf16 v[114:117], v[174:177], v[190:193], v[114:117]
	v_mfma_f32_16x16x32_bf16 v[102:105], v[146:149], v[194:197], v[102:105]
	v_mfma_f32_16x16x32_bf16 v[102:105], v[150:153], v[198:201], v[102:105]
	v_mfma_f32_16x16x32_bf16 v[98:101], v[170:173], v[194:197], v[98:101]
	v_mfma_f32_16x16x32_bf16 v[98:101], v[174:177], v[198:201], v[98:101]
	v_mfma_f32_16x16x32_bf16 v[86:89], v[146:149], v[202:205], v[86:89]
	v_mfma_f32_16x16x32_bf16 v[86:89], v[150:153], v[206:209], v[86:89]
	v_mfma_f32_16x16x32_bf16 v[82:85], v[170:173], v[202:205], v[82:85]
	v_mfma_f32_16x16x32_bf16 v[82:85], v[174:177], v[206:209], v[82:85]
	v_mfma_f32_16x16x32_bf16 v[70:73], v[146:149], v[210:213], v[70:73]
	v_mfma_f32_16x16x32_bf16 v[70:73], v[150:153], v[214:217], v[70:73]
	v_mfma_f32_16x16x32_bf16 v[66:69], v[170:173], v[210:213], v[66:69]
	v_mfma_f32_16x16x32_bf16 v[66:69], v[174:177], v[214:217], v[66:69]
	s_setprio 0
	s_barrier
	s_add_i32 s0, s60, s45
	v_lshl_add_u64 v[218:219], v[218:219], 0, s[16:17]
	s_mov_b32 m0, s0
	ds_read_b128 v[178:181], v188 offset:49152
	ds_read_b128 v[190:193], v188 offset:50176
	ds_read_b128 v[194:197], v188 offset:51200
	ds_read_b128 v[198:201], v188 offset:52224
	ds_read_b128 v[202:205], v188 offset:53248
	ds_read_b128 v[206:209], v188 offset:54272
	ds_read_b128 v[210:213], v188 offset:55296
	ds_read_b128 v[214:217], v188 offset:56320
	global_load_lds_dwordx4 v[218:219], off
	s_add_i32 m0, s0, 0x2000
	s_add_u32 s0, s2, 0x40080
	v_lshl_add_u64 v[218:219], v[220:221], 0, s[16:17]
	s_addc_u32 s1, s3, 0
	s_add_i32 s2, s61, s45
	global_load_lds_dwordx4 v[218:219], off
	v_lshl_add_u64 v[218:219], s[0:1], 0, v[156:157]
	s_mov_b32 m0, s2
	s_nop 0
	global_load_lds_dwordx4 v[218:219], off
	v_lshl_add_u64 v[218:219], s[0:1], 0, v[160:161]
	s_add_i32 m0, s2, 0x2000
	s_nop 0
	global_load_lds_dwordx4 v[218:219], off
	v_lshl_add_u64 v[218:219], v[222:223], 0, s[16:17]
	s_mov_b32 m0, s50
	s_nop 0
	global_load_lds_dwordx4 v[218:219], off
	v_lshl_add_u64 v[218:219], v[224:225], 0, s[16:17]
	s_mov_b32 m0, s51
	s_nop 0
	global_load_lds_dwordx4 v[218:219], off
	s_waitcnt vmcnt(8)
	s_waitcnt lgkmcnt(0)
	s_barrier
	s_setprio 1
	v_mfma_f32_16x16x32_bf16 v[62:65], v[130:133], v[178:181], v[62:65]
	v_mfma_f32_16x16x32_bf16 v[62:65], v[134:137], v[190:193], v[62:65]
	v_mfma_f32_16x16x32_bf16 v[58:61], v[138:141], v[178:181], v[58:61]
	v_mfma_f32_16x16x32_bf16 v[58:61], v[142:145], v[190:193], v[58:61]
	v_mfma_f32_16x16x32_bf16 v[46:49], v[130:133], v[194:197], v[46:49]
	v_mfma_f32_16x16x32_bf16 v[46:49], v[134:137], v[198:201], v[46:49]
	v_mfma_f32_16x16x32_bf16 v[42:45], v[138:141], v[194:197], v[42:45]
	v_mfma_f32_16x16x32_bf16 v[42:45], v[142:145], v[198:201], v[42:45]
	v_mfma_f32_16x16x32_bf16 v[30:33], v[130:133], v[202:205], v[30:33]
	v_mfma_f32_16x16x32_bf16 v[30:33], v[134:137], v[206:209], v[30:33]
	v_mfma_f32_16x16x32_bf16 v[26:29], v[138:141], v[202:205], v[26:29]
	v_mfma_f32_16x16x32_bf16 v[26:29], v[142:145], v[206:209], v[26:29]
	v_mfma_f32_16x16x32_bf16 v[14:17], v[130:133], v[210:213], v[14:17]
	v_mfma_f32_16x16x32_bf16 v[14:17], v[134:137], v[214:217], v[14:17]
	v_mfma_f32_16x16x32_bf16 v[10:13], v[138:141], v[210:213], v[10:13]
	v_mfma_f32_16x16x32_bf16 v[10:13], v[142:145], v[214:217], v[10:13]
	s_setprio 0
	s_setprio 1
	v_mfma_f32_16x16x32_bf16 v[54:57], v[146:149], v[178:181], v[54:57]
	s_add_i32 s59, s59, 2
	s_add_u32 s38, s38, 0x100
	s_addc_u32 s39, s39, 0
	s_add_u32 s57, s57, 0x100
	s_addc_u32 s58, s58, 0
	s_cmp_gt_u32 s59, 13
	v_mfma_f32_16x16x32_bf16 v[54:57], v[150:153], v[190:193], v[54:57]
	v_mfma_f32_16x16x32_bf16 v[50:53], v[170:173], v[178:181], v[50:53]
	v_mfma_f32_16x16x32_bf16 v[50:53], v[174:177], v[190:193], v[50:53]
	v_mfma_f32_16x16x32_bf16 v[38:41], v[146:149], v[194:197], v[38:41]
	v_mfma_f32_16x16x32_bf16 v[38:41], v[150:153], v[198:201], v[38:41]
	v_mfma_f32_16x16x32_bf16 v[34:37], v[170:173], v[194:197], v[34:37]
	v_mfma_f32_16x16x32_bf16 v[34:37], v[174:177], v[198:201], v[34:37]
	v_mfma_f32_16x16x32_bf16 v[22:25], v[146:149], v[202:205], v[22:25]
	v_mfma_f32_16x16x32_bf16 v[22:25], v[150:153], v[206:209], v[22:25]
	v_mfma_f32_16x16x32_bf16 v[18:21], v[170:173], v[202:205], v[18:21]
	v_mfma_f32_16x16x32_bf16 v[18:21], v[174:177], v[206:209], v[18:21]
	v_mfma_f32_16x16x32_bf16 v[6:9], v[146:149], v[210:213], v[6:9]
	v_mfma_f32_16x16x32_bf16 v[6:9], v[150:153], v[214:217], v[6:9]
	v_mfma_f32_16x16x32_bf16 v[2:5], v[170:173], v[210:213], v[2:5]
	v_mfma_f32_16x16x32_bf16 v[2:5], v[174:177], v[214:217], v[2:5]
	s_setprio 0
	s_barrier
	s_cbranch_scc0 .LBB0_2118
	s_and_b64 vcc, exec, s[18:19]
	s_cbranch_vccz .LBB0_2121
	s_barrier

.LBB0_2207:
	ds_read_b128 v[148:151], v165
	ds_read_b128 v[152:155], v165 offset:1024
	ds_read_b128 v[156:159], v165 offset:2048
	ds_read_b128 v[160:163], v165 offset:3072
	ds_read_b128 v[170:173], v166
	ds_read_b128 v[174:177], v166 offset:1024
	ds_read_b128 v[178:181], v166 offset:2048
	ds_read_b128 v[182:185], v166 offset:3072
	s_add_u32 s0, s28, 0xfffc0080
	s_addc_u32 s1, s29, -1
	s_cmp_eq_u32 s53, 12
	s_cselect_b32 s31, s21, s1
	s_cselect_b32 s30, s49, s0
	s_cselect_b32 s3, s19, s52
	s_cselect_b32 s2, s50, s51
	v_lshl_add_u64 v[218:219], s[28:29], 0, v[140:141]
	s_add_i32 m0, s27, 0xc000
	ds_read_b128 v[186:189], v167
	ds_read_b128 v[190:193], v167 offset:1024
	ds_read_b128 v[194:197], v167 offset:2048
	ds_read_b128 v[198:201], v167 offset:3072
	ds_read_b128 v[202:205], v167 offset:4096
	ds_read_b128 v[206:209], v167 offset:5120
	ds_read_b128 v[210:213], v167 offset:6144
	ds_read_b128 v[214:217], v167 offset:7168
	global_load_lds_dwordx4 v[218:219], off
	v_lshl_add_u64 v[218:219], s[28:29], 0, v[142:143]
	s_add_i32 m0, s27, 0xe000
	s_nop 0
	global_load_lds_dwordx4 v[218:219], off
	s_waitcnt vmcnt(8)
	s_waitcnt lgkmcnt(0)
	s_barrier
	s_setprio 1
	v_mfma_f32_16x16x32_bf16 v[126:129], v[148:151], v[186:189], v[126:129]
	v_mfma_f32_16x16x32_bf16 v[126:129], v[152:155], v[190:193], v[126:129]
	v_mfma_f32_16x16x32_bf16 v[118:121], v[156:159], v[186:189], v[118:121]
	v_mfma_f32_16x16x32_bf16 v[118:121], v[160:163], v[190:193], v[118:121]
	v_mfma_f32_16x16x32_bf16 v[110:113], v[148:151], v[194:197], v[110:113]
	v_mfma_f32_16x16x32_bf16 v[110:113], v[152:155], v[198:201], v[110:113]
	v_mfma_f32_16x16x32_bf16 v[102:105], v[156:159], v[194:197], v[102:105]
	v_mfma_f32_16x16x32_bf16 v[102:105], v[160:163], v[198:201], v[102:105]
	v_mfma_f32_16x16x32_bf16 v[94:97], v[148:151], v[202:205], v[94:97]
	v_mfma_f32_16x16x32_bf16 v[94:97], v[152:155], v[206:209], v[94:97]
	v_mfma_f32_16x16x32_bf16 v[86:89], v[156:159], v[202:205], v[86:89]
	v_mfma_f32_16x16x32_bf16 v[86:89], v[160:163], v[206:209], v[86:89]
	v_mfma_f32_16x16x32_bf16 v[78:81], v[148:151], v[210:213], v[78:81]
	v_mfma_f32_16x16x32_bf16 v[78:81], v[152:155], v[214:217], v[78:81]
	v_mfma_f32_16x16x32_bf16 v[70:73], v[156:159], v[210:213], v[70:73]
	v_mfma_f32_16x16x32_bf16 v[70:73], v[160:163], v[214:217], v[70:73]
	s_setprio 0
	s_setprio 1
	v_mfma_f32_16x16x32_bf16 v[122:125], v[170:173], v[186:189], v[122:125]
	v_mfma_f32_16x16x32_bf16 v[122:125], v[174:177], v[190:193], v[122:125]
	v_mfma_f32_16x16x32_bf16 v[114:117], v[178:181], v[186:189], v[114:117]
	v_mfma_f32_16x16x32_bf16 v[114:117], v[182:185], v[190:193], v[114:117]
	v_mfma_f32_16x16x32_bf16 v[106:109], v[170:173], v[194:197], v[106:109]
	v_mfma_f32_16x16x32_bf16 v[106:109], v[174:177], v[198:201], v[106:109]
	v_mfma_f32_16x16x32_bf16 v[98:101], v[178:181], v[194:197], v[98:101]
	v_mfma_f32_16x16x32_bf16 v[98:101], v[182:185], v[198:201], v[98:101]
	v_mfma_f32_16x16x32_bf16 v[90:93], v[170:173], v[202:205], v[90:93]
	v_mfma_f32_16x16x32_bf16 v[90:93], v[174:177], v[206:209], v[90:93]
	v_mfma_f32_16x16x32_bf16 v[82:85], v[178:181], v[202:205], v[82:85]
	v_mfma_f32_16x16x32_bf16 v[82:85], v[182:185], v[206:209], v[82:85]
	v_mfma_f32_16x16x32_bf16 v[74:77], v[170:173], v[210:213], v[74:77]
	v_mfma_f32_16x16x32_bf16 v[74:77], v[174:177], v[214:217], v[74:77]
	v_mfma_f32_16x16x32_bf16 v[66:69], v[178:181], v[210:213], v[66:69]
	v_mfma_f32_16x16x32_bf16 v[66:69], v[182:185], v[214:217], v[66:69]
	s_setprio 0
	s_barrier
	s_add_i32 s0, s44, s35
	v_lshl_add_u64 v[218:219], s[2:3], 0, v[134:135]
	s_mov_b32 m0, s0
	ds_read_b128 v[186:189], v167 offset:16384
	ds_read_b128 v[190:193], v167 offset:17408
	ds_read_b128 v[194:197], v167 offset:18432
	ds_read_b128 v[198:201], v167 offset:19456
	ds_read_b128 v[202:205], v167 offset:20480
	ds_read_b128 v[206:209], v167 offset:21504
	ds_read_b128 v[210:213], v167 offset:22528
	ds_read_b128 v[214:217], v167 offset:23552
	global_load_lds_dwordx4 v[218:219], off
	s_add_i32 m0, s0, 0x2000
	s_add_u32 s0, s2, 0x40000
	v_lshl_add_u64 v[220:221], s[2:3], 0, v[130:131]
	s_addc_u32 s1, s3, 0
	s_add_i32 s54, s45, s35
	global_load_lds_dwordx4 v[220:221], off
	v_lshl_add_u64 v[222:223], s[0:1], 0, v[134:135]
	s_mov_b32 m0, s54
	v_lshl_add_u64 v[224:225], s[30:31], 0, v[132:133]
	global_load_lds_dwordx4 v[222:223], off
	v_lshl_add_u64 v[222:223], s[0:1], 0, v[130:131]
	s_add_i32 m0, s54, 0x2000
	s_nop 0
	global_load_lds_dwordx4 v[222:223], off
	v_lshl_add_u64 v[222:223], s[30:31], 0, v[136:137]
	s_mov_b32 m0, s27
	s_nop 0
	global_load_lds_dwordx4 v[222:223], off
	s_mov_b32 m0, s38
	s_nop 0
	global_load_lds_dwordx4 v[224:225], off
	s_waitcnt vmcnt(8)
	s_waitcnt lgkmcnt(0)
	s_barrier
	s_setprio 1
	v_mfma_f32_16x16x32_bf16 v[62:65], v[148:151], v[186:189], v[62:65]
	v_mfma_f32_16x16x32_bf16 v[62:65], v[152:155], v[190:193], v[62:65]
	v_mfma_f32_16x16x32_bf16 v[54:57], v[156:159], v[186:189], v[54:57]
	v_mfma_f32_16x16x32_bf16 v[54:57], v[160:163], v[190:193], v[54:57]
	v_mfma_f32_16x16x32_bf16 v[46:49], v[148:151], v[194:197], v[46:49]
	v_mfma_f32_16x16x32_bf16 v[46:49], v[152:155], v[198:201], v[46:49]
	v_mfma_f32_16x16x32_bf16 v[38:41], v[156:159], v[194:197], v[38:41]
	v_mfma_f32_16x16x32_bf16 v[38:41], v[160:163], v[198:201], v[38:41]
	v_mfma_f32_16x16x32_bf16 v[30:33], v[148:151], v[202:205], v[30:33]
	v_mfma_f32_16x16x32_bf16 v[30:33], v[152:155], v[206:209], v[30:33]
	v_mfma_f32_16x16x32_bf16 v[22:25], v[156:159], v[202:205], v[22:25]
	v_mfma_f32_16x16x32_bf16 v[22:25], v[160:163], v[206:209], v[22:25]
	v_mfma_f32_16x16x32_bf16 v[14:17], v[148:151], v[210:213], v[14:17]
	v_mfma_f32_16x16x32_bf16 v[14:17], v[152:155], v[214:217], v[14:17]
	v_mfma_f32_16x16x32_bf16 v[6:9], v[156:159], v[210:213], v[6:9]
	v_mfma_f32_16x16x32_bf16 v[6:9], v[160:163], v[214:217], v[6:9]
	s_setprio 0
	s_setprio 1
	v_mfma_f32_16x16x32_bf16 v[58:61], v[170:173], v[186:189], v[58:61]
	v_mfma_f32_16x16x32_bf16 v[58:61], v[174:177], v[190:193], v[58:61]
	v_mfma_f32_16x16x32_bf16 v[50:53], v[178:181], v[186:189], v[50:53]
	v_mfma_f32_16x16x32_bf16 v[50:53], v[182:185], v[190:193], v[50:53]
	v_mfma_f32_16x16x32_bf16 v[42:45], v[170:173], v[194:197], v[42:45]
	v_mfma_f32_16x16x32_bf16 v[42:45], v[174:177], v[198:201], v[42:45]
	v_mfma_f32_16x16x32_bf16 v[34:37], v[178:181], v[194:197], v[34:37]
	v_mfma_f32_16x16x32_bf16 v[34:37], v[182:185], v[198:201], v[34:37]
	v_mfma_f32_16x16x32_bf16 v[26:29], v[170:173], v[202:205], v[26:29]
	v_mfma_f32_16x16x32_bf16 v[26:29], v[174:177], v[206:209], v[26:29]
	v_mfma_f32_16x16x32_bf16 v[18:21], v[178:181], v[202:205], v[18:21]
	v_mfma_f32_16x16x32_bf16 v[18:21], v[182:185], v[206:209], v[18:21]
	v_mfma_f32_16x16x32_bf16 v[10:13], v[170:173], v[210:213], v[10:13]
	v_mfma_f32_16x16x32_bf16 v[10:13], v[174:177], v[214:217], v[10:13]
	v_mfma_f32_16x16x32_bf16 v[2:5], v[178:181], v[210:213], v[2:5]
	v_mfma_f32_16x16x32_bf16 v[2:5], v[182:185], v[214:217], v[2:5]
	s_setprio 0
	s_barrier
	s_add_i32 s54, 0, 0x18000
	s_add_i32 s55, 0, 0x1c000
	v_add_u32_e32 v160, s54, v164
	v_add_u32_e32 v169, s55, v164
	ds_read_b128 v[148:151], v160
	ds_read_b128 v[152:155], v160 offset:1024
	ds_read_b128 v[156:159], v160 offset:2048
	ds_read_b128 v[160:163], v160 offset:3072
	ds_read_b128 v[170:173], v169
	ds_read_b128 v[174:177], v169 offset:1024
	ds_read_b128 v[178:181], v169 offset:2048
	ds_read_b128 v[182:185], v169 offset:3072
	s_add_u32 s0, s30, 0x40000
	s_addc_u32 s1, s31, 0
	s_mov_b32 m0, s39
	v_lshl_add_u64 v[226:227], s[0:1], 0, v[136:137]
	ds_read_b128 v[186:189], v167 offset:32768
	ds_read_b128 v[190:193], v167 offset:33792
	ds_read_b128 v[194:197], v167 offset:34816
	ds_read_b128 v[198:201], v167 offset:35840
	ds_read_b128 v[202:205], v167 offset:36864
	ds_read_b128 v[206:209], v167 offset:37888
	ds_read_b128 v[210:213], v167 offset:38912
	ds_read_b128 v[214:217], v167 offset:39936
	global_load_lds_dwordx4 v[226:227], off
	v_lshl_add_u64 v[226:227], s[0:1], 0, v[132:133]
	s_mov_b32 m0, s40
	s_nop 0
	global_load_lds_dwordx4 v[226:227], off
	s_waitcnt vmcnt(8)
	s_waitcnt lgkmcnt(0)
	s_barrier
	s_setprio 1
	v_mfma_f32_16x16x32_bf16 v[126:129], v[148:151], v[186:189], v[126:129]
	v_mfma_f32_16x16x32_bf16 v[126:129], v[152:155], v[190:193], v[126:129]
	v_mfma_f32_16x16x32_bf16 v[118:121], v[156:159], v[186:189], v[118:121]
	v_mfma_f32_16x16x32_bf16 v[118:121], v[160:163], v[190:193], v[118:121]
	v_mfma_f32_16x16x32_bf16 v[110:113], v[148:151], v[194:197], v[110:113]
	v_mfma_f32_16x16x32_bf16 v[110:113], v[152:155], v[198:201], v[110:113]
	v_mfma_f32_16x16x32_bf16 v[102:105], v[156:159], v[194:197], v[102:105]
	v_mfma_f32_16x16x32_bf16 v[102:105], v[160:163], v[198:201], v[102:105]
	v_mfma_f32_16x16x32_bf16 v[94:97], v[148:151], v[202:205], v[94:97]
	v_mfma_f32_16x16x32_bf16 v[94:97], v[152:155], v[206:209], v[94:97]
	v_mfma_f32_16x16x32_bf16 v[86:89], v[156:159], v[202:205], v[86:89]
	v_mfma_f32_16x16x32_bf16 v[86:89], v[160:163], v[206:209], v[86:89]
	v_mfma_f32_16x16x32_bf16 v[78:81], v[148:151], v[210:213], v[78:81]
	v_mfma_f32_16x16x32_bf16 v[78:81], v[152:155], v[214:217], v[78:81]
	v_mfma_f32_16x16x32_bf16 v[70:73], v[156:159], v[210:213], v[70:73]
	v_mfma_f32_16x16x32_bf16 v[70:73], v[160:163], v[214:217], v[70:73]
	s_setprio 0
	s_setprio 1
	v_mfma_f32_16x16x32_bf16 v[122:125], v[170:173], v[186:189], v[122:125]
	v_mfma_f32_16x16x32_bf16 v[122:125], v[174:177], v[190:193], v[122:125]
	v_mfma_f32_16x16x32_bf16 v[114:117], v[178:181], v[186:189], v[114:117]
	v_mfma_f32_16x16x32_bf16 v[114:117], v[182:185], v[190:193], v[114:117]
	v_mfma_f32_16x16x32_bf16 v[106:109], v[170:173], v[194:197], v[106:109]
	v_mfma_f32_16x16x32_bf16 v[106:109], v[174:177], v[198:201], v[106:109]
	v_mfma_f32_16x16x32_bf16 v[98:101], v[178:181], v[194:197], v[98:101]
	v_mfma_f32_16x16x32_bf16 v[98:101], v[182:185], v[198:201], v[98:101]
	v_mfma_f32_16x16x32_bf16 v[90:93], v[170:173], v[202:205], v[90:93]
	v_mfma_f32_16x16x32_bf16 v[90:93], v[174:177], v[206:209], v[90:93]
	v_mfma_f32_16x16x32_bf16 v[82:85], v[178:181], v[202:205], v[82:85]
	v_mfma_f32_16x16x32_bf16 v[82:85], v[182:185], v[206:209], v[82:85]
	v_mfma_f32_16x16x32_bf16 v[74:77], v[170:173], v[210:213], v[74:77]
	v_mfma_f32_16x16x32_bf16 v[74:77], v[174:177], v[214:217], v[74:77]
	v_mfma_f32_16x16x32_bf16 v[66:69], v[178:181], v[210:213], v[66:69]
	v_mfma_f32_16x16x32_bf16 v[66:69], v[182:185], v[214:217], v[66:69]
	s_setprio 0
	s_barrier
	s_add_i32 s0, s54, s35
	v_lshl_add_u64 v[218:219], v[218:219], 0, s[14:15]
	s_mov_b32 m0, s0
	ds_read_b128 v[186:189], v167 offset:49152
	ds_read_b128 v[190:193], v167 offset:50176
	ds_read_b128 v[194:197], v167 offset:51200
	ds_read_b128 v[198:201], v167 offset:52224
	ds_read_b128 v[202:205], v167 offset:53248
	ds_read_b128 v[206:209], v167 offset:54272
	ds_read_b128 v[210:213], v167 offset:55296
	ds_read_b128 v[214:217], v167 offset:56320
	global_load_lds_dwordx4 v[218:219], off
	s_add_i32 m0, s0, 0x2000
	s_add_u32 s0, s2, 0x40080
	v_lshl_add_u64 v[218:219], v[220:221], 0, s[14:15]
	s_addc_u32 s1, s3, 0
	s_add_i32 s2, s55, s35
	global_load_lds_dwordx4 v[218:219], off
	v_lshl_add_u64 v[218:219], s[0:1], 0, v[134:135]
	s_mov_b32 m0, s2
	s_nop 0
	global_load_lds_dwordx4 v[218:219], off
	v_lshl_add_u64 v[218:219], s[0:1], 0, v[130:131]
	s_add_i32 m0, s2, 0x2000
	s_nop 0
	global_load_lds_dwordx4 v[218:219], off
	v_lshl_add_u64 v[218:219], v[222:223], 0, s[14:15]
	s_mov_b32 m0, s41
	s_nop 0
	global_load_lds_dwordx4 v[218:219], off
	v_lshl_add_u64 v[218:219], v[224:225], 0, s[14:15]
	s_mov_b32 m0, s42
	s_nop 0
	global_load_lds_dwordx4 v[218:219], off
	s_waitcnt vmcnt(8)
	s_waitcnt lgkmcnt(0)
	s_barrier
	s_setprio 1
	v_mfma_f32_16x16x32_bf16 v[62:65], v[148:151], v[186:189], v[62:65]
	v_mfma_f32_16x16x32_bf16 v[62:65], v[152:155], v[190:193], v[62:65]
	v_mfma_f32_16x16x32_bf16 v[54:57], v[156:159], v[186:189], v[54:57]
	v_mfma_f32_16x16x32_bf16 v[54:57], v[160:163], v[190:193], v[54:57]
	v_mfma_f32_16x16x32_bf16 v[46:49], v[148:151], v[194:197], v[46:49]
	v_mfma_f32_16x16x32_bf16 v[46:49], v[152:155], v[198:201], v[46:49]
	v_mfma_f32_16x16x32_bf16 v[38:41], v[156:159], v[194:197], v[38:41]
	v_mfma_f32_16x16x32_bf16 v[38:41], v[160:163], v[198:201], v[38:41]
	v_mfma_f32_16x16x32_bf16 v[30:33], v[148:151], v[202:205], v[30:33]
	v_mfma_f32_16x16x32_bf16 v[30:33], v[152:155], v[206:209], v[30:33]
	v_mfma_f32_16x16x32_bf16 v[22:25], v[156:159], v[202:205], v[22:25]
	v_mfma_f32_16x16x32_bf16 v[22:25], v[160:163], v[206:209], v[22:25]
	v_mfma_f32_16x16x32_bf16 v[14:17], v[148:151], v[210:213], v[14:17]
	v_mfma_f32_16x16x32_bf16 v[14:17], v[152:155], v[214:217], v[14:17]
	v_mfma_f32_16x16x32_bf16 v[6:9], v[156:159], v[210:213], v[6:9]
	v_mfma_f32_16x16x32_bf16 v[6:9], v[160:163], v[214:217], v[6:9]
	s_setprio 0
	s_setprio 1
	v_mfma_f32_16x16x32_bf16 v[58:61], v[170:173], v[186:189], v[58:61]
	s_add_i32 s53, s53, 2
	s_add_u32 s28, s28, 0x100
	s_addc_u32 s29, s29, 0
	s_add_u32 s51, s51, 0x100
	s_addc_u32 s52, s52, 0
	s_cmp_gt_u32 s53, 13
	v_mfma_f32_16x16x32_bf16 v[58:61], v[174:177], v[190:193], v[58:61]
	v_mfma_f32_16x16x32_bf16 v[50:53], v[178:181], v[186:189], v[50:53]
	v_mfma_f32_16x16x32_bf16 v[50:53], v[182:185], v[190:193], v[50:53]
	v_mfma_f32_16x16x32_bf16 v[42:45], v[170:173], v[194:197], v[42:45]
	v_mfma_f32_16x16x32_bf16 v[42:45], v[174:177], v[198:201], v[42:45]
	v_mfma_f32_16x16x32_bf16 v[34:37], v[178:181], v[194:197], v[34:37]
	v_mfma_f32_16x16x32_bf16 v[34:37], v[182:185], v[198:201], v[34:37]
	v_mfma_f32_16x16x32_bf16 v[26:29], v[170:173], v[202:205], v[26:29]
	v_mfma_f32_16x16x32_bf16 v[26:29], v[174:177], v[206:209], v[26:29]
	v_mfma_f32_16x16x32_bf16 v[18:21], v[178:181], v[202:205], v[18:21]
	v_mfma_f32_16x16x32_bf16 v[18:21], v[182:185], v[206:209], v[18:21]
	v_mfma_f32_16x16x32_bf16 v[10:13], v[170:173], v[210:213], v[10:13]
	v_mfma_f32_16x16x32_bf16 v[10:13], v[174:177], v[214:217], v[10:13]
	v_mfma_f32_16x16x32_bf16 v[2:5], v[178:181], v[210:213], v[2:5]
	v_mfma_f32_16x16x32_bf16 v[2:5], v[182:185], v[214:217], v[2:5]
	s_setprio 0
	s_barrier
	s_cbranch_scc0 .LBB0_2207
	s_and_b64 vcc, exec, s[16:17]
	s_cbranch_vccz .LBB0_2210
	s_barrier

.LBB0_2290:
	ds_read_b128 v[144:147], v153
	ds_read_b128 v[156:159], v153 offset:1024
	ds_read_b128 v[160:163], v153 offset:2048
	ds_read_b128 v[164:167], v153 offset:3072
	ds_read_b128 v[168:171], v154
	ds_read_b128 v[172:175], v154 offset:1024
	ds_read_b128 v[176:179], v154 offset:2048
	ds_read_b128 v[180:183], v154 offset:3072
	s_add_u32 s2, s16, 0xfff50080
	s_addc_u32 s3, s17, -1
	s_cmp_eq_u32 s43, 40
	s_cselect_b32 s19, s5, s3
	s_cselect_b32 s18, s4, s2
	s_cselect_b32 s3, s15, s42
	s_cselect_b32 s2, s14, s41
	v_lshl_add_u64 v[148:149], s[16:17], 0, v[136:137]
	s_add_i32 m0, s26, 0xc000
	ds_read_b128 v[184:187], v155
	ds_read_b128 v[188:191], v155 offset:1024
	ds_read_b128 v[192:195], v155 offset:2048
	ds_read_b128 v[196:199], v155 offset:3072
	ds_read_b128 v[200:203], v155 offset:4096
	ds_read_b128 v[204:207], v155 offset:5120
	ds_read_b128 v[208:211], v155 offset:6144
	ds_read_b128 v[212:215], v155 offset:7168
	global_load_lds_dwordx4 v[148:149], off
	v_lshl_add_u64 v[148:149], s[16:17], 0, v[138:139]
	s_add_i32 m0, s26, 0xe000
	s_nop 0
	global_load_lds_dwordx4 v[148:149], off
	s_waitcnt vmcnt(8)
	s_waitcnt lgkmcnt(0)
	s_barrier
	s_setprio 1
	v_mfma_f32_16x16x32_bf16 v[124:127], v[144:147], v[184:187], v[124:127]
	v_mfma_f32_16x16x32_bf16 v[124:127], v[156:159], v[188:191], v[124:127]
	v_mfma_f32_16x16x32_bf16 v[120:123], v[160:163], v[184:187], v[120:123]
	v_mfma_f32_16x16x32_bf16 v[120:123], v[164:167], v[188:191], v[120:123]
	v_mfma_f32_16x16x32_bf16 v[112:115], v[144:147], v[192:195], v[112:115]
	v_mfma_f32_16x16x32_bf16 v[112:115], v[156:159], v[196:199], v[112:115]
	v_mfma_f32_16x16x32_bf16 v[104:107], v[160:163], v[192:195], v[104:107]
	v_mfma_f32_16x16x32_bf16 v[104:107], v[164:167], v[196:199], v[104:107]
	v_mfma_f32_16x16x32_bf16 v[96:99], v[144:147], v[200:203], v[96:99]
	v_mfma_f32_16x16x32_bf16 v[96:99], v[156:159], v[204:207], v[96:99]
	v_mfma_f32_16x16x32_bf16 v[88:91], v[160:163], v[200:203], v[88:91]
	v_mfma_f32_16x16x32_bf16 v[88:91], v[164:167], v[204:207], v[88:91]
	v_mfma_f32_16x16x32_bf16 v[80:83], v[144:147], v[208:211], v[80:83]
	v_mfma_f32_16x16x32_bf16 v[80:83], v[156:159], v[212:215], v[80:83]
	v_mfma_f32_16x16x32_bf16 v[72:75], v[160:163], v[208:211], v[72:75]
	v_mfma_f32_16x16x32_bf16 v[72:75], v[164:167], v[212:215], v[72:75]
	s_setprio 0
	s_setprio 1
	v_mfma_f32_16x16x32_bf16 v[116:119], v[168:171], v[184:187], v[116:119]
	v_mfma_f32_16x16x32_bf16 v[116:119], v[172:175], v[188:191], v[116:119]
	v_mfma_f32_16x16x32_bf16 v[108:111], v[176:179], v[184:187], v[108:111]
	v_mfma_f32_16x16x32_bf16 v[108:111], v[180:183], v[188:191], v[108:111]
	v_mfma_f32_16x16x32_bf16 v[100:103], v[168:171], v[192:195], v[100:103]
	v_mfma_f32_16x16x32_bf16 v[100:103], v[172:175], v[196:199], v[100:103]
	v_mfma_f32_16x16x32_bf16 v[92:95], v[176:179], v[192:195], v[92:95]
	v_mfma_f32_16x16x32_bf16 v[92:95], v[180:183], v[196:199], v[92:95]
	v_mfma_f32_16x16x32_bf16 v[84:87], v[168:171], v[200:203], v[84:87]
	v_mfma_f32_16x16x32_bf16 v[84:87], v[172:175], v[204:207], v[84:87]
	v_mfma_f32_16x16x32_bf16 v[76:79], v[176:179], v[200:203], v[76:79]
	v_mfma_f32_16x16x32_bf16 v[76:79], v[180:183], v[204:207], v[76:79]
	v_mfma_f32_16x16x32_bf16 v[68:71], v[168:171], v[208:211], v[68:71]
	v_mfma_f32_16x16x32_bf16 v[68:71], v[172:175], v[212:215], v[68:71]
	v_mfma_f32_16x16x32_bf16 v[64:67], v[176:179], v[208:211], v[64:67]
	v_mfma_f32_16x16x32_bf16 v[64:67], v[180:183], v[212:215], v[64:67]
	s_setprio 0
	s_barrier
	s_add_i32 s44, s35, s25
	v_lshl_add_u64 v[148:149], s[2:3], 0, v[130:131]
	s_mov_b32 m0, s44
	ds_read_b128 v[184:187], v155 offset:16384
	ds_read_b128 v[188:191], v155 offset:17408
	ds_read_b128 v[192:195], v155 offset:18432
	ds_read_b128 v[196:199], v155 offset:19456
	ds_read_b128 v[200:203], v155 offset:20480
	ds_read_b128 v[204:207], v155 offset:21504
	ds_read_b128 v[208:211], v155 offset:22528
	ds_read_b128 v[212:215], v155 offset:23552
	global_load_lds_dwordx4 v[148:149], off
	s_add_i32 m0, s44, 0x2000
	s_add_u32 s44, s2, 0xb0000
	v_lshl_add_u64 v[216:217], s[2:3], 0, v[134:135]
	s_addc_u32 s45, s3, 0
	s_add_i32 s46, s36, s25
	global_load_lds_dwordx4 v[216:217], off
	v_lshl_add_u64 v[218:219], s[44:45], 0, v[130:131]
	s_mov_b32 m0, s46
	v_lshl_add_u64 v[220:221], s[18:19], 0, v[132:133]
	global_load_lds_dwordx4 v[218:219], off
	v_lshl_add_u64 v[218:219], s[44:45], 0, v[134:135]
	s_add_i32 m0, s46, 0x2000
	s_nop 0
	global_load_lds_dwordx4 v[218:219], off
	v_lshl_add_u64 v[218:219], s[18:19], 0, v[128:129]
	s_mov_b32 m0, s26
	s_nop 0
	global_load_lds_dwordx4 v[218:219], off
	s_mov_b32 m0, s27
	s_nop 0
	global_load_lds_dwordx4 v[220:221], off
	s_waitcnt vmcnt(8)
	s_waitcnt lgkmcnt(0)
	s_barrier
	s_setprio 1
	v_mfma_f32_16x16x32_bf16 v[60:63], v[144:147], v[184:187], v[60:63]
	v_mfma_f32_16x16x32_bf16 v[60:63], v[156:159], v[188:191], v[60:63]
	v_mfma_f32_16x16x32_bf16 v[56:59], v[160:163], v[184:187], v[56:59]
	v_mfma_f32_16x16x32_bf16 v[56:59], v[164:167], v[188:191], v[56:59]
	v_mfma_f32_16x16x32_bf16 v[48:51], v[144:147], v[192:195], v[48:51]
	v_mfma_f32_16x16x32_bf16 v[48:51], v[156:159], v[196:199], v[48:51]
	v_mfma_f32_16x16x32_bf16 v[40:43], v[160:163], v[192:195], v[40:43]
	v_mfma_f32_16x16x32_bf16 v[40:43], v[164:167], v[196:199], v[40:43]
	v_mfma_f32_16x16x32_bf16 v[32:35], v[144:147], v[200:203], v[32:35]
	v_mfma_f32_16x16x32_bf16 v[32:35], v[156:159], v[204:207], v[32:35]
	v_mfma_f32_16x16x32_bf16 v[24:27], v[160:163], v[200:203], v[24:27]
	v_mfma_f32_16x16x32_bf16 v[24:27], v[164:167], v[204:207], v[24:27]
	v_mfma_f32_16x16x32_bf16 v[16:19], v[144:147], v[208:211], v[16:19]
	v_mfma_f32_16x16x32_bf16 v[16:19], v[156:159], v[212:215], v[16:19]
	v_mfma_f32_16x16x32_bf16 v[8:11], v[160:163], v[208:211], v[8:11]
	v_mfma_f32_16x16x32_bf16 v[8:11], v[164:167], v[212:215], v[8:11]
	s_setprio 0
	s_setprio 1
	v_mfma_f32_16x16x32_bf16 v[52:55], v[168:171], v[184:187], v[52:55]
	v_mfma_f32_16x16x32_bf16 v[52:55], v[172:175], v[188:191], v[52:55]
	v_mfma_f32_16x16x32_bf16 v[44:47], v[176:179], v[184:187], v[44:47]
	v_mfma_f32_16x16x32_bf16 v[44:47], v[180:183], v[188:191], v[44:47]
	v_mfma_f32_16x16x32_bf16 v[36:39], v[168:171], v[192:195], v[36:39]
	v_mfma_f32_16x16x32_bf16 v[36:39], v[172:175], v[196:199], v[36:39]
	v_mfma_f32_16x16x32_bf16 v[28:31], v[176:179], v[192:195], v[28:31]
	v_mfma_f32_16x16x32_bf16 v[28:31], v[180:183], v[196:199], v[28:31]
	v_mfma_f32_16x16x32_bf16 v[20:23], v[168:171], v[200:203], v[20:23]
	v_mfma_f32_16x16x32_bf16 v[20:23], v[172:175], v[204:207], v[20:23]
	v_mfma_f32_16x16x32_bf16 v[12:15], v[176:179], v[200:203], v[12:15]
	v_mfma_f32_16x16x32_bf16 v[12:15], v[180:183], v[204:207], v[12:15]
	v_mfma_f32_16x16x32_bf16 v[4:7], v[168:171], v[208:211], v[4:7]
	v_mfma_f32_16x16x32_bf16 v[4:7], v[172:175], v[212:215], v[4:7]
	v_mfma_f32_16x16x32_bf16 v[0:3], v[176:179], v[208:211], v[0:3]
	v_mfma_f32_16x16x32_bf16 v[0:3], v[180:183], v[212:215], v[0:3]
	s_setprio 0
	s_barrier
	s_add_i32 s44, 0, 0x18000
	s_add_i32 s45, 0, 0x1c000
	v_add_u32_e32 v164, s44, v151
	v_add_u32_e32 v180, s45, v151
	ds_read_b128 v[144:147], v164
	ds_read_b128 v[156:159], v164 offset:1024
	ds_read_b128 v[160:163], v164 offset:2048
	ds_read_b128 v[164:167], v164 offset:3072
	ds_read_b128 v[168:171], v180
	ds_read_b128 v[172:175], v180 offset:1024
	ds_read_b128 v[176:179], v180 offset:2048
	ds_read_b128 v[180:183], v180 offset:3072
	s_add_u32 s18, s18, 0xb0000
	s_addc_u32 s19, s19, 0
	s_mov_b32 m0, s28
	v_lshl_add_u64 v[222:223], s[18:19], 0, v[128:129]
	ds_read_b128 v[184:187], v155 offset:32768
	ds_read_b128 v[188:191], v155 offset:33792
	ds_read_b128 v[192:195], v155 offset:34816
	ds_read_b128 v[196:199], v155 offset:35840
	ds_read_b128 v[200:203], v155 offset:36864
	ds_read_b128 v[204:207], v155 offset:37888
	ds_read_b128 v[208:211], v155 offset:38912
	ds_read_b128 v[212:215], v155 offset:39936
	global_load_lds_dwordx4 v[222:223], off
	v_lshl_add_u64 v[222:223], s[18:19], 0, v[132:133]
	s_mov_b32 m0, s29
	s_nop 0
	global_load_lds_dwordx4 v[222:223], off
	s_waitcnt vmcnt(8)
	s_waitcnt lgkmcnt(0)
	s_barrier
	s_setprio 1
	v_mfma_f32_16x16x32_bf16 v[124:127], v[144:147], v[184:187], v[124:127]
	v_mfma_f32_16x16x32_bf16 v[124:127], v[156:159], v[188:191], v[124:127]
	v_mfma_f32_16x16x32_bf16 v[120:123], v[160:163], v[184:187], v[120:123]
	v_mfma_f32_16x16x32_bf16 v[120:123], v[164:167], v[188:191], v[120:123]
	v_mfma_f32_16x16x32_bf16 v[112:115], v[144:147], v[192:195], v[112:115]
	v_mfma_f32_16x16x32_bf16 v[112:115], v[156:159], v[196:199], v[112:115]
	v_mfma_f32_16x16x32_bf16 v[104:107], v[160:163], v[192:195], v[104:107]
	v_mfma_f32_16x16x32_bf16 v[104:107], v[164:167], v[196:199], v[104:107]
	v_mfma_f32_16x16x32_bf16 v[96:99], v[144:147], v[200:203], v[96:99]
	v_mfma_f32_16x16x32_bf16 v[96:99], v[156:159], v[204:207], v[96:99]
	v_mfma_f32_16x16x32_bf16 v[88:91], v[160:163], v[200:203], v[88:91]
	v_mfma_f32_16x16x32_bf16 v[88:91], v[164:167], v[204:207], v[88:91]
	v_mfma_f32_16x16x32_bf16 v[80:83], v[144:147], v[208:211], v[80:83]
	v_mfma_f32_16x16x32_bf16 v[80:83], v[156:159], v[212:215], v[80:83]
	v_mfma_f32_16x16x32_bf16 v[72:75], v[160:163], v[208:211], v[72:75]
	v_mfma_f32_16x16x32_bf16 v[72:75], v[164:167], v[212:215], v[72:75]
	s_setprio 0
	s_setprio 1
	v_mfma_f32_16x16x32_bf16 v[116:119], v[168:171], v[184:187], v[116:119]
	v_mfma_f32_16x16x32_bf16 v[116:119], v[172:175], v[188:191], v[116:119]
	v_mfma_f32_16x16x32_bf16 v[108:111], v[176:179], v[184:187], v[108:111]
	v_mfma_f32_16x16x32_bf16 v[108:111], v[180:183], v[188:191], v[108:111]
	v_mfma_f32_16x16x32_bf16 v[100:103], v[168:171], v[192:195], v[100:103]
	v_mfma_f32_16x16x32_bf16 v[100:103], v[172:175], v[196:199], v[100:103]
	v_mfma_f32_16x16x32_bf16 v[92:95], v[176:179], v[192:195], v[92:95]
	v_mfma_f32_16x16x32_bf16 v[92:95], v[180:183], v[196:199], v[92:95]
	v_mfma_f32_16x16x32_bf16 v[84:87], v[168:171], v[200:203], v[84:87]
	v_mfma_f32_16x16x32_bf16 v[84:87], v[172:175], v[204:207], v[84:87]
	v_mfma_f32_16x16x32_bf16 v[76:79], v[176:179], v[200:203], v[76:79]
	v_mfma_f32_16x16x32_bf16 v[76:79], v[180:183], v[204:207], v[76:79]
	v_mfma_f32_16x16x32_bf16 v[68:71], v[168:171], v[208:211], v[68:71]
	v_mfma_f32_16x16x32_bf16 v[68:71], v[172:175], v[212:215], v[68:71]
	v_mfma_f32_16x16x32_bf16 v[64:67], v[176:179], v[208:211], v[64:67]
	v_mfma_f32_16x16x32_bf16 v[64:67], v[180:183], v[212:215], v[64:67]
	s_setprio 0
	s_barrier
	s_add_i32 s18, s44, s25
	v_lshl_add_u64 v[148:149], v[148:149], 0, s[10:11]
	s_mov_b32 m0, s18
	ds_read_b128 v[184:187], v155 offset:49152
	ds_read_b128 v[188:191], v155 offset:50176
	ds_read_b128 v[192:195], v155 offset:51200
	ds_read_b128 v[196:199], v155 offset:52224
	ds_read_b128 v[200:203], v155 offset:53248
	ds_read_b128 v[204:207], v155 offset:54272
	ds_read_b128 v[208:211], v155 offset:55296
	ds_read_b128 v[212:215], v155 offset:56320
	global_load_lds_dwordx4 v[148:149], off
	s_add_i32 m0, s18, 0x2000
	s_add_u32 s2, s2, 0xb0080
	v_lshl_add_u64 v[148:149], v[216:217], 0, s[10:11]
	s_addc_u32 s3, s3, 0
	s_add_i32 s18, s45, s25
	global_load_lds_dwordx4 v[148:149], off
	v_lshl_add_u64 v[148:149], s[2:3], 0, v[130:131]
	s_mov_b32 m0, s18
	s_nop 0
	global_load_lds_dwordx4 v[148:149], off
	v_lshl_add_u64 v[148:149], s[2:3], 0, v[134:135]
	s_add_i32 m0, s18, 0x2000
	s_nop 0
	global_load_lds_dwordx4 v[148:149], off
	v_lshl_add_u64 v[148:149], v[218:219], 0, s[10:11]
	s_mov_b32 m0, s31
	s_nop 0
	global_load_lds_dwordx4 v[148:149], off
	v_lshl_add_u64 v[148:149], v[220:221], 0, s[10:11]
	s_mov_b32 m0, s33
	s_nop 0
	global_load_lds_dwordx4 v[148:149], off
	s_waitcnt vmcnt(8)
	s_waitcnt lgkmcnt(0)
	s_barrier
	s_setprio 1
	v_mfma_f32_16x16x32_bf16 v[60:63], v[144:147], v[184:187], v[60:63]
	v_mfma_f32_16x16x32_bf16 v[60:63], v[156:159], v[188:191], v[60:63]
	v_mfma_f32_16x16x32_bf16 v[56:59], v[160:163], v[184:187], v[56:59]
	v_mfma_f32_16x16x32_bf16 v[56:59], v[164:167], v[188:191], v[56:59]
	v_mfma_f32_16x16x32_bf16 v[48:51], v[144:147], v[192:195], v[48:51]
	v_mfma_f32_16x16x32_bf16 v[48:51], v[156:159], v[196:199], v[48:51]
	v_mfma_f32_16x16x32_bf16 v[40:43], v[160:163], v[192:195], v[40:43]
	v_mfma_f32_16x16x32_bf16 v[40:43], v[164:167], v[196:199], v[40:43]
	v_mfma_f32_16x16x32_bf16 v[32:35], v[144:147], v[200:203], v[32:35]
	v_mfma_f32_16x16x32_bf16 v[32:35], v[156:159], v[204:207], v[32:35]
	v_mfma_f32_16x16x32_bf16 v[24:27], v[160:163], v[200:203], v[24:27]
	v_mfma_f32_16x16x32_bf16 v[24:27], v[164:167], v[204:207], v[24:27]
	v_mfma_f32_16x16x32_bf16 v[16:19], v[144:147], v[208:211], v[16:19]
	v_mfma_f32_16x16x32_bf16 v[16:19], v[156:159], v[212:215], v[16:19]
	v_mfma_f32_16x16x32_bf16 v[8:11], v[160:163], v[208:211], v[8:11]
	v_mfma_f32_16x16x32_bf16 v[8:11], v[164:167], v[212:215], v[8:11]
	s_setprio 0
	s_setprio 1
	v_mfma_f32_16x16x32_bf16 v[52:55], v[168:171], v[184:187], v[52:55]
	s_add_i32 s43, s43, 2
	s_add_u32 s16, s16, 0x100
	s_addc_u32 s17, s17, 0
	s_add_u32 s41, s41, 0x100
	s_addc_u32 s42, s42, 0
	s_cmp_gt_u32 s43, 41
	v_mfma_f32_16x16x32_bf16 v[52:55], v[172:175], v[188:191], v[52:55]
	v_mfma_f32_16x16x32_bf16 v[44:47], v[176:179], v[184:187], v[44:47]
	v_mfma_f32_16x16x32_bf16 v[44:47], v[180:183], v[188:191], v[44:47]
	v_mfma_f32_16x16x32_bf16 v[36:39], v[168:171], v[192:195], v[36:39]
	v_mfma_f32_16x16x32_bf16 v[36:39], v[172:175], v[196:199], v[36:39]
	v_mfma_f32_16x16x32_bf16 v[28:31], v[176:179], v[192:195], v[28:31]
	v_mfma_f32_16x16x32_bf16 v[28:31], v[180:183], v[196:199], v[28:31]
	v_mfma_f32_16x16x32_bf16 v[20:23], v[168:171], v[200:203], v[20:23]
	v_mfma_f32_16x16x32_bf16 v[20:23], v[172:175], v[204:207], v[20:23]
	v_mfma_f32_16x16x32_bf16 v[12:15], v[176:179], v[200:203], v[12:15]
	v_mfma_f32_16x16x32_bf16 v[12:15], v[180:183], v[204:207], v[12:15]
	v_mfma_f32_16x16x32_bf16 v[4:7], v[168:171], v[208:211], v[4:7]
	v_mfma_f32_16x16x32_bf16 v[4:7], v[172:175], v[212:215], v[4:7]
	v_mfma_f32_16x16x32_bf16 v[0:3], v[176:179], v[208:211], v[0:3]
	v_mfma_f32_16x16x32_bf16 v[0:3], v[180:183], v[212:215], v[0:3]
	s_setprio 0
	s_barrier
	s_cbranch_scc0 .LBB0_2290
	s_and_b64 vcc, exec, s[12:13]
	s_cbranch_vccz .LBB0_2293
	s_barrier
